# scaled-state RWKV scan (no decay operand, rescale every 4 steps) + attention 2-tiles-in-flight/fragment prefetch
# speedup vs baseline: 1.0043x; 1.0043x over previous
; template <int CPL>
; DI void scan_block2(CP p, int layer, int s, int d, int hd, int rowhalf, char* smem) {
;     ...
;       }
;       __syncthreads();
;     }
;     __builtin_amdgcn_s_setprio(0);
;   }
;   __syncthreads();
.LBB0_85:
	s_or_b64 exec, exec, s[8:9]
	s_setprio 0
	s_barrier

; template <int CPL>
; DI void scan_block2(CP p, int layer, int s, int d, int hd, int rowhalf, char* smem) {
;     ...
;     constexpr int LPRW = 64 / CPL;
;     constexpr int NV = CPL / 2;
;     const int cg = lane % LPRW;
;     const int row = (CPL == 8 ? rowhalf * 32 + wv * 8 : wv * 16) + lane / LPRW;
;     f2 S[NV];
; #pragma unroll
;     for (int i = 0; i < NV; ++i) S[i] = mk2(0.f, 0.f);
;     __builtin_amdgcn_s_setprio(3);
;     __syncthreads();
;     for (int c = 0; c < nch; ++c) {
;       const int nst = min(32, L - c * 32);
;       const float* ob = OP + (c & 1) * 32 * 392;
;       float* yb = YB + (c & 1) * 2048;
;       float* ydst = cg == 0 ? yb + row : (float*)(smem + 147712) + lane;
;       const int ystride = cg == 0 ? 64 : 0;
;       float4 ca[CPL / 4], cy[CPL / 4], cw[CPL / 4], cb[CPL / 4], ck[CPL / 4];
;       float cvv;
;       {
;         const float* o = ob + cg * CPL;
; #pragma unroll
;         for (int i = 0; i < CPL / 4; ++i) {
;           ca[i] = *(const float4*)(o + 4 * i); cy[i] = *(const float4*)(o + 64 + 4 * i); cw[i] = *(const float4*)(o + 128 + 4 * i);
;           cb[i] = *(const float4*)(o + 192 + 4 * i); ck[i] = *(const float4*)(o + 256 + 4 * i);
;         }
;         cvv = ob[320 + row];
;       }
; #pragma unroll 8
;       for (int jj = 0; jj < nst; ++jj) {
;         float4 na[CPL / 4], ny[CPL / 4], nw[CPL / 4], nb[CPL / 4], nk[CPL / 4];
;         float nvv;
;         {
;           const int jn = jj + 1;
;           const float* o = ob + jn * 392 + cg * CPL;
; #pragma unroll
;           for (int i = 0; i < CPL / 4; ++i) {
;             na[i] = *(const float4*)(o + 4 * i); ny[i] = *(const float4*)(o + 64 + 4 * i); nw[i] = *(const float4*)(o + 128 + 4 * i);
;             nb[i] = *(const float4*)(o + 192 + 4 * i); nk[i] = *(const float4*)(o + 256 + 4 * i);
;           }
;           nvv = ob[jn * 392 + 320 + row];
;         }
;         f2 A[NV], Y[NV], W[NV], B[NV], K[NV];
; #pragma unroll
;         for (int i = 0; i < CPL / 4; ++i) {
;           A[2 * i] = mk2(ca[i].x, ca[i].y); A[2 * i + 1] = mk2(ca[i].z, ca[i].w);
;           Y[2 * i] = mk2(cy[i].x, cy[i].y); Y[2 * i + 1] = mk2(cy[i].z, cy[i].w);
;           W[2 * i] = mk2(cw[i].x, cw[i].y); W[2 * i + 1] = mk2(cw[i].z, cw[i].w);
;           B[2 * i] = mk2(cb[i].x, cb[i].y); B[2 * i + 1] = mk2(cb[i].z, cb[i].w);
.LBB0_181:
	s_or_b64 exec, exec, s[2:3]
	v_ashrrev_i32_e32 v0, 6, v2
	s_and_b32 s16, s82, 1
	v_cmp_gt_i32_e32 vcc, 4, v0
	v_lshlrev_b32_e32 v52, 3, v0
	s_waitcnt lgkmcnt(0)
	s_barrier
	s_and_saveexec_b64 s[2:3], vcc
	s_xor_b64 s[2:3], exec, s[2:3]
	s_cbranch_execz .LBB0_187
	s_setprio 3
	v_and_b32_e32 v0, 63, v179
	v_lshrrev_b32_e32 v202, 6, v179
	v_and_b32_e32 v203, 7, v0
	v_lshrrev_b32_e32 v204, 3, v0
	v_lshl_add_u32 v204, v202, 3, v204
	s_lshl_b32 s8, s16, 5
	v_add_u32_e32 v204, s8, v204
	v_lshlrev_b32_e32 v202, 5, v203
	v_lshlrev_b32_e32 v204, 2, v204
	v_add_u32_e32 v205, 0x500, v204
	v_add_u32_e32 v204, 0x18800, v204
	v_lshlrev_b32_e32 v206, 2, v0
	v_add_u32_e32 v206, 0x24800, v206
	v_cmp_eq_u32_e32 vcc, 0, v203
	v_mov_b32_e32 v170, 0
	v_mov_b32_e32 v171, 0
	v_mov_b32_e32 v172, 0
	v_mov_b32_e32 v173, 0
	v_mov_b32_e32 v174, 0
	v_mov_b32_e32 v175, 0
	v_mov_b32_e32 v176, 0
	v_mov_b32_e32 v177, 0
	s_mov_b32 s10, 0
	s_barrier
.Lsc8_chunk:
	s_and_b32 s17, s10, 1
	s_mul_i32 s15, s17, 0xc400
	v_add_u32_e32 v199, s15, v202
	v_add_u32_e32 v200, s15, v205
	s_lshl_b32 s15, s17, 13
	v_add_u32_e32 v0, s15, v204
	v_cndmask_b32_e32 v201, v206, v0, vcc
	ds_read_b128 v[2:5], v199 offset:0
	ds_read_b128 v[6:9], v199 offset:16
	ds_read_b128 v[34:37], v199 offset:1024
	ds_read_b128 v[38:41], v199 offset:1040
	ds_read_b32 v42, v200 offset:0
	ds_read_b128 v[26:29], v199 offset:768
	ds_read_b128 v[30:33], v199 offset:784
	ds_read_b128 v[10:13], v199 offset:256
	ds_read_b128 v[14:17], v199 offset:272
	s_waitcnt lgkmcnt(0)
	v_pk_mul_f32 v[88:89], v[2:3], v[170:171]
	ds_read_b128 v[44:47], v199 offset:1568
	v_pk_fma_f32 v[88:89], v[4:5], v[172:173], v[88:89]
	ds_read_b128 v[48:51], v199 offset:1584
	v_pk_fma_f32 v[88:89], v[6:7], v[174:175], v[88:89]
	ds_read_b128 v[76:79], v199 offset:2592
	v_pk_fma_f32 v[88:89], v[8:9], v[176:177], v[88:89]
	ds_read_b128 v[80:83], v199 offset:2608
	v_add_f32_e32 v86, v88, v89
	ds_read_b32 v84, v200 offset:1568
	v_pk_fma_f32 v[162:163], v[34:35], v[42:43], v[170:171] op_sel_hi:[1,0,1]
	v_add_f32_dpp v86, v86, v86 quad_perm:[1,0,3,2] row_mask:0xf bank_mask:0xf bound_ctrl:1
	v_pk_fma_f32 v[164:165], v[36:37], v[42:43], v[172:173] op_sel_hi:[1,0,1]
	ds_read_b128 v[68:71], v199 offset:2336
	v_add_f32_dpp v86, v86, v86 quad_perm:[2,3,0,1] row_mask:0xf bank_mask:0xf bound_ctrl:1
	s_nop 0
	ds_read_b128 v[72:75], v199 offset:2352
	v_add_f32_dpp v86, v86, v86 row_half_mirror row_mask:0xf bank_mask:0xf bound_ctrl:1
	v_pk_fma_f32 v[166:167], v[38:39], v[42:43], v[174:175] op_sel_hi:[1,0,1]
	v_pk_fma_f32 v[168:169], v[40:41], v[42:43], v[176:177] op_sel_hi:[1,0,1]
	v_pk_fma_f32 v[94:95], v[26:27], v[86:87], v[162:163] op_sel_hi:[1,0,1]
	v_pk_fma_f32 v[96:97], v[28:29], v[86:87], v[164:165] op_sel_hi:[1,0,1]
	v_pk_fma_f32 v[98:99], v[30:31], v[86:87], v[166:167] op_sel_hi:[1,0,1]
	v_pk_fma_f32 v[100:101], v[32:33], v[86:87], v[168:169] op_sel_hi:[1,0,1]
	ds_read_b128 v[52:55], v199 offset:1824
	ds_read_b128 v[56:59], v199 offset:1840
	s_waitcnt lgkmcnt(4)
	v_pk_mul_f32 v[88:89], v[44:45], v[94:95]
	ds_read_b128 v[2:5], v199 offset:3136
	v_pk_fma_f32 v[88:89], v[46:47], v[96:97], v[88:89]
	ds_read_b128 v[6:9], v199 offset:3152
	v_pk_fma_f32 v[88:89], v[48:49], v[98:99], v[88:89]
	ds_read_b128 v[34:37], v199 offset:4160
	v_pk_fma_f32 v[88:89], v[50:51], v[100:101], v[88:89]
	ds_read_b128 v[38:41], v199 offset:4176
	v_add_f32_e32 v86, v88, v89
	ds_read_b32 v42, v200 offset:3136
	v_pk_fma_f32 v[162:163], v[76:77], v[84:85], v[94:95] op_sel_hi:[1,0,1]
	v_add_f32_dpp v86, v86, v86 quad_perm:[1,0,3,2] row_mask:0xf bank_mask:0xf bound_ctrl:1
	v_pk_fma_f32 v[164:165], v[78:79], v[84:85], v[96:97] op_sel_hi:[1,0,1]
	ds_read_b128 v[26:29], v199 offset:3904
	v_add_f32_dpp v86, v86, v86 quad_perm:[2,3,0,1] row_mask:0xf bank_mask:0xf bound_ctrl:1
	s_nop 0
	ds_read_b128 v[30:33], v199 offset:3920
	v_add_f32_dpp v86, v86, v86 row_half_mirror row_mask:0xf bank_mask:0xf bound_ctrl:1
	v_pk_fma_f32 v[166:167], v[80:81], v[84:85], v[98:99] op_sel_hi:[1,0,1]
	v_pk_fma_f32 v[168:169], v[82:83], v[84:85], v[100:101] op_sel_hi:[1,0,1]
	s_waitcnt lgkmcnt(9)
	v_pk_fma_f32 v[170:171], v[68:69], v[86:87], v[162:163] op_sel_hi:[1,0,1]
	v_pk_fma_f32 v[172:173], v[70:71], v[86:87], v[164:165] op_sel_hi:[1,0,1]
	v_pk_fma_f32 v[174:175], v[72:73], v[86:87], v[166:167] op_sel_hi:[1,0,1]
	v_pk_fma_f32 v[176:177], v[74:75], v[86:87], v[168:169] op_sel_hi:[1,0,1]
	v_pk_mul_f32 v[90:91], v[10:11], v[94:95]
	v_pk_fma_f32 v[90:91], v[12:13], v[96:97], v[90:91]
	v_pk_fma_f32 v[90:91], v[14:15], v[98:99], v[90:91]
	v_pk_fma_f32 v[90:91], v[16:17], v[100:101], v[90:91]
	ds_read_b128 v[10:13], v199 offset:3392
	v_add_f32_e32 v92, v90, v91
	ds_read_b128 v[14:17], v199 offset:3408
	s_waitcnt lgkmcnt(4)
	v_pk_mul_f32 v[88:89], v[2:3], v[170:171]
	ds_read_b128 v[44:47], v199 offset:4704
	v_pk_fma_f32 v[88:89], v[4:5], v[172:173], v[88:89]
	ds_read_b128 v[48:51], v199 offset:4720
	v_pk_fma_f32 v[88:89], v[6:7], v[174:175], v[88:89]
	ds_read_b128 v[76:79], v199 offset:5728
	v_pk_fma_f32 v[88:89], v[8:9], v[176:177], v[88:89]
	ds_read_b128 v[80:83], v199 offset:5744
	v_add_f32_e32 v86, v88, v89
	ds_read_b32 v84, v200 offset:4704
	v_pk_fma_f32 v[162:163], v[34:35], v[42:43], v[170:171] op_sel_hi:[1,0,1]
	v_add_f32_dpp v86, v86, v86 quad_perm:[1,0,3,2] row_mask:0xf bank_mask:0xf bound_ctrl:1
	v_add_f32_dpp v92, v92, v92 quad_perm:[1,0,3,2] row_mask:0xf bank_mask:0xf bound_ctrl:1
	ds_read_b128 v[68:71], v199 offset:5472
	v_add_f32_dpp v86, v86, v86 quad_perm:[2,3,0,1] row_mask:0xf bank_mask:0xf bound_ctrl:1
	v_add_f32_dpp v92, v92, v92 quad_perm:[2,3,0,1] row_mask:0xf bank_mask:0xf bound_ctrl:1
	ds_read_b128 v[72:75], v199 offset:5488
	v_add_f32_dpp v86, v86, v86 row_half_mirror row_mask:0xf bank_mask:0xf bound_ctrl:1
	v_add_f32_dpp v92, v92, v92 row_half_mirror row_mask:0xf bank_mask:0xf bound_ctrl:1
	v_pk_fma_f32 v[164:165], v[36:37], v[42:43], v[172:173] op_sel_hi:[1,0,1]
	v_pk_fma_f32 v[166:167], v[38:39], v[42:43], v[174:175] op_sel_hi:[1,0,1]
	v_pk_fma_f32 v[168:169], v[40:41], v[42:43], v[176:177] op_sel_hi:[1,0,1]
	s_waitcnt lgkmcnt(9)
; template <int CPL>
; DI void scan_block2(CP p, int layer, int s, int d, int hd, int rowhalf, char* smem) {
;     ...
; #pragma unroll 8
;       for (int jj = 0; jj < nst; ++jj) {
;         float4 na[CPL / 4], ny[CPL / 4], nw[CPL / 4], nb[CPL / 4], nk[CPL / 4];
;         float nvv;
;         {
;           const int jn = jj + 1;
;           const float* o = ob + jn * 392 + cg * CPL;
; #pragma unroll
;           for (int i = 0; i < CPL / 4; ++i) {
;             na[i] = *(const float4*)(o + 4 * i); ny[i] = *(const float4*)(o + 64 + 4 * i); nw[i] = *(const float4*)(o + 128 + 4 * i);
;             nb[i] = *(const float4*)(o + 192 + 4 * i); nk[i] = *(const float4*)(o + 256 + 4 * i);
;           }
;           nvv = ob[jn * 392 + 320 + row];
;         }
;         f2 A[NV], Y[NV], W[NV], B[NV], K[NV];
; #pragma unroll
;         for (int i = 0; i < CPL / 4; ++i) {
;           A[2 * i] = mk2(ca[i].x, ca[i].y); A[2 * i + 1] = mk2(ca[i].z, ca[i].w);
;           Y[2 * i] = mk2(cy[i].x, cy[i].y); Y[2 * i + 1] = mk2(cy[i].z, cy[i].w);
;           W[2 * i] = mk2(cw[i].x, cw[i].y); W[2 * i + 1] = mk2(cw[i].z, cw[i].w);
;           B[2 * i] = mk2(cb[i].x, cb[i].y); B[2 * i + 1] = mk2(cb[i].z, cb[i].w);
;           K[2 * i] = mk2(ck[i].x, ck[i].y); K[2 * i + 1] = mk2(ck[i].z, ck[i].w);
;         }
;         const float vv = cvv;
;         f2 pa0 = S[0] * A[0], pa1 = S[1] * A[1];
; #pragma unroll
;         for (int i = 2; i < NV; i += 2) { pa0 = S[i] * A[i] + pa0; pa1 = S[i + 1] * A[i + 1] + pa1; }
;         pa0 = pa0 + pa1;
;         float da = pa0.x + pa0.y;
;         const f2 vvv = mk2(vv, vv);
;         f2 SW[NV];
; #pragma unroll
;         for (int i = 0; i < NV; ++i) SW[i] = S[i] * W[i] + vvv * K[i];
;         da += __int_as_float(__builtin_amdgcn_update_dpp(0, __float_as_int(da), 0xB1, 0xf, 0xf, false));
;         da += __int_as_float(__builtin_amdgcn_update_dpp(0, __float_as_int(da), 0x4E, 0xf, 0xf, false));
;         if (CPL == 8) da += __int_as_float(__builtin_amdgcn_update_dpp(0, __float_as_int(da), 0x141, 0xf, 0xf, false));
;         const f2 dav = mk2(da, da);
; #pragma unroll
;         for (int i = 0; i < NV; ++i) S[i] = dav * B[i] + SW[i];
;         f2 py0 = S[0] * Y[0], py1 = S[1] * Y[1];
; #pragma unroll
;         for (int i = 2; i < NV; i += 2) { py0 = S[i] * Y[i] + py0; py1 = S[i + 1] * Y[i + 1] + py1; }
;         py0 = py0 + py1;
;         float yv = py0.x + py0.y;
	v_pk_fma_f32 v[94:95], v[26:27], v[86:87], v[162:163] op_sel_hi:[1,0,1]
	v_pk_fma_f32 v[96:97], v[28:29], v[86:87], v[164:165] op_sel_hi:[1,0,1]
	v_pk_fma_f32 v[98:99], v[30:31], v[86:87], v[166:167] op_sel_hi:[1,0,1]
	v_pk_fma_f32 v[100:101], v[32:33], v[86:87], v[168:169] op_sel_hi:[1,0,1]
	ds_write_b32 v201, v92 offset:0
	v_pk_mul_f32 v[90:91], v[52:53], v[170:171]
	v_pk_fma_f32 v[90:91], v[54:55], v[172:173], v[90:91]
	v_pk_fma_f32 v[90:91], v[56:57], v[174:175], v[90:91]
	v_pk_fma_f32 v[90:91], v[58:59], v[176:177], v[90:91]
	ds_read_b128 v[52:55], v199 offset:4960
	v_add_f32_e32 v93, v90, v91
	ds_read_b128 v[56:59], v199 offset:4976
	s_waitcnt lgkmcnt(5)
	v_pk_mul_f32 v[88:89], v[44:45], v[94:95]
	ds_read_b128 v[2:5], v199 offset:6272
	v_pk_fma_f32 v[88:89], v[46:47], v[96:97], v[88:89]
	ds_read_b128 v[6:9], v199 offset:6288
	v_pk_fma_f32 v[88:89], v[48:49], v[98:99], v[88:89]
	ds_read_b128 v[34:37], v199 offset:7296
	v_pk_fma_f32 v[88:89], v[50:51], v[100:101], v[88:89]
	ds_read_b128 v[38:41], v199 offset:7312
	v_add_f32_e32 v86, v88, v89
	ds_read_b32 v42, v200 offset:6272
	ds_read_b128 v[18:21], v199 offset:5216
	ds_read_b128 v[22:25], v199 offset:5232
	v_add_f32_dpp v86, v86, v86 quad_perm:[1,0,3,2] row_mask:0xf bank_mask:0xf bound_ctrl:1
	v_add_f32_dpp v93, v93, v93 quad_perm:[1,0,3,2] row_mask:0xf bank_mask:0xf bound_ctrl:1
	ds_read_b128 v[26:29], v199 offset:7040
	v_add_f32_dpp v86, v86, v86 quad_perm:[2,3,0,1] row_mask:0xf bank_mask:0xf bound_ctrl:1
	v_add_f32_dpp v93, v93, v93 quad_perm:[2,3,0,1] row_mask:0xf bank_mask:0xf bound_ctrl:1
	ds_read_b128 v[30:33], v199 offset:7056
	v_add_f32_dpp v86, v86, v86 row_half_mirror row_mask:0xf bank_mask:0xf bound_ctrl:1
	v_add_f32_dpp v93, v93, v93 row_half_mirror row_mask:0xf bank_mask:0xf bound_ctrl:1
	v_pk_fma_f32 v[162:163], v[76:77], v[84:85], v[94:95] op_sel_hi:[1,0,1]
	v_pk_fma_f32 v[164:165], v[78:79], v[84:85], v[96:97] op_sel_hi:[1,0,1]
	v_pk_fma_f32 v[166:167], v[80:81], v[84:85], v[98:99] op_sel_hi:[1,0,1]
	v_pk_fma_f32 v[168:169], v[82:83], v[84:85], v[100:101] op_sel_hi:[1,0,1]
	s_waitcnt lgkmcnt(12)
	v_pk_fma_f32 v[170:171], v[68:69], v[86:87], v[162:163] op_sel_hi:[1,0,1]
	v_pk_fma_f32 v[172:173], v[70:71], v[86:87], v[164:165] op_sel_hi:[1,0,1]
	v_pk_fma_f32 v[174:175], v[72:73], v[86:87], v[166:167] op_sel_hi:[1,0,1]
	v_pk_fma_f32 v[176:177], v[74:75], v[86:87], v[168:169] op_sel_hi:[1,0,1]
	s_waitcnt lgkmcnt(2)
	v_pk_mul_f32 v[170:171], v[170:171], v[18:19]
	v_pk_mul_f32 v[172:173], v[172:173], v[20:21]
	v_pk_mul_f32 v[174:175], v[174:175], v[22:23]
	v_pk_mul_f32 v[176:177], v[176:177], v[24:25]
	ds_write_b32 v201, v93 offset:256
	v_pk_mul_f32 v[90:91], v[10:11], v[94:95]
	v_pk_fma_f32 v[90:91], v[12:13], v[96:97], v[90:91]
	v_pk_fma_f32 v[90:91], v[14:15], v[98:99], v[90:91]
	v_pk_fma_f32 v[90:91], v[16:17], v[100:101], v[90:91]
	ds_read_b128 v[10:13], v199 offset:6528
	v_add_f32_e32 v92, v90, v91
	ds_read_b128 v[14:17], v199 offset:6544
	s_waitcnt lgkmcnt(7)
	v_pk_mul_f32 v[88:89], v[2:3], v[170:171]
	ds_read_b128 v[44:47], v199 offset:7840
	v_pk_fma_f32 v[88:89], v[4:5], v[172:173], v[88:89]
	ds_read_b128 v[48:51], v199 offset:7856
	v_pk_fma_f32 v[88:89], v[6:7], v[174:175], v[88:89]
	ds_read_b128 v[76:79], v199 offset:8864
	v_pk_fma_f32 v[88:89], v[8:9], v[176:177], v[88:89]
	ds_read_b128 v[80:83], v199 offset:8880
	v_add_f32_e32 v86, v88, v89
	ds_read_b32 v84, v200 offset:7840
	v_pk_fma_f32 v[162:163], v[34:35], v[42:43], v[170:171] op_sel_hi:[1,0,1]
	v_add_f32_dpp v86, v86, v86 quad_perm:[1,0,3,2] row_mask:0xf bank_mask:0xf bound_ctrl:1
	v_add_f32_dpp v92, v92, v92 quad_perm:[1,0,3,2] row_mask:0xf bank_mask:0xf bound_ctrl:1
	ds_read_b128 v[68:71], v199 offset:8608
	v_add_f32_dpp v86, v86, v86 quad_perm:[2,3,0,1] row_mask:0xf bank_mask:0xf bound_ctrl:1
	v_add_f32_dpp v92, v92, v92 quad_perm:[2,3,0,1] row_mask:0xf bank_mask:0xf bound_ctrl:1
	ds_read_b128 v[72:75], v199 offset:8624
	v_add_f32_dpp v86, v86, v86 row_half_mirror row_mask:0xf bank_mask:0xf bound_ctrl:1
	v_add_f32_dpp v92, v92, v92 row_half_mirror row_mask:0xf bank_mask:0xf bound_ctrl:1
	v_pk_fma_f32 v[164:165], v[36:37], v[42:43], v[172:173] op_sel_hi:[1,0,1]
	v_pk_fma_f32 v[166:167], v[38:39], v[42:43], v[174:175] op_sel_hi:[1,0,1]
	v_pk_fma_f32 v[168:169], v[40:41], v[42:43], v[176:177] op_sel_hi:[1,0,1]
	s_waitcnt lgkmcnt(10)
	v_pk_fma_f32 v[94:95], v[26:27], v[86:87], v[162:163] op_sel_hi:[1,0,1]
	v_pk_fma_f32 v[96:97], v[28:29], v[86:87], v[164:165] op_sel_hi:[1,0,1]
	v_pk_fma_f32 v[98:99], v[30:31], v[86:87], v[166:167] op_sel_hi:[1,0,1]
	v_pk_fma_f32 v[100:101], v[32:33], v[86:87], v[168:169] op_sel_hi:[1,0,1]
	ds_write_b32 v201, v92 offset:512
	v_pk_mul_f32 v[90:91], v[52:53], v[170:171]
	v_pk_fma_f32 v[90:91], v[54:55], v[172:173], v[90:91]
	v_pk_fma_f32 v[90:91], v[56:57], v[174:175], v[90:91]
	v_pk_fma_f32 v[90:91], v[58:59], v[176:177], v[90:91]
	ds_read_b128 v[52:55], v199 offset:8096
	v_add_f32_e32 v93, v90, v91
	ds_read_b128 v[56:59], v199 offset:8112
	s_waitcnt lgkmcnt(5)
; template <int CPL>
; DI void scan_block2(CP p, int layer, int s, int d, int hd, int rowhalf, char* smem) {
;     ...
; #pragma unroll 8
;       for (int jj = 0; jj < nst; ++jj) {
;         float4 na[CPL / 4], ny[CPL / 4], nw[CPL / 4], nb[CPL / 4], nk[CPL / 4];
;         float nvv;
;         {
;           const int jn = jj + 1;
;           const float* o = ob + jn * 392 + cg * CPL;
; #pragma unroll
;           for (int i = 0; i < CPL / 4; ++i) {
;             na[i] = *(const float4*)(o + 4 * i); ny[i] = *(const float4*)(o + 64 + 4 * i); nw[i] = *(const float4*)(o + 128 + 4 * i);
;             nb[i] = *(const float4*)(o + 192 + 4 * i); nk[i] = *(const float4*)(o + 256 + 4 * i);
;           }
;           nvv = ob[jn * 392 + 320 + row];
;         }
;         f2 A[NV], Y[NV], W[NV], B[NV], K[NV];
; #pragma unroll
;         for (int i = 0; i < CPL / 4; ++i) {
;           A[2 * i] = mk2(ca[i].x, ca[i].y); A[2 * i + 1] = mk2(ca[i].z, ca[i].w);
;           Y[2 * i] = mk2(cy[i].x, cy[i].y); Y[2 * i + 1] = mk2(cy[i].z, cy[i].w);
;           W[2 * i] = mk2(cw[i].x, cw[i].y); W[2 * i + 1] = mk2(cw[i].z, cw[i].w);
;           B[2 * i] = mk2(cb[i].x, cb[i].y); B[2 * i + 1] = mk2(cb[i].z, cb[i].w);
;           K[2 * i] = mk2(ck[i].x, ck[i].y); K[2 * i + 1] = mk2(ck[i].z, ck[i].w);
;         }
;         const float vv = cvv;
;         f2 pa0 = S[0] * A[0], pa1 = S[1] * A[1];
; #pragma unroll
;         for (int i = 2; i < NV; i += 2) { pa0 = S[i] * A[i] + pa0; pa1 = S[i + 1] * A[i + 1] + pa1; }
;         pa0 = pa0 + pa1;
;         float da = pa0.x + pa0.y;
;         const f2 vvv = mk2(vv, vv);
;         f2 SW[NV];
; #pragma unroll
;         for (int i = 0; i < NV; ++i) SW[i] = S[i] * W[i] + vvv * K[i];
;         da += __int_as_float(__builtin_amdgcn_update_dpp(0, __float_as_int(da), 0xB1, 0xf, 0xf, false));
;         da += __int_as_float(__builtin_amdgcn_update_dpp(0, __float_as_int(da), 0x4E, 0xf, 0xf, false));
;         if (CPL == 8) da += __int_as_float(__builtin_amdgcn_update_dpp(0, __float_as_int(da), 0x141, 0xf, 0xf, false));
;         const f2 dav = mk2(da, da);
; #pragma unroll
;         for (int i = 0; i < NV; ++i) S[i] = dav * B[i] + SW[i];
;         f2 py0 = S[0] * Y[0], py1 = S[1] * Y[1];
; #pragma unroll
;         for (int i = 2; i < NV; i += 2) { py0 = S[i] * Y[i] + py0; py1 = S[i + 1] * Y[i + 1] + py1; }
;         py0 = py0 + py1;
;         float yv = py0.x + py0.y;
	v_pk_mul_f32 v[88:89], v[44:45], v[94:95]
	ds_read_b128 v[2:5], v199 offset:9408
	v_pk_fma_f32 v[88:89], v[46:47], v[96:97], v[88:89]
	ds_read_b128 v[6:9], v199 offset:9424
	v_pk_fma_f32 v[88:89], v[48:49], v[98:99], v[88:89]
	ds_read_b128 v[34:37], v199 offset:10432
	v_pk_fma_f32 v[88:89], v[50:51], v[100:101], v[88:89]
	ds_read_b128 v[38:41], v199 offset:10448
	v_add_f32_e32 v86, v88, v89
	ds_read_b32 v42, v200 offset:9408
	v_pk_fma_f32 v[162:163], v[76:77], v[84:85], v[94:95] op_sel_hi:[1,0,1]
	v_add_f32_dpp v86, v86, v86 quad_perm:[1,0,3,2] row_mask:0xf bank_mask:0xf bound_ctrl:1
	v_add_f32_dpp v93, v93, v93 quad_perm:[1,0,3,2] row_mask:0xf bank_mask:0xf bound_ctrl:1
	ds_read_b128 v[26:29], v199 offset:10176
	v_add_f32_dpp v86, v86, v86 quad_perm:[2,3,0,1] row_mask:0xf bank_mask:0xf bound_ctrl:1
	v_add_f32_dpp v93, v93, v93 quad_perm:[2,3,0,1] row_mask:0xf bank_mask:0xf bound_ctrl:1
	ds_read_b128 v[30:33], v199 offset:10192
	v_add_f32_dpp v86, v86, v86 row_half_mirror row_mask:0xf bank_mask:0xf bound_ctrl:1
	v_add_f32_dpp v93, v93, v93 row_half_mirror row_mask:0xf bank_mask:0xf bound_ctrl:1
	v_pk_fma_f32 v[164:165], v[78:79], v[84:85], v[96:97] op_sel_hi:[1,0,1]
	v_pk_fma_f32 v[166:167], v[80:81], v[84:85], v[98:99] op_sel_hi:[1,0,1]
	v_pk_fma_f32 v[168:169], v[82:83], v[84:85], v[100:101] op_sel_hi:[1,0,1]
	s_waitcnt lgkmcnt(10)
	v_pk_fma_f32 v[170:171], v[68:69], v[86:87], v[162:163] op_sel_hi:[1,0,1]
	v_pk_fma_f32 v[172:173], v[70:71], v[86:87], v[164:165] op_sel_hi:[1,0,1]
	v_pk_fma_f32 v[174:175], v[72:73], v[86:87], v[166:167] op_sel_hi:[1,0,1]
	v_pk_fma_f32 v[176:177], v[74:75], v[86:87], v[168:169] op_sel_hi:[1,0,1]
	ds_write_b32 v201, v93 offset:768
	v_pk_mul_f32 v[90:91], v[10:11], v[94:95]
	v_pk_fma_f32 v[90:91], v[12:13], v[96:97], v[90:91]
	v_pk_fma_f32 v[90:91], v[14:15], v[98:99], v[90:91]
	v_pk_fma_f32 v[90:91], v[16:17], v[100:101], v[90:91]
	ds_read_b128 v[10:13], v199 offset:9664
	v_add_f32_e32 v92, v90, v91
	ds_read_b128 v[14:17], v199 offset:9680
	s_waitcnt lgkmcnt(5)
	v_pk_mul_f32 v[88:89], v[2:3], v[170:171]
	ds_read_b128 v[44:47], v199 offset:10976
	v_pk_fma_f32 v[88:89], v[4:5], v[172:173], v[88:89]
	ds_read_b128 v[48:51], v199 offset:10992
	v_pk_fma_f32 v[88:89], v[6:7], v[174:175], v[88:89]
	ds_read_b128 v[76:79], v199 offset:12000
	v_pk_fma_f32 v[88:89], v[8:9], v[176:177], v[88:89]
	ds_read_b128 v[80:83], v199 offset:12016
	v_add_f32_e32 v86, v88, v89
	ds_read_b32 v84, v200 offset:10976
	v_pk_fma_f32 v[162:163], v[34:35], v[42:43], v[170:171] op_sel_hi:[1,0,1]
	v_add_f32_dpp v86, v86, v86 quad_perm:[1,0,3,2] row_mask:0xf bank_mask:0xf bound_ctrl:1
	v_add_f32_dpp v92, v92, v92 quad_perm:[1,0,3,2] row_mask:0xf bank_mask:0xf bound_ctrl:1
	ds_read_b128 v[68:71], v199 offset:11744
	v_add_f32_dpp v86, v86, v86 quad_perm:[2,3,0,1] row_mask:0xf bank_mask:0xf bound_ctrl:1
	v_add_f32_dpp v92, v92, v92 quad_perm:[2,3,0,1] row_mask:0xf bank_mask:0xf bound_ctrl:1
	ds_read_b128 v[72:75], v199 offset:11760
	v_add_f32_dpp v86, v86, v86 row_half_mirror row_mask:0xf bank_mask:0xf bound_ctrl:1
	v_add_f32_dpp v92, v92, v92 row_half_mirror row_mask:0xf bank_mask:0xf bound_ctrl:1
	v_pk_fma_f32 v[164:165], v[36:37], v[42:43], v[172:173] op_sel_hi:[1,0,1]
	v_pk_fma_f32 v[166:167], v[38:39], v[42:43], v[174:175] op_sel_hi:[1,0,1]
	v_pk_fma_f32 v[168:169], v[40:41], v[42:43], v[176:177] op_sel_hi:[1,0,1]
	s_waitcnt lgkmcnt(10)
	v_pk_fma_f32 v[94:95], v[26:27], v[86:87], v[162:163] op_sel_hi:[1,0,1]
	v_pk_fma_f32 v[96:97], v[28:29], v[86:87], v[164:165] op_sel_hi:[1,0,1]
	v_pk_fma_f32 v[98:99], v[30:31], v[86:87], v[166:167] op_sel_hi:[1,0,1]
	v_pk_fma_f32 v[100:101], v[32:33], v[86:87], v[168:169] op_sel_hi:[1,0,1]
	ds_write_b32 v201, v92 offset:1024
	v_pk_mul_f32 v[90:91], v[52:53], v[170:171]
	v_pk_fma_f32 v[90:91], v[54:55], v[172:173], v[90:91]
	v_pk_fma_f32 v[90:91], v[56:57], v[174:175], v[90:91]
	v_pk_fma_f32 v[90:91], v[58:59], v[176:177], v[90:91]
	ds_read_b128 v[52:55], v199 offset:11232
	v_add_f32_e32 v93, v90, v91
	ds_read_b128 v[56:59], v199 offset:11248
	s_waitcnt lgkmcnt(5)
	v_pk_mul_f32 v[88:89], v[44:45], v[94:95]
	ds_read_b128 v[2:5], v199 offset:12544
	v_pk_fma_f32 v[88:89], v[46:47], v[96:97], v[88:89]
	ds_read_b128 v[6:9], v199 offset:12560
	v_pk_fma_f32 v[88:89], v[48:49], v[98:99], v[88:89]
	ds_read_b128 v[34:37], v199 offset:13568
	v_pk_fma_f32 v[88:89], v[50:51], v[100:101], v[88:89]
	ds_read_b128 v[38:41], v199 offset:13584
	v_add_f32_e32 v86, v88, v89
	ds_read_b32 v42, v200 offset:12544
	ds_read_b128 v[18:21], v199 offset:11488
	ds_read_b128 v[22:25], v199 offset:11504
	v_add_f32_dpp v86, v86, v86 quad_perm:[1,0,3,2] row_mask:0xf bank_mask:0xf bound_ctrl:1
	v_add_f32_dpp v93, v93, v93 quad_perm:[1,0,3,2] row_mask:0xf bank_mask:0xf bound_ctrl:1
	ds_read_b128 v[26:29], v199 offset:13312
	v_add_f32_dpp v86, v86, v86 quad_perm:[2,3,0,1] row_mask:0xf bank_mask:0xf bound_ctrl:1
	v_add_f32_dpp v93, v93, v93 quad_perm:[2,3,0,1] row_mask:0xf bank_mask:0xf bound_ctrl:1
	ds_read_b128 v[30:33], v199 offset:13328
	v_add_f32_dpp v86, v86, v86 row_half_mirror row_mask:0xf bank_mask:0xf bound_ctrl:1
	v_add_f32_dpp v93, v93, v93 row_half_mirror row_mask:0xf bank_mask:0xf bound_ctrl:1
	v_pk_fma_f32 v[162:163], v[76:77], v[84:85], v[94:95] op_sel_hi:[1,0,1]
	v_pk_fma_f32 v[164:165], v[78:79], v[84:85], v[96:97] op_sel_hi:[1,0,1]
	v_pk_fma_f32 v[166:167], v[80:81], v[84:85], v[98:99] op_sel_hi:[1,0,1]
	v_pk_fma_f32 v[168:169], v[82:83], v[84:85], v[100:101] op_sel_hi:[1,0,1]
	s_waitcnt lgkmcnt(12)
; template <int CPL>
; DI void scan_block2(CP p, int layer, int s, int d, int hd, int rowhalf, char* smem) {
;     ...
; #pragma unroll 8
;       for (int jj = 0; jj < nst; ++jj) {
;         float4 na[CPL / 4], ny[CPL / 4], nw[CPL / 4], nb[CPL / 4], nk[CPL / 4];
;         float nvv;
;         {
;           const int jn = jj + 1;
;           const float* o = ob + jn * 392 + cg * CPL;
; #pragma unroll
;           for (int i = 0; i < CPL / 4; ++i) {
;             na[i] = *(const float4*)(o + 4 * i); ny[i] = *(const float4*)(o + 64 + 4 * i); nw[i] = *(const float4*)(o + 128 + 4 * i);
;             nb[i] = *(const float4*)(o + 192 + 4 * i); nk[i] = *(const float4*)(o + 256 + 4 * i);
;           }
;           nvv = ob[jn * 392 + 320 + row];
;         }
;         f2 A[NV], Y[NV], W[NV], B[NV], K[NV];
; #pragma unroll
;         for (int i = 0; i < CPL / 4; ++i) {
;           A[2 * i] = mk2(ca[i].x, ca[i].y); A[2 * i + 1] = mk2(ca[i].z, ca[i].w);
;           Y[2 * i] = mk2(cy[i].x, cy[i].y); Y[2 * i + 1] = mk2(cy[i].z, cy[i].w);
;           W[2 * i] = mk2(cw[i].x, cw[i].y); W[2 * i + 1] = mk2(cw[i].z, cw[i].w);
;           B[2 * i] = mk2(cb[i].x, cb[i].y); B[2 * i + 1] = mk2(cb[i].z, cb[i].w);
;           K[2 * i] = mk2(ck[i].x, ck[i].y); K[2 * i + 1] = mk2(ck[i].z, ck[i].w);
;         }
;         const float vv = cvv;
;         f2 pa0 = S[0] * A[0], pa1 = S[1] * A[1];
; #pragma unroll
;         for (int i = 2; i < NV; i += 2) { pa0 = S[i] * A[i] + pa0; pa1 = S[i + 1] * A[i + 1] + pa1; }
;         pa0 = pa0 + pa1;
;         float da = pa0.x + pa0.y;
;         const f2 vvv = mk2(vv, vv);
;         f2 SW[NV];
; #pragma unroll
;         for (int i = 0; i < NV; ++i) SW[i] = S[i] * W[i] + vvv * K[i];
;         da += __int_as_float(__builtin_amdgcn_update_dpp(0, __float_as_int(da), 0xB1, 0xf, 0xf, false));
;         da += __int_as_float(__builtin_amdgcn_update_dpp(0, __float_as_int(da), 0x4E, 0xf, 0xf, false));
;         if (CPL == 8) da += __int_as_float(__builtin_amdgcn_update_dpp(0, __float_as_int(da), 0x141, 0xf, 0xf, false));
;         const f2 dav = mk2(da, da);
; #pragma unroll
;         for (int i = 0; i < NV; ++i) S[i] = dav * B[i] + SW[i];
;         f2 py0 = S[0] * Y[0], py1 = S[1] * Y[1];
; #pragma unroll
;         for (int i = 2; i < NV; i += 2) { py0 = S[i] * Y[i] + py0; py1 = S[i + 1] * Y[i + 1] + py1; }
;         py0 = py0 + py1;
;         float yv = py0.x + py0.y;
	v_pk_fma_f32 v[170:171], v[68:69], v[86:87], v[162:163] op_sel_hi:[1,0,1]
	v_pk_fma_f32 v[172:173], v[70:71], v[86:87], v[164:165] op_sel_hi:[1,0,1]
	v_pk_fma_f32 v[174:175], v[72:73], v[86:87], v[166:167] op_sel_hi:[1,0,1]
	v_pk_fma_f32 v[176:177], v[74:75], v[86:87], v[168:169] op_sel_hi:[1,0,1]
	s_waitcnt lgkmcnt(2)
	v_pk_mul_f32 v[170:171], v[170:171], v[18:19]
	v_pk_mul_f32 v[172:173], v[172:173], v[20:21]
	v_pk_mul_f32 v[174:175], v[174:175], v[22:23]
	v_pk_mul_f32 v[176:177], v[176:177], v[24:25]
	ds_write_b32 v201, v93 offset:1280
	v_pk_mul_f32 v[90:91], v[10:11], v[94:95]
	v_pk_fma_f32 v[90:91], v[12:13], v[96:97], v[90:91]
	v_pk_fma_f32 v[90:91], v[14:15], v[98:99], v[90:91]
	v_pk_fma_f32 v[90:91], v[16:17], v[100:101], v[90:91]
	ds_read_b128 v[10:13], v199 offset:12800
	v_add_f32_e32 v92, v90, v91
	ds_read_b128 v[14:17], v199 offset:12816
	s_waitcnt lgkmcnt(7)
	v_pk_mul_f32 v[88:89], v[2:3], v[170:171]
	ds_read_b128 v[44:47], v199 offset:14112
	v_pk_fma_f32 v[88:89], v[4:5], v[172:173], v[88:89]
	ds_read_b128 v[48:51], v199 offset:14128
	v_pk_fma_f32 v[88:89], v[6:7], v[174:175], v[88:89]
	ds_read_b128 v[76:79], v199 offset:15136
	v_pk_fma_f32 v[88:89], v[8:9], v[176:177], v[88:89]
	ds_read_b128 v[80:83], v199 offset:15152
	v_add_f32_e32 v86, v88, v89
	ds_read_b32 v84, v200 offset:14112
	v_pk_fma_f32 v[162:163], v[34:35], v[42:43], v[170:171] op_sel_hi:[1,0,1]
	v_add_f32_dpp v86, v86, v86 quad_perm:[1,0,3,2] row_mask:0xf bank_mask:0xf bound_ctrl:1
	v_add_f32_dpp v92, v92, v92 quad_perm:[1,0,3,2] row_mask:0xf bank_mask:0xf bound_ctrl:1
	ds_read_b128 v[68:71], v199 offset:14880
	v_add_f32_dpp v86, v86, v86 quad_perm:[2,3,0,1] row_mask:0xf bank_mask:0xf bound_ctrl:1
	v_add_f32_dpp v92, v92, v92 quad_perm:[2,3,0,1] row_mask:0xf bank_mask:0xf bound_ctrl:1
	ds_read_b128 v[72:75], v199 offset:14896
	v_add_f32_dpp v86, v86, v86 row_half_mirror row_mask:0xf bank_mask:0xf bound_ctrl:1
	v_add_f32_dpp v92, v92, v92 row_half_mirror row_mask:0xf bank_mask:0xf bound_ctrl:1
	v_pk_fma_f32 v[164:165], v[36:37], v[42:43], v[172:173] op_sel_hi:[1,0,1]
	v_pk_fma_f32 v[166:167], v[38:39], v[42:43], v[174:175] op_sel_hi:[1,0,1]
	v_pk_fma_f32 v[168:169], v[40:41], v[42:43], v[176:177] op_sel_hi:[1,0,1]
	s_waitcnt lgkmcnt(10)
	v_pk_fma_f32 v[94:95], v[26:27], v[86:87], v[162:163] op_sel_hi:[1,0,1]
	v_pk_fma_f32 v[96:97], v[28:29], v[86:87], v[164:165] op_sel_hi:[1,0,1]
	v_pk_fma_f32 v[98:99], v[30:31], v[86:87], v[166:167] op_sel_hi:[1,0,1]
	v_pk_fma_f32 v[100:101], v[32:33], v[86:87], v[168:169] op_sel_hi:[1,0,1]
	ds_write_b32 v201, v92 offset:1536
	v_pk_mul_f32 v[90:91], v[52:53], v[170:171]
	v_pk_fma_f32 v[90:91], v[54:55], v[172:173], v[90:91]
	v_pk_fma_f32 v[90:91], v[56:57], v[174:175], v[90:91]
	v_pk_fma_f32 v[90:91], v[58:59], v[176:177], v[90:91]
	ds_read_b128 v[52:55], v199 offset:14368
	v_add_f32_e32 v93, v90, v91
	ds_read_b128 v[56:59], v199 offset:14384
	s_waitcnt lgkmcnt(5)
	v_pk_mul_f32 v[88:89], v[44:45], v[94:95]
	ds_read_b128 v[2:5], v199 offset:15680
	v_pk_fma_f32 v[88:89], v[46:47], v[96:97], v[88:89]
	ds_read_b128 v[6:9], v199 offset:15696
	v_pk_fma_f32 v[88:89], v[48:49], v[98:99], v[88:89]
	ds_read_b128 v[34:37], v199 offset:16704
	v_pk_fma_f32 v[88:89], v[50:51], v[100:101], v[88:89]
	ds_read_b128 v[38:41], v199 offset:16720
	v_add_f32_e32 v86, v88, v89
	ds_read_b32 v42, v200 offset:15680
	v_pk_fma_f32 v[162:163], v[76:77], v[84:85], v[94:95] op_sel_hi:[1,0,1]
	v_add_f32_dpp v86, v86, v86 quad_perm:[1,0,3,2] row_mask:0xf bank_mask:0xf bound_ctrl:1
	v_add_f32_dpp v93, v93, v93 quad_perm:[1,0,3,2] row_mask:0xf bank_mask:0xf bound_ctrl:1
	ds_read_b128 v[26:29], v199 offset:16448
	v_add_f32_dpp v86, v86, v86 quad_perm:[2,3,0,1] row_mask:0xf bank_mask:0xf bound_ctrl:1
	v_add_f32_dpp v93, v93, v93 quad_perm:[2,3,0,1] row_mask:0xf bank_mask:0xf bound_ctrl:1
	ds_read_b128 v[30:33], v199 offset:16464
	v_add_f32_dpp v86, v86, v86 row_half_mirror row_mask:0xf bank_mask:0xf bound_ctrl:1
	v_add_f32_dpp v93, v93, v93 row_half_mirror row_mask:0xf bank_mask:0xf bound_ctrl:1
	v_pk_fma_f32 v[164:165], v[78:79], v[84:85], v[96:97] op_sel_hi:[1,0,1]
	v_pk_fma_f32 v[166:167], v[80:81], v[84:85], v[98:99] op_sel_hi:[1,0,1]
	v_pk_fma_f32 v[168:169], v[82:83], v[84:85], v[100:101] op_sel_hi:[1,0,1]
	s_waitcnt lgkmcnt(10)
	v_pk_fma_f32 v[170:171], v[68:69], v[86:87], v[162:163] op_sel_hi:[1,0,1]
	v_pk_fma_f32 v[172:173], v[70:71], v[86:87], v[164:165] op_sel_hi:[1,0,1]
	v_pk_fma_f32 v[174:175], v[72:73], v[86:87], v[166:167] op_sel_hi:[1,0,1]
	v_pk_fma_f32 v[176:177], v[74:75], v[86:87], v[168:169] op_sel_hi:[1,0,1]
	ds_write_b32 v201, v93 offset:1792
	v_pk_mul_f32 v[90:91], v[10:11], v[94:95]
	v_pk_fma_f32 v[90:91], v[12:13], v[96:97], v[90:91]
	v_pk_fma_f32 v[90:91], v[14:15], v[98:99], v[90:91]
	v_pk_fma_f32 v[90:91], v[16:17], v[100:101], v[90:91]
	ds_read_b128 v[10:13], v199 offset:15936
	v_add_f32_e32 v92, v90, v91
	ds_read_b128 v[14:17], v199 offset:15952
	s_waitcnt lgkmcnt(5)
; template <int CPL>
; DI void scan_block2(CP p, int layer, int s, int d, int hd, int rowhalf, char* smem) {
;     ...
; #pragma unroll 8
;       for (int jj = 0; jj < nst; ++jj) {
;         float4 na[CPL / 4], ny[CPL / 4], nw[CPL / 4], nb[CPL / 4], nk[CPL / 4];
;         float nvv;
;         {
;           const int jn = jj + 1;
;           const float* o = ob + jn * 392 + cg * CPL;
; #pragma unroll
;           for (int i = 0; i < CPL / 4; ++i) {
;             na[i] = *(const float4*)(o + 4 * i); ny[i] = *(const float4*)(o + 64 + 4 * i); nw[i] = *(const float4*)(o + 128 + 4 * i);
;             nb[i] = *(const float4*)(o + 192 + 4 * i); nk[i] = *(const float4*)(o + 256 + 4 * i);
;           }
;           nvv = ob[jn * 392 + 320 + row];
;         }
;         f2 A[NV], Y[NV], W[NV], B[NV], K[NV];
; #pragma unroll
;         for (int i = 0; i < CPL / 4; ++i) {
;           A[2 * i] = mk2(ca[i].x, ca[i].y); A[2 * i + 1] = mk2(ca[i].z, ca[i].w);
;           Y[2 * i] = mk2(cy[i].x, cy[i].y); Y[2 * i + 1] = mk2(cy[i].z, cy[i].w);
;           W[2 * i] = mk2(cw[i].x, cw[i].y); W[2 * i + 1] = mk2(cw[i].z, cw[i].w);
;           B[2 * i] = mk2(cb[i].x, cb[i].y); B[2 * i + 1] = mk2(cb[i].z, cb[i].w);
;           K[2 * i] = mk2(ck[i].x, ck[i].y); K[2 * i + 1] = mk2(ck[i].z, ck[i].w);
;         }
;         const float vv = cvv;
;         f2 pa0 = S[0] * A[0], pa1 = S[1] * A[1];
; #pragma unroll
;         for (int i = 2; i < NV; i += 2) { pa0 = S[i] * A[i] + pa0; pa1 = S[i + 1] * A[i + 1] + pa1; }
;         pa0 = pa0 + pa1;
;         float da = pa0.x + pa0.y;
;         const f2 vvv = mk2(vv, vv);
;         f2 SW[NV];
; #pragma unroll
;         for (int i = 0; i < NV; ++i) SW[i] = S[i] * W[i] + vvv * K[i];
;         da += __int_as_float(__builtin_amdgcn_update_dpp(0, __float_as_int(da), 0xB1, 0xf, 0xf, false));
;         da += __int_as_float(__builtin_amdgcn_update_dpp(0, __float_as_int(da), 0x4E, 0xf, 0xf, false));
;         if (CPL == 8) da += __int_as_float(__builtin_amdgcn_update_dpp(0, __float_as_int(da), 0x141, 0xf, 0xf, false));
;         const f2 dav = mk2(da, da);
; #pragma unroll
;         for (int i = 0; i < NV; ++i) S[i] = dav * B[i] + SW[i];
;         f2 py0 = S[0] * Y[0], py1 = S[1] * Y[1];
; #pragma unroll
;         for (int i = 2; i < NV; i += 2) { py0 = S[i] * Y[i] + py0; py1 = S[i + 1] * Y[i + 1] + py1; }
;         py0 = py0 + py1;
;         float yv = py0.x + py0.y;
	v_pk_mul_f32 v[88:89], v[2:3], v[170:171]
	ds_read_b128 v[44:47], v199 offset:17248
	v_pk_fma_f32 v[88:89], v[4:5], v[172:173], v[88:89]
	ds_read_b128 v[48:51], v199 offset:17264
	v_pk_fma_f32 v[88:89], v[6:7], v[174:175], v[88:89]
	ds_read_b128 v[76:79], v199 offset:18272
	v_pk_fma_f32 v[88:89], v[8:9], v[176:177], v[88:89]
	ds_read_b128 v[80:83], v199 offset:18288
	v_add_f32_e32 v86, v88, v89
	ds_read_b32 v84, v200 offset:17248
	v_pk_fma_f32 v[162:163], v[34:35], v[42:43], v[170:171] op_sel_hi:[1,0,1]
	v_add_f32_dpp v86, v86, v86 quad_perm:[1,0,3,2] row_mask:0xf bank_mask:0xf bound_ctrl:1
	v_add_f32_dpp v92, v92, v92 quad_perm:[1,0,3,2] row_mask:0xf bank_mask:0xf bound_ctrl:1
	ds_read_b128 v[68:71], v199 offset:18016
	v_add_f32_dpp v86, v86, v86 quad_perm:[2,3,0,1] row_mask:0xf bank_mask:0xf bound_ctrl:1
	v_add_f32_dpp v92, v92, v92 quad_perm:[2,3,0,1] row_mask:0xf bank_mask:0xf bound_ctrl:1
	ds_read_b128 v[72:75], v199 offset:18032
	v_add_f32_dpp v86, v86, v86 row_half_mirror row_mask:0xf bank_mask:0xf bound_ctrl:1
	v_add_f32_dpp v92, v92, v92 row_half_mirror row_mask:0xf bank_mask:0xf bound_ctrl:1
	v_pk_fma_f32 v[164:165], v[36:37], v[42:43], v[172:173] op_sel_hi:[1,0,1]
	v_pk_fma_f32 v[166:167], v[38:39], v[42:43], v[174:175] op_sel_hi:[1,0,1]
	v_pk_fma_f32 v[168:169], v[40:41], v[42:43], v[176:177] op_sel_hi:[1,0,1]
	s_waitcnt lgkmcnt(10)
	v_pk_fma_f32 v[94:95], v[26:27], v[86:87], v[162:163] op_sel_hi:[1,0,1]
	v_pk_fma_f32 v[96:97], v[28:29], v[86:87], v[164:165] op_sel_hi:[1,0,1]
	v_pk_fma_f32 v[98:99], v[30:31], v[86:87], v[166:167] op_sel_hi:[1,0,1]
	v_pk_fma_f32 v[100:101], v[32:33], v[86:87], v[168:169] op_sel_hi:[1,0,1]
	ds_write_b32 v201, v92 offset:2048
	v_pk_mul_f32 v[90:91], v[52:53], v[170:171]
	v_pk_fma_f32 v[90:91], v[54:55], v[172:173], v[90:91]
	v_pk_fma_f32 v[90:91], v[56:57], v[174:175], v[90:91]
	v_pk_fma_f32 v[90:91], v[58:59], v[176:177], v[90:91]
	ds_read_b128 v[52:55], v199 offset:17504
	v_add_f32_e32 v93, v90, v91
	ds_read_b128 v[56:59], v199 offset:17520
	s_waitcnt lgkmcnt(5)
	v_pk_mul_f32 v[88:89], v[44:45], v[94:95]
	ds_read_b128 v[2:5], v199 offset:18816
	v_pk_fma_f32 v[88:89], v[46:47], v[96:97], v[88:89]
	ds_read_b128 v[6:9], v199 offset:18832
	v_pk_fma_f32 v[88:89], v[48:49], v[98:99], v[88:89]
	ds_read_b128 v[34:37], v199 offset:19840
	v_pk_fma_f32 v[88:89], v[50:51], v[100:101], v[88:89]
	ds_read_b128 v[38:41], v199 offset:19856
	v_add_f32_e32 v86, v88, v89
	ds_read_b32 v42, v200 offset:18816
	ds_read_b128 v[18:21], v199 offset:17760
	ds_read_b128 v[22:25], v199 offset:17776
	v_add_f32_dpp v86, v86, v86 quad_perm:[1,0,3,2] row_mask:0xf bank_mask:0xf bound_ctrl:1
	v_add_f32_dpp v93, v93, v93 quad_perm:[1,0,3,2] row_mask:0xf bank_mask:0xf bound_ctrl:1
	ds_read_b128 v[26:29], v199 offset:19584
	v_add_f32_dpp v86, v86, v86 quad_perm:[2,3,0,1] row_mask:0xf bank_mask:0xf bound_ctrl:1
	v_add_f32_dpp v93, v93, v93 quad_perm:[2,3,0,1] row_mask:0xf bank_mask:0xf bound_ctrl:1
	ds_read_b128 v[30:33], v199 offset:19600
	v_add_f32_dpp v86, v86, v86 row_half_mirror row_mask:0xf bank_mask:0xf bound_ctrl:1
	v_add_f32_dpp v93, v93, v93 row_half_mirror row_mask:0xf bank_mask:0xf bound_ctrl:1
	v_pk_fma_f32 v[162:163], v[76:77], v[84:85], v[94:95] op_sel_hi:[1,0,1]
	v_pk_fma_f32 v[164:165], v[78:79], v[84:85], v[96:97] op_sel_hi:[1,0,1]
	v_pk_fma_f32 v[166:167], v[80:81], v[84:85], v[98:99] op_sel_hi:[1,0,1]
	v_pk_fma_f32 v[168:169], v[82:83], v[84:85], v[100:101] op_sel_hi:[1,0,1]
	s_waitcnt lgkmcnt(12)
	v_pk_fma_f32 v[170:171], v[68:69], v[86:87], v[162:163] op_sel_hi:[1,0,1]
	v_pk_fma_f32 v[172:173], v[70:71], v[86:87], v[164:165] op_sel_hi:[1,0,1]
	v_pk_fma_f32 v[174:175], v[72:73], v[86:87], v[166:167] op_sel_hi:[1,0,1]
	v_pk_fma_f32 v[176:177], v[74:75], v[86:87], v[168:169] op_sel_hi:[1,0,1]
	s_waitcnt lgkmcnt(2)
	v_pk_mul_f32 v[170:171], v[170:171], v[18:19]
	v_pk_mul_f32 v[172:173], v[172:173], v[20:21]
	v_pk_mul_f32 v[174:175], v[174:175], v[22:23]
	v_pk_mul_f32 v[176:177], v[176:177], v[24:25]
	ds_write_b32 v201, v93 offset:2304
	v_pk_mul_f32 v[90:91], v[10:11], v[94:95]
	v_pk_fma_f32 v[90:91], v[12:13], v[96:97], v[90:91]
	v_pk_fma_f32 v[90:91], v[14:15], v[98:99], v[90:91]
	v_pk_fma_f32 v[90:91], v[16:17], v[100:101], v[90:91]
	ds_read_b128 v[10:13], v199 offset:19072
	v_add_f32_e32 v92, v90, v91
	ds_read_b128 v[14:17], v199 offset:19088
	s_waitcnt lgkmcnt(7)
	v_pk_mul_f32 v[88:89], v[2:3], v[170:171]
	ds_read_b128 v[44:47], v199 offset:20384
	v_pk_fma_f32 v[88:89], v[4:5], v[172:173], v[88:89]
	ds_read_b128 v[48:51], v199 offset:20400
	v_pk_fma_f32 v[88:89], v[6:7], v[174:175], v[88:89]
	ds_read_b128 v[76:79], v199 offset:21408
	v_pk_fma_f32 v[88:89], v[8:9], v[176:177], v[88:89]
	ds_read_b128 v[80:83], v199 offset:21424
	v_add_f32_e32 v86, v88, v89
	ds_read_b32 v84, v200 offset:20384
	v_pk_fma_f32 v[162:163], v[34:35], v[42:43], v[170:171] op_sel_hi:[1,0,1]
	v_add_f32_dpp v86, v86, v86 quad_perm:[1,0,3,2] row_mask:0xf bank_mask:0xf bound_ctrl:1
	v_add_f32_dpp v92, v92, v92 quad_perm:[1,0,3,2] row_mask:0xf bank_mask:0xf bound_ctrl:1
	ds_read_b128 v[68:71], v199 offset:21152
	v_add_f32_dpp v86, v86, v86 quad_perm:[2,3,0,1] row_mask:0xf bank_mask:0xf bound_ctrl:1
	v_add_f32_dpp v92, v92, v92 quad_perm:[2,3,0,1] row_mask:0xf bank_mask:0xf bound_ctrl:1
	ds_read_b128 v[72:75], v199 offset:21168
	v_add_f32_dpp v86, v86, v86 row_half_mirror row_mask:0xf bank_mask:0xf bound_ctrl:1
	v_add_f32_dpp v92, v92, v92 row_half_mirror row_mask:0xf bank_mask:0xf bound_ctrl:1
	v_pk_fma_f32 v[164:165], v[36:37], v[42:43], v[172:173] op_sel_hi:[1,0,1]
	v_pk_fma_f32 v[166:167], v[38:39], v[42:43], v[174:175] op_sel_hi:[1,0,1]
	v_pk_fma_f32 v[168:169], v[40:41], v[42:43], v[176:177] op_sel_hi:[1,0,1]
	s_waitcnt lgkmcnt(10)
; template <int CPL>
; DI void scan_block2(CP p, int layer, int s, int d, int hd, int rowhalf, char* smem) {
;     ...
; #pragma unroll 8
;       for (int jj = 0; jj < nst; ++jj) {
;         float4 na[CPL / 4], ny[CPL / 4], nw[CPL / 4], nb[CPL / 4], nk[CPL / 4];
;         float nvv;
;         {
;           const int jn = jj + 1;
;           const float* o = ob + jn * 392 + cg * CPL;
; #pragma unroll
;           for (int i = 0; i < CPL / 4; ++i) {
;             na[i] = *(const float4*)(o + 4 * i); ny[i] = *(const float4*)(o + 64 + 4 * i); nw[i] = *(const float4*)(o + 128 + 4 * i);
;             nb[i] = *(const float4*)(o + 192 + 4 * i); nk[i] = *(const float4*)(o + 256 + 4 * i);
;           }
;           nvv = ob[jn * 392 + 320 + row];
;         }
;         f2 A[NV], Y[NV], W[NV], B[NV], K[NV];
; #pragma unroll
;         for (int i = 0; i < CPL / 4; ++i) {
;           A[2 * i] = mk2(ca[i].x, ca[i].y); A[2 * i + 1] = mk2(ca[i].z, ca[i].w);
;           Y[2 * i] = mk2(cy[i].x, cy[i].y); Y[2 * i + 1] = mk2(cy[i].z, cy[i].w);
;           W[2 * i] = mk2(cw[i].x, cw[i].y); W[2 * i + 1] = mk2(cw[i].z, cw[i].w);
;           B[2 * i] = mk2(cb[i].x, cb[i].y); B[2 * i + 1] = mk2(cb[i].z, cb[i].w);
;           K[2 * i] = mk2(ck[i].x, ck[i].y); K[2 * i + 1] = mk2(ck[i].z, ck[i].w);
;         }
;         const float vv = cvv;
;         f2 pa0 = S[0] * A[0], pa1 = S[1] * A[1];
; #pragma unroll
;         for (int i = 2; i < NV; i += 2) { pa0 = S[i] * A[i] + pa0; pa1 = S[i + 1] * A[i + 1] + pa1; }
;         pa0 = pa0 + pa1;
;         float da = pa0.x + pa0.y;
;         const f2 vvv = mk2(vv, vv);
;         f2 SW[NV];
; #pragma unroll
;         for (int i = 0; i < NV; ++i) SW[i] = S[i] * W[i] + vvv * K[i];
;         da += __int_as_float(__builtin_amdgcn_update_dpp(0, __float_as_int(da), 0xB1, 0xf, 0xf, false));
;         da += __int_as_float(__builtin_amdgcn_update_dpp(0, __float_as_int(da), 0x4E, 0xf, 0xf, false));
;         if (CPL == 8) da += __int_as_float(__builtin_amdgcn_update_dpp(0, __float_as_int(da), 0x141, 0xf, 0xf, false));
;         const f2 dav = mk2(da, da);
; #pragma unroll
;         for (int i = 0; i < NV; ++i) S[i] = dav * B[i] + SW[i];
;         f2 py0 = S[0] * Y[0], py1 = S[1] * Y[1];
; #pragma unroll
;         for (int i = 2; i < NV; i += 2) { py0 = S[i] * Y[i] + py0; py1 = S[i + 1] * Y[i + 1] + py1; }
;         py0 = py0 + py1;
;         float yv = py0.x + py0.y;
	v_pk_fma_f32 v[94:95], v[26:27], v[86:87], v[162:163] op_sel_hi:[1,0,1]
	v_pk_fma_f32 v[96:97], v[28:29], v[86:87], v[164:165] op_sel_hi:[1,0,1]
	v_pk_fma_f32 v[98:99], v[30:31], v[86:87], v[166:167] op_sel_hi:[1,0,1]
	v_pk_fma_f32 v[100:101], v[32:33], v[86:87], v[168:169] op_sel_hi:[1,0,1]
	ds_write_b32 v201, v92 offset:2560
	v_pk_mul_f32 v[90:91], v[52:53], v[170:171]
	v_pk_fma_f32 v[90:91], v[54:55], v[172:173], v[90:91]
	v_pk_fma_f32 v[90:91], v[56:57], v[174:175], v[90:91]
	v_pk_fma_f32 v[90:91], v[58:59], v[176:177], v[90:91]
	ds_read_b128 v[52:55], v199 offset:20640
	v_add_f32_e32 v93, v90, v91
	ds_read_b128 v[56:59], v199 offset:20656
	s_waitcnt lgkmcnt(5)
	v_pk_mul_f32 v[88:89], v[44:45], v[94:95]
	ds_read_b128 v[2:5], v199 offset:21952
	v_pk_fma_f32 v[88:89], v[46:47], v[96:97], v[88:89]
	ds_read_b128 v[6:9], v199 offset:21968
	v_pk_fma_f32 v[88:89], v[48:49], v[98:99], v[88:89]
	ds_read_b128 v[34:37], v199 offset:22976
	v_pk_fma_f32 v[88:89], v[50:51], v[100:101], v[88:89]
	ds_read_b128 v[38:41], v199 offset:22992
	v_add_f32_e32 v86, v88, v89
	ds_read_b32 v42, v200 offset:21952
	v_pk_fma_f32 v[162:163], v[76:77], v[84:85], v[94:95] op_sel_hi:[1,0,1]
	v_add_f32_dpp v86, v86, v86 quad_perm:[1,0,3,2] row_mask:0xf bank_mask:0xf bound_ctrl:1
	v_add_f32_dpp v93, v93, v93 quad_perm:[1,0,3,2] row_mask:0xf bank_mask:0xf bound_ctrl:1
	ds_read_b128 v[26:29], v199 offset:22720
	v_add_f32_dpp v86, v86, v86 quad_perm:[2,3,0,1] row_mask:0xf bank_mask:0xf bound_ctrl:1
	v_add_f32_dpp v93, v93, v93 quad_perm:[2,3,0,1] row_mask:0xf bank_mask:0xf bound_ctrl:1
	ds_read_b128 v[30:33], v199 offset:22736
	v_add_f32_dpp v86, v86, v86 row_half_mirror row_mask:0xf bank_mask:0xf bound_ctrl:1
	v_add_f32_dpp v93, v93, v93 row_half_mirror row_mask:0xf bank_mask:0xf bound_ctrl:1
	v_pk_fma_f32 v[164:165], v[78:79], v[84:85], v[96:97] op_sel_hi:[1,0,1]
	v_pk_fma_f32 v[166:167], v[80:81], v[84:85], v[98:99] op_sel_hi:[1,0,1]
	v_pk_fma_f32 v[168:169], v[82:83], v[84:85], v[100:101] op_sel_hi:[1,0,1]
	s_waitcnt lgkmcnt(10)
	v_pk_fma_f32 v[170:171], v[68:69], v[86:87], v[162:163] op_sel_hi:[1,0,1]
	v_pk_fma_f32 v[172:173], v[70:71], v[86:87], v[164:165] op_sel_hi:[1,0,1]
	v_pk_fma_f32 v[174:175], v[72:73], v[86:87], v[166:167] op_sel_hi:[1,0,1]
	v_pk_fma_f32 v[176:177], v[74:75], v[86:87], v[168:169] op_sel_hi:[1,0,1]
	ds_write_b32 v201, v93 offset:2816
	v_pk_mul_f32 v[90:91], v[10:11], v[94:95]
	v_pk_fma_f32 v[90:91], v[12:13], v[96:97], v[90:91]
	v_pk_fma_f32 v[90:91], v[14:15], v[98:99], v[90:91]
	v_pk_fma_f32 v[90:91], v[16:17], v[100:101], v[90:91]
	ds_read_b128 v[10:13], v199 offset:22208
	v_add_f32_e32 v92, v90, v91
	ds_read_b128 v[14:17], v199 offset:22224
	s_waitcnt lgkmcnt(5)
	v_pk_mul_f32 v[88:89], v[2:3], v[170:171]
	ds_read_b128 v[44:47], v199 offset:23520
	v_pk_fma_f32 v[88:89], v[4:5], v[172:173], v[88:89]
	ds_read_b128 v[48:51], v199 offset:23536
	v_pk_fma_f32 v[88:89], v[6:7], v[174:175], v[88:89]
	ds_read_b128 v[76:79], v199 offset:24544
	v_pk_fma_f32 v[88:89], v[8:9], v[176:177], v[88:89]
	ds_read_b128 v[80:83], v199 offset:24560
	v_add_f32_e32 v86, v88, v89
	ds_read_b32 v84, v200 offset:23520
	v_pk_fma_f32 v[162:163], v[34:35], v[42:43], v[170:171] op_sel_hi:[1,0,1]
	v_add_f32_dpp v86, v86, v86 quad_perm:[1,0,3,2] row_mask:0xf bank_mask:0xf bound_ctrl:1
	v_add_f32_dpp v92, v92, v92 quad_perm:[1,0,3,2] row_mask:0xf bank_mask:0xf bound_ctrl:1
	ds_read_b128 v[68:71], v199 offset:24288
	v_add_f32_dpp v86, v86, v86 quad_perm:[2,3,0,1] row_mask:0xf bank_mask:0xf bound_ctrl:1
	v_add_f32_dpp v92, v92, v92 quad_perm:[2,3,0,1] row_mask:0xf bank_mask:0xf bound_ctrl:1
	ds_read_b128 v[72:75], v199 offset:24304
	v_add_f32_dpp v86, v86, v86 row_half_mirror row_mask:0xf bank_mask:0xf bound_ctrl:1
	v_add_f32_dpp v92, v92, v92 row_half_mirror row_mask:0xf bank_mask:0xf bound_ctrl:1
	v_pk_fma_f32 v[164:165], v[36:37], v[42:43], v[172:173] op_sel_hi:[1,0,1]
	v_pk_fma_f32 v[166:167], v[38:39], v[42:43], v[174:175] op_sel_hi:[1,0,1]
	v_pk_fma_f32 v[168:169], v[40:41], v[42:43], v[176:177] op_sel_hi:[1,0,1]
	s_waitcnt lgkmcnt(10)
	v_pk_fma_f32 v[94:95], v[26:27], v[86:87], v[162:163] op_sel_hi:[1,0,1]
	v_pk_fma_f32 v[96:97], v[28:29], v[86:87], v[164:165] op_sel_hi:[1,0,1]
	v_pk_fma_f32 v[98:99], v[30:31], v[86:87], v[166:167] op_sel_hi:[1,0,1]
	v_pk_fma_f32 v[100:101], v[32:33], v[86:87], v[168:169] op_sel_hi:[1,0,1]
	ds_write_b32 v201, v92 offset:3072
	v_pk_mul_f32 v[90:91], v[52:53], v[170:171]
	v_pk_fma_f32 v[90:91], v[54:55], v[172:173], v[90:91]
	v_pk_fma_f32 v[90:91], v[56:57], v[174:175], v[90:91]
	v_pk_fma_f32 v[90:91], v[58:59], v[176:177], v[90:91]
	ds_read_b128 v[52:55], v199 offset:23776
	v_add_f32_e32 v93, v90, v91
	ds_read_b128 v[56:59], v199 offset:23792
	s_waitcnt lgkmcnt(5)
	v_pk_mul_f32 v[88:89], v[44:45], v[94:95]
	ds_read_b128 v[2:5], v199 offset:25088
	v_pk_fma_f32 v[88:89], v[46:47], v[96:97], v[88:89]
	ds_read_b128 v[6:9], v199 offset:25104
	v_pk_fma_f32 v[88:89], v[48:49], v[98:99], v[88:89]
	ds_read_b128 v[34:37], v199 offset:26112
	v_pk_fma_f32 v[88:89], v[50:51], v[100:101], v[88:89]
	ds_read_b128 v[38:41], v199 offset:26128
	v_add_f32_e32 v86, v88, v89
	ds_read_b32 v42, v200 offset:25088
	ds_read_b128 v[18:21], v199 offset:24032
	ds_read_b128 v[22:25], v199 offset:24048
	v_add_f32_dpp v86, v86, v86 quad_perm:[1,0,3,2] row_mask:0xf bank_mask:0xf bound_ctrl:1
	v_add_f32_dpp v93, v93, v93 quad_perm:[1,0,3,2] row_mask:0xf bank_mask:0xf bound_ctrl:1
	ds_read_b128 v[26:29], v199 offset:25856
	v_add_f32_dpp v86, v86, v86 quad_perm:[2,3,0,1] row_mask:0xf bank_mask:0xf bound_ctrl:1
	v_add_f32_dpp v93, v93, v93 quad_perm:[2,3,0,1] row_mask:0xf bank_mask:0xf bound_ctrl:1
	ds_read_b128 v[30:33], v199 offset:25872
	v_add_f32_dpp v86, v86, v86 row_half_mirror row_mask:0xf bank_mask:0xf bound_ctrl:1
	v_add_f32_dpp v93, v93, v93 row_half_mirror row_mask:0xf bank_mask:0xf bound_ctrl:1
	v_pk_fma_f32 v[162:163], v[76:77], v[84:85], v[94:95] op_sel_hi:[1,0,1]
	v_pk_fma_f32 v[164:165], v[78:79], v[84:85], v[96:97] op_sel_hi:[1,0,1]
	v_pk_fma_f32 v[166:167], v[80:81], v[84:85], v[98:99] op_sel_hi:[1,0,1]
	v_pk_fma_f32 v[168:169], v[82:83], v[84:85], v[100:101] op_sel_hi:[1,0,1]
	s_waitcnt lgkmcnt(12)
; template <int CPL>
; DI void scan_block2(CP p, int layer, int s, int d, int hd, int rowhalf, char* smem) {
;     ...
; #pragma unroll 8
;       for (int jj = 0; jj < nst; ++jj) {
;         float4 na[CPL / 4], ny[CPL / 4], nw[CPL / 4], nb[CPL / 4], nk[CPL / 4];
;         float nvv;
;         {
;           const int jn = jj + 1;
;           const float* o = ob + jn * 392 + cg * CPL;
; #pragma unroll
;           for (int i = 0; i < CPL / 4; ++i) {
;             na[i] = *(const float4*)(o + 4 * i); ny[i] = *(const float4*)(o + 64 + 4 * i); nw[i] = *(const float4*)(o + 128 + 4 * i);
;             nb[i] = *(const float4*)(o + 192 + 4 * i); nk[i] = *(const float4*)(o + 256 + 4 * i);
;           }
;           nvv = ob[jn * 392 + 320 + row];
;         }
;         f2 A[NV], Y[NV], W[NV], B[NV], K[NV];
; #pragma unroll
;         for (int i = 0; i < CPL / 4; ++i) {
;           A[2 * i] = mk2(ca[i].x, ca[i].y); A[2 * i + 1] = mk2(ca[i].z, ca[i].w);
;           Y[2 * i] = mk2(cy[i].x, cy[i].y); Y[2 * i + 1] = mk2(cy[i].z, cy[i].w);
;           W[2 * i] = mk2(cw[i].x, cw[i].y); W[2 * i + 1] = mk2(cw[i].z, cw[i].w);
;           B[2 * i] = mk2(cb[i].x, cb[i].y); B[2 * i + 1] = mk2(cb[i].z, cb[i].w);
;           K[2 * i] = mk2(ck[i].x, ck[i].y); K[2 * i + 1] = mk2(ck[i].z, ck[i].w);
;         }
;         const float vv = cvv;
;         f2 pa0 = S[0] * A[0], pa1 = S[1] * A[1];
; #pragma unroll
;         for (int i = 2; i < NV; i += 2) { pa0 = S[i] * A[i] + pa0; pa1 = S[i + 1] * A[i + 1] + pa1; }
;         pa0 = pa0 + pa1;
;         float da = pa0.x + pa0.y;
;         const f2 vvv = mk2(vv, vv);
;         f2 SW[NV];
; #pragma unroll
;         for (int i = 0; i < NV; ++i) SW[i] = S[i] * W[i] + vvv * K[i];
;         da += __int_as_float(__builtin_amdgcn_update_dpp(0, __float_as_int(da), 0xB1, 0xf, 0xf, false));
;         da += __int_as_float(__builtin_amdgcn_update_dpp(0, __float_as_int(da), 0x4E, 0xf, 0xf, false));
;         if (CPL == 8) da += __int_as_float(__builtin_amdgcn_update_dpp(0, __float_as_int(da), 0x141, 0xf, 0xf, false));
;         const f2 dav = mk2(da, da);
; #pragma unroll
;         for (int i = 0; i < NV; ++i) S[i] = dav * B[i] + SW[i];
;         f2 py0 = S[0] * Y[0], py1 = S[1] * Y[1];
; #pragma unroll
;         for (int i = 2; i < NV; i += 2) { py0 = S[i] * Y[i] + py0; py1 = S[i + 1] * Y[i + 1] + py1; }
;         py0 = py0 + py1;
;         float yv = py0.x + py0.y;
	v_pk_fma_f32 v[170:171], v[68:69], v[86:87], v[162:163] op_sel_hi:[1,0,1]
	v_pk_fma_f32 v[172:173], v[70:71], v[86:87], v[164:165] op_sel_hi:[1,0,1]
	v_pk_fma_f32 v[174:175], v[72:73], v[86:87], v[166:167] op_sel_hi:[1,0,1]
	v_pk_fma_f32 v[176:177], v[74:75], v[86:87], v[168:169] op_sel_hi:[1,0,1]
	s_waitcnt lgkmcnt(2)
	v_pk_mul_f32 v[170:171], v[170:171], v[18:19]
	v_pk_mul_f32 v[172:173], v[172:173], v[20:21]
	v_pk_mul_f32 v[174:175], v[174:175], v[22:23]
	v_pk_mul_f32 v[176:177], v[176:177], v[24:25]
	ds_write_b32 v201, v93 offset:3328
	v_pk_mul_f32 v[90:91], v[10:11], v[94:95]
	v_pk_fma_f32 v[90:91], v[12:13], v[96:97], v[90:91]
	v_pk_fma_f32 v[90:91], v[14:15], v[98:99], v[90:91]
	v_pk_fma_f32 v[90:91], v[16:17], v[100:101], v[90:91]
	ds_read_b128 v[10:13], v199 offset:25344
	v_add_f32_e32 v92, v90, v91
	ds_read_b128 v[14:17], v199 offset:25360
	s_cmp_eq_u32 s10, 0x100
	s_cbranch_scc1 .Lsc8_drain16
	s_waitcnt lgkmcnt(7)
	v_pk_mul_f32 v[88:89], v[2:3], v[170:171]
	ds_read_b128 v[44:47], v199 offset:26656
	v_pk_fma_f32 v[88:89], v[4:5], v[172:173], v[88:89]
	ds_read_b128 v[48:51], v199 offset:26672
	v_pk_fma_f32 v[88:89], v[6:7], v[174:175], v[88:89]
	ds_read_b128 v[76:79], v199 offset:27680
	v_pk_fma_f32 v[88:89], v[8:9], v[176:177], v[88:89]
	ds_read_b128 v[80:83], v199 offset:27696
	v_add_f32_e32 v86, v88, v89
	ds_read_b32 v84, v200 offset:26656
	v_pk_fma_f32 v[162:163], v[34:35], v[42:43], v[170:171] op_sel_hi:[1,0,1]
	v_add_f32_dpp v86, v86, v86 quad_perm:[1,0,3,2] row_mask:0xf bank_mask:0xf bound_ctrl:1
	v_add_f32_dpp v92, v92, v92 quad_perm:[1,0,3,2] row_mask:0xf bank_mask:0xf bound_ctrl:1
	ds_read_b128 v[68:71], v199 offset:27424
	v_add_f32_dpp v86, v86, v86 quad_perm:[2,3,0,1] row_mask:0xf bank_mask:0xf bound_ctrl:1
	v_add_f32_dpp v92, v92, v92 quad_perm:[2,3,0,1] row_mask:0xf bank_mask:0xf bound_ctrl:1
	ds_read_b128 v[72:75], v199 offset:27440
	v_add_f32_dpp v86, v86, v86 row_half_mirror row_mask:0xf bank_mask:0xf bound_ctrl:1
	v_add_f32_dpp v92, v92, v92 row_half_mirror row_mask:0xf bank_mask:0xf bound_ctrl:1
	v_pk_fma_f32 v[164:165], v[36:37], v[42:43], v[172:173] op_sel_hi:[1,0,1]
	v_pk_fma_f32 v[166:167], v[38:39], v[42:43], v[174:175] op_sel_hi:[1,0,1]
	v_pk_fma_f32 v[168:169], v[40:41], v[42:43], v[176:177] op_sel_hi:[1,0,1]
	s_waitcnt lgkmcnt(10)
	v_pk_fma_f32 v[94:95], v[26:27], v[86:87], v[162:163] op_sel_hi:[1,0,1]
	v_pk_fma_f32 v[96:97], v[28:29], v[86:87], v[164:165] op_sel_hi:[1,0,1]
	v_pk_fma_f32 v[98:99], v[30:31], v[86:87], v[166:167] op_sel_hi:[1,0,1]
	v_pk_fma_f32 v[100:101], v[32:33], v[86:87], v[168:169] op_sel_hi:[1,0,1]
	ds_write_b32 v201, v92 offset:3584
	v_pk_mul_f32 v[90:91], v[52:53], v[170:171]
	v_pk_fma_f32 v[90:91], v[54:55], v[172:173], v[90:91]
	v_pk_fma_f32 v[90:91], v[56:57], v[174:175], v[90:91]
	v_pk_fma_f32 v[90:91], v[58:59], v[176:177], v[90:91]
	ds_read_b128 v[52:55], v199 offset:26912
	v_add_f32_e32 v93, v90, v91
	ds_read_b128 v[56:59], v199 offset:26928
	s_waitcnt lgkmcnt(5)
	v_pk_mul_f32 v[88:89], v[44:45], v[94:95]
	ds_read_b128 v[2:5], v199 offset:28224
	v_pk_fma_f32 v[88:89], v[46:47], v[96:97], v[88:89]
	ds_read_b128 v[6:9], v199 offset:28240
	v_pk_fma_f32 v[88:89], v[48:49], v[98:99], v[88:89]
	ds_read_b128 v[34:37], v199 offset:29248
	v_pk_fma_f32 v[88:89], v[50:51], v[100:101], v[88:89]
	ds_read_b128 v[38:41], v199 offset:29264
	v_add_f32_e32 v86, v88, v89
	ds_read_b32 v42, v200 offset:28224
	v_pk_fma_f32 v[162:163], v[76:77], v[84:85], v[94:95] op_sel_hi:[1,0,1]
	v_add_f32_dpp v86, v86, v86 quad_perm:[1,0,3,2] row_mask:0xf bank_mask:0xf bound_ctrl:1
	v_add_f32_dpp v93, v93, v93 quad_perm:[1,0,3,2] row_mask:0xf bank_mask:0xf bound_ctrl:1
	ds_read_b128 v[26:29], v199 offset:28992
	v_add_f32_dpp v86, v86, v86 quad_perm:[2,3,0,1] row_mask:0xf bank_mask:0xf bound_ctrl:1
	v_add_f32_dpp v93, v93, v93 quad_perm:[2,3,0,1] row_mask:0xf bank_mask:0xf bound_ctrl:1
	ds_read_b128 v[30:33], v199 offset:29008
	v_add_f32_dpp v86, v86, v86 row_half_mirror row_mask:0xf bank_mask:0xf bound_ctrl:1
	v_add_f32_dpp v93, v93, v93 row_half_mirror row_mask:0xf bank_mask:0xf bound_ctrl:1
	v_pk_fma_f32 v[164:165], v[78:79], v[84:85], v[96:97] op_sel_hi:[1,0,1]
	v_pk_fma_f32 v[166:167], v[80:81], v[84:85], v[98:99] op_sel_hi:[1,0,1]
	v_pk_fma_f32 v[168:169], v[82:83], v[84:85], v[100:101] op_sel_hi:[1,0,1]
	s_waitcnt lgkmcnt(10)
	v_pk_fma_f32 v[170:171], v[68:69], v[86:87], v[162:163] op_sel_hi:[1,0,1]
	v_pk_fma_f32 v[172:173], v[70:71], v[86:87], v[164:165] op_sel_hi:[1,0,1]
	v_pk_fma_f32 v[174:175], v[72:73], v[86:87], v[166:167] op_sel_hi:[1,0,1]
	v_pk_fma_f32 v[176:177], v[74:75], v[86:87], v[168:169] op_sel_hi:[1,0,1]
	ds_write_b32 v201, v93 offset:3840
	v_pk_mul_f32 v[90:91], v[10:11], v[94:95]
	v_pk_fma_f32 v[90:91], v[12:13], v[96:97], v[90:91]
	v_pk_fma_f32 v[90:91], v[14:15], v[98:99], v[90:91]
	v_pk_fma_f32 v[90:91], v[16:17], v[100:101], v[90:91]
	ds_read_b128 v[10:13], v199 offset:28480
	v_add_f32_e32 v92, v90, v91
	ds_read_b128 v[14:17], v199 offset:28496
	s_waitcnt lgkmcnt(5)
; template <int CPL>
; DI void scan_block2(CP p, int layer, int s, int d, int hd, int rowhalf, char* smem) {
;     ...
; #pragma unroll 8
;       for (int jj = 0; jj < nst; ++jj) {
;         float4 na[CPL / 4], ny[CPL / 4], nw[CPL / 4], nb[CPL / 4], nk[CPL / 4];
;         float nvv;
;         {
;           const int jn = jj + 1;
;           const float* o = ob + jn * 392 + cg * CPL;
; #pragma unroll
;           for (int i = 0; i < CPL / 4; ++i) {
;             na[i] = *(const float4*)(o + 4 * i); ny[i] = *(const float4*)(o + 64 + 4 * i); nw[i] = *(const float4*)(o + 128 + 4 * i);
;             nb[i] = *(const float4*)(o + 192 + 4 * i); nk[i] = *(const float4*)(o + 256 + 4 * i);
;           }
;           nvv = ob[jn * 392 + 320 + row];
;         }
;         f2 A[NV], Y[NV], W[NV], B[NV], K[NV];
; #pragma unroll
;         for (int i = 0; i < CPL / 4; ++i) {
;           A[2 * i] = mk2(ca[i].x, ca[i].y); A[2 * i + 1] = mk2(ca[i].z, ca[i].w);
;           Y[2 * i] = mk2(cy[i].x, cy[i].y); Y[2 * i + 1] = mk2(cy[i].z, cy[i].w);
;           W[2 * i] = mk2(cw[i].x, cw[i].y); W[2 * i + 1] = mk2(cw[i].z, cw[i].w);
;           B[2 * i] = mk2(cb[i].x, cb[i].y); B[2 * i + 1] = mk2(cb[i].z, cb[i].w);
;           K[2 * i] = mk2(ck[i].x, ck[i].y); K[2 * i + 1] = mk2(ck[i].z, ck[i].w);
;         }
;         const float vv = cvv;
;         f2 pa0 = S[0] * A[0], pa1 = S[1] * A[1];
; #pragma unroll
;         for (int i = 2; i < NV; i += 2) { pa0 = S[i] * A[i] + pa0; pa1 = S[i + 1] * A[i + 1] + pa1; }
;         pa0 = pa0 + pa1;
;         float da = pa0.x + pa0.y;
;         const f2 vvv = mk2(vv, vv);
;         f2 SW[NV];
; #pragma unroll
;         for (int i = 0; i < NV; ++i) SW[i] = S[i] * W[i] + vvv * K[i];
;         da += __int_as_float(__builtin_amdgcn_update_dpp(0, __float_as_int(da), 0xB1, 0xf, 0xf, false));
;         da += __int_as_float(__builtin_amdgcn_update_dpp(0, __float_as_int(da), 0x4E, 0xf, 0xf, false));
;         if (CPL == 8) da += __int_as_float(__builtin_amdgcn_update_dpp(0, __float_as_int(da), 0x141, 0xf, 0xf, false));
;         const f2 dav = mk2(da, da);
; #pragma unroll
;         for (int i = 0; i < NV; ++i) S[i] = dav * B[i] + SW[i];
;         f2 py0 = S[0] * Y[0], py1 = S[1] * Y[1];
; #pragma unroll
;         for (int i = 2; i < NV; i += 2) { py0 = S[i] * Y[i] + py0; py1 = S[i + 1] * Y[i + 1] + py1; }
;         py0 = py0 + py1;
;         float yv = py0.x + py0.y;
	v_pk_mul_f32 v[88:89], v[2:3], v[170:171]
	ds_read_b128 v[44:47], v199 offset:29792
	v_pk_fma_f32 v[88:89], v[4:5], v[172:173], v[88:89]
	ds_read_b128 v[48:51], v199 offset:29808
	v_pk_fma_f32 v[88:89], v[6:7], v[174:175], v[88:89]
	ds_read_b128 v[76:79], v199 offset:30816
	v_pk_fma_f32 v[88:89], v[8:9], v[176:177], v[88:89]
	ds_read_b128 v[80:83], v199 offset:30832
	v_add_f32_e32 v86, v88, v89
	ds_read_b32 v84, v200 offset:29792
	v_pk_fma_f32 v[162:163], v[34:35], v[42:43], v[170:171] op_sel_hi:[1,0,1]
	v_add_f32_dpp v86, v86, v86 quad_perm:[1,0,3,2] row_mask:0xf bank_mask:0xf bound_ctrl:1
	v_add_f32_dpp v92, v92, v92 quad_perm:[1,0,3,2] row_mask:0xf bank_mask:0xf bound_ctrl:1
	ds_read_b128 v[68:71], v199 offset:30560
	v_add_f32_dpp v86, v86, v86 quad_perm:[2,3,0,1] row_mask:0xf bank_mask:0xf bound_ctrl:1
	v_add_f32_dpp v92, v92, v92 quad_perm:[2,3,0,1] row_mask:0xf bank_mask:0xf bound_ctrl:1
	ds_read_b128 v[72:75], v199 offset:30576
	v_add_f32_dpp v86, v86, v86 row_half_mirror row_mask:0xf bank_mask:0xf bound_ctrl:1
	v_add_f32_dpp v92, v92, v92 row_half_mirror row_mask:0xf bank_mask:0xf bound_ctrl:1
	v_pk_fma_f32 v[164:165], v[36:37], v[42:43], v[172:173] op_sel_hi:[1,0,1]
	v_pk_fma_f32 v[166:167], v[38:39], v[42:43], v[174:175] op_sel_hi:[1,0,1]
	v_pk_fma_f32 v[168:169], v[40:41], v[42:43], v[176:177] op_sel_hi:[1,0,1]
	s_waitcnt lgkmcnt(10)
	v_pk_fma_f32 v[94:95], v[26:27], v[86:87], v[162:163] op_sel_hi:[1,0,1]
	v_pk_fma_f32 v[96:97], v[28:29], v[86:87], v[164:165] op_sel_hi:[1,0,1]
	v_pk_fma_f32 v[98:99], v[30:31], v[86:87], v[166:167] op_sel_hi:[1,0,1]
	v_pk_fma_f32 v[100:101], v[32:33], v[86:87], v[168:169] op_sel_hi:[1,0,1]
	ds_write_b32 v201, v92 offset:4096
	v_pk_mul_f32 v[90:91], v[52:53], v[170:171]
	v_pk_fma_f32 v[90:91], v[54:55], v[172:173], v[90:91]
	v_pk_fma_f32 v[90:91], v[56:57], v[174:175], v[90:91]
	v_pk_fma_f32 v[90:91], v[58:59], v[176:177], v[90:91]
	ds_read_b128 v[52:55], v199 offset:30048
	v_add_f32_e32 v93, v90, v91
	ds_read_b128 v[56:59], v199 offset:30064
	s_waitcnt lgkmcnt(5)
	v_pk_mul_f32 v[88:89], v[44:45], v[94:95]
	ds_read_b128 v[2:5], v199 offset:31360
	v_pk_fma_f32 v[88:89], v[46:47], v[96:97], v[88:89]
	ds_read_b128 v[6:9], v199 offset:31376
	v_pk_fma_f32 v[88:89], v[48:49], v[98:99], v[88:89]
	ds_read_b128 v[34:37], v199 offset:32384
	v_pk_fma_f32 v[88:89], v[50:51], v[100:101], v[88:89]
	ds_read_b128 v[38:41], v199 offset:32400
	v_add_f32_e32 v86, v88, v89
	ds_read_b32 v42, v200 offset:31360
	ds_read_b128 v[18:21], v199 offset:30304
	ds_read_b128 v[22:25], v199 offset:30320
	v_add_f32_dpp v86, v86, v86 quad_perm:[1,0,3,2] row_mask:0xf bank_mask:0xf bound_ctrl:1
	v_add_f32_dpp v93, v93, v93 quad_perm:[1,0,3,2] row_mask:0xf bank_mask:0xf bound_ctrl:1
	ds_read_b128 v[26:29], v199 offset:32128
	v_add_f32_dpp v86, v86, v86 quad_perm:[2,3,0,1] row_mask:0xf bank_mask:0xf bound_ctrl:1
	v_add_f32_dpp v93, v93, v93 quad_perm:[2,3,0,1] row_mask:0xf bank_mask:0xf bound_ctrl:1
	ds_read_b128 v[30:33], v199 offset:32144
	v_add_f32_dpp v86, v86, v86 row_half_mirror row_mask:0xf bank_mask:0xf bound_ctrl:1
	v_add_f32_dpp v93, v93, v93 row_half_mirror row_mask:0xf bank_mask:0xf bound_ctrl:1
	v_pk_fma_f32 v[162:163], v[76:77], v[84:85], v[94:95] op_sel_hi:[1,0,1]
	v_pk_fma_f32 v[164:165], v[78:79], v[84:85], v[96:97] op_sel_hi:[1,0,1]
	v_pk_fma_f32 v[166:167], v[80:81], v[84:85], v[98:99] op_sel_hi:[1,0,1]
	v_pk_fma_f32 v[168:169], v[82:83], v[84:85], v[100:101] op_sel_hi:[1,0,1]
	s_waitcnt lgkmcnt(12)
	v_pk_fma_f32 v[170:171], v[68:69], v[86:87], v[162:163] op_sel_hi:[1,0,1]
	v_pk_fma_f32 v[172:173], v[70:71], v[86:87], v[164:165] op_sel_hi:[1,0,1]
	v_pk_fma_f32 v[174:175], v[72:73], v[86:87], v[166:167] op_sel_hi:[1,0,1]
	v_pk_fma_f32 v[176:177], v[74:75], v[86:87], v[168:169] op_sel_hi:[1,0,1]
	s_waitcnt lgkmcnt(2)
	v_pk_mul_f32 v[170:171], v[170:171], v[18:19]
	v_pk_mul_f32 v[172:173], v[172:173], v[20:21]
	v_pk_mul_f32 v[174:175], v[174:175], v[22:23]
	v_pk_mul_f32 v[176:177], v[176:177], v[24:25]
	ds_write_b32 v201, v93 offset:4352
	v_pk_mul_f32 v[90:91], v[10:11], v[94:95]
	v_pk_fma_f32 v[90:91], v[12:13], v[96:97], v[90:91]
	v_pk_fma_f32 v[90:91], v[14:15], v[98:99], v[90:91]
	v_pk_fma_f32 v[90:91], v[16:17], v[100:101], v[90:91]
	ds_read_b128 v[10:13], v199 offset:31616
	v_add_f32_e32 v92, v90, v91
	ds_read_b128 v[14:17], v199 offset:31632
	s_waitcnt lgkmcnt(7)
	v_pk_mul_f32 v[88:89], v[2:3], v[170:171]
	ds_read_b128 v[44:47], v199 offset:32928
	v_pk_fma_f32 v[88:89], v[4:5], v[172:173], v[88:89]
	ds_read_b128 v[48:51], v199 offset:32944
	v_pk_fma_f32 v[88:89], v[6:7], v[174:175], v[88:89]
	ds_read_b128 v[76:79], v199 offset:33952
	v_pk_fma_f32 v[88:89], v[8:9], v[176:177], v[88:89]
	ds_read_b128 v[80:83], v199 offset:33968
	v_add_f32_e32 v86, v88, v89
	ds_read_b32 v84, v200 offset:32928
	v_pk_fma_f32 v[162:163], v[34:35], v[42:43], v[170:171] op_sel_hi:[1,0,1]
	v_add_f32_dpp v86, v86, v86 quad_perm:[1,0,3,2] row_mask:0xf bank_mask:0xf bound_ctrl:1
	v_add_f32_dpp v92, v92, v92 quad_perm:[1,0,3,2] row_mask:0xf bank_mask:0xf bound_ctrl:1
	ds_read_b128 v[68:71], v199 offset:33696
	v_add_f32_dpp v86, v86, v86 quad_perm:[2,3,0,1] row_mask:0xf bank_mask:0xf bound_ctrl:1
	v_add_f32_dpp v92, v92, v92 quad_perm:[2,3,0,1] row_mask:0xf bank_mask:0xf bound_ctrl:1
	ds_read_b128 v[72:75], v199 offset:33712
	v_add_f32_dpp v86, v86, v86 row_half_mirror row_mask:0xf bank_mask:0xf bound_ctrl:1
	v_add_f32_dpp v92, v92, v92 row_half_mirror row_mask:0xf bank_mask:0xf bound_ctrl:1
	v_pk_fma_f32 v[164:165], v[36:37], v[42:43], v[172:173] op_sel_hi:[1,0,1]
	v_pk_fma_f32 v[166:167], v[38:39], v[42:43], v[174:175] op_sel_hi:[1,0,1]
	v_pk_fma_f32 v[168:169], v[40:41], v[42:43], v[176:177] op_sel_hi:[1,0,1]
	s_waitcnt lgkmcnt(10)
; template <int CPL>
; DI void scan_block2(CP p, int layer, int s, int d, int hd, int rowhalf, char* smem) {
;     ...
; #pragma unroll 8
;       for (int jj = 0; jj < nst; ++jj) {
;         float4 na[CPL / 4], ny[CPL / 4], nw[CPL / 4], nb[CPL / 4], nk[CPL / 4];
;         float nvv;
;         {
;           const int jn = jj + 1;
;           const float* o = ob + jn * 392 + cg * CPL;
; #pragma unroll
;           for (int i = 0; i < CPL / 4; ++i) {
;             na[i] = *(const float4*)(o + 4 * i); ny[i] = *(const float4*)(o + 64 + 4 * i); nw[i] = *(const float4*)(o + 128 + 4 * i);
;             nb[i] = *(const float4*)(o + 192 + 4 * i); nk[i] = *(const float4*)(o + 256 + 4 * i);
;           }
;           nvv = ob[jn * 392 + 320 + row];
;         }
;         f2 A[NV], Y[NV], W[NV], B[NV], K[NV];
; #pragma unroll
;         for (int i = 0; i < CPL / 4; ++i) {
;           A[2 * i] = mk2(ca[i].x, ca[i].y); A[2 * i + 1] = mk2(ca[i].z, ca[i].w);
;           Y[2 * i] = mk2(cy[i].x, cy[i].y); Y[2 * i + 1] = mk2(cy[i].z, cy[i].w);
;           W[2 * i] = mk2(cw[i].x, cw[i].y); W[2 * i + 1] = mk2(cw[i].z, cw[i].w);
;           B[2 * i] = mk2(cb[i].x, cb[i].y); B[2 * i + 1] = mk2(cb[i].z, cb[i].w);
;           K[2 * i] = mk2(ck[i].x, ck[i].y); K[2 * i + 1] = mk2(ck[i].z, ck[i].w);
;         }
;         const float vv = cvv;
;         f2 pa0 = S[0] * A[0], pa1 = S[1] * A[1];
; #pragma unroll
;         for (int i = 2; i < NV; i += 2) { pa0 = S[i] * A[i] + pa0; pa1 = S[i + 1] * A[i + 1] + pa1; }
;         pa0 = pa0 + pa1;
;         float da = pa0.x + pa0.y;
;         const f2 vvv = mk2(vv, vv);
;         f2 SW[NV];
; #pragma unroll
;         for (int i = 0; i < NV; ++i) SW[i] = S[i] * W[i] + vvv * K[i];
;         da += __int_as_float(__builtin_amdgcn_update_dpp(0, __float_as_int(da), 0xB1, 0xf, 0xf, false));
;         da += __int_as_float(__builtin_amdgcn_update_dpp(0, __float_as_int(da), 0x4E, 0xf, 0xf, false));
;         if (CPL == 8) da += __int_as_float(__builtin_amdgcn_update_dpp(0, __float_as_int(da), 0x141, 0xf, 0xf, false));
;         const f2 dav = mk2(da, da);
; #pragma unroll
;         for (int i = 0; i < NV; ++i) S[i] = dav * B[i] + SW[i];
;         f2 py0 = S[0] * Y[0], py1 = S[1] * Y[1];
; #pragma unroll
;         for (int i = 2; i < NV; i += 2) { py0 = S[i] * Y[i] + py0; py1 = S[i + 1] * Y[i + 1] + py1; }
;         py0 = py0 + py1;
;         float yv = py0.x + py0.y;
	v_pk_fma_f32 v[94:95], v[26:27], v[86:87], v[162:163] op_sel_hi:[1,0,1]
	v_pk_fma_f32 v[96:97], v[28:29], v[86:87], v[164:165] op_sel_hi:[1,0,1]
	v_pk_fma_f32 v[98:99], v[30:31], v[86:87], v[166:167] op_sel_hi:[1,0,1]
	v_pk_fma_f32 v[100:101], v[32:33], v[86:87], v[168:169] op_sel_hi:[1,0,1]
	ds_write_b32 v201, v92 offset:4608
	v_pk_mul_f32 v[90:91], v[52:53], v[170:171]
	v_pk_fma_f32 v[90:91], v[54:55], v[172:173], v[90:91]
	v_pk_fma_f32 v[90:91], v[56:57], v[174:175], v[90:91]
	v_pk_fma_f32 v[90:91], v[58:59], v[176:177], v[90:91]
	ds_read_b128 v[52:55], v199 offset:33184
	v_add_f32_e32 v93, v90, v91
	ds_read_b128 v[56:59], v199 offset:33200
	s_waitcnt lgkmcnt(5)
	v_pk_mul_f32 v[88:89], v[44:45], v[94:95]
	ds_read_b128 v[2:5], v199 offset:34496
	v_pk_fma_f32 v[88:89], v[46:47], v[96:97], v[88:89]
	ds_read_b128 v[6:9], v199 offset:34512
	v_pk_fma_f32 v[88:89], v[48:49], v[98:99], v[88:89]
	ds_read_b128 v[34:37], v199 offset:35520
	v_pk_fma_f32 v[88:89], v[50:51], v[100:101], v[88:89]
	ds_read_b128 v[38:41], v199 offset:35536
	v_add_f32_e32 v86, v88, v89
	ds_read_b32 v42, v200 offset:34496
	v_pk_fma_f32 v[162:163], v[76:77], v[84:85], v[94:95] op_sel_hi:[1,0,1]
	v_add_f32_dpp v86, v86, v86 quad_perm:[1,0,3,2] row_mask:0xf bank_mask:0xf bound_ctrl:1
	v_add_f32_dpp v93, v93, v93 quad_perm:[1,0,3,2] row_mask:0xf bank_mask:0xf bound_ctrl:1
	ds_read_b128 v[26:29], v199 offset:35264
	v_add_f32_dpp v86, v86, v86 quad_perm:[2,3,0,1] row_mask:0xf bank_mask:0xf bound_ctrl:1
	v_add_f32_dpp v93, v93, v93 quad_perm:[2,3,0,1] row_mask:0xf bank_mask:0xf bound_ctrl:1
	ds_read_b128 v[30:33], v199 offset:35280
	v_add_f32_dpp v86, v86, v86 row_half_mirror row_mask:0xf bank_mask:0xf bound_ctrl:1
	v_add_f32_dpp v93, v93, v93 row_half_mirror row_mask:0xf bank_mask:0xf bound_ctrl:1
	v_pk_fma_f32 v[164:165], v[78:79], v[84:85], v[96:97] op_sel_hi:[1,0,1]
	v_pk_fma_f32 v[166:167], v[80:81], v[84:85], v[98:99] op_sel_hi:[1,0,1]
	v_pk_fma_f32 v[168:169], v[82:83], v[84:85], v[100:101] op_sel_hi:[1,0,1]
	s_waitcnt lgkmcnt(10)
	v_pk_fma_f32 v[170:171], v[68:69], v[86:87], v[162:163] op_sel_hi:[1,0,1]
	v_pk_fma_f32 v[172:173], v[70:71], v[86:87], v[164:165] op_sel_hi:[1,0,1]
	v_pk_fma_f32 v[174:175], v[72:73], v[86:87], v[166:167] op_sel_hi:[1,0,1]
	v_pk_fma_f32 v[176:177], v[74:75], v[86:87], v[168:169] op_sel_hi:[1,0,1]
	ds_write_b32 v201, v93 offset:4864
	v_pk_mul_f32 v[90:91], v[10:11], v[94:95]
	v_pk_fma_f32 v[90:91], v[12:13], v[96:97], v[90:91]
	v_pk_fma_f32 v[90:91], v[14:15], v[98:99], v[90:91]
	v_pk_fma_f32 v[90:91], v[16:17], v[100:101], v[90:91]
	ds_read_b128 v[10:13], v199 offset:34752
	v_add_f32_e32 v92, v90, v91
	ds_read_b128 v[14:17], v199 offset:34768
	s_waitcnt lgkmcnt(5)
	v_pk_mul_f32 v[88:89], v[2:3], v[170:171]
	ds_read_b128 v[44:47], v199 offset:36064
	v_pk_fma_f32 v[88:89], v[4:5], v[172:173], v[88:89]
	ds_read_b128 v[48:51], v199 offset:36080
	v_pk_fma_f32 v[88:89], v[6:7], v[174:175], v[88:89]
	ds_read_b128 v[76:79], v199 offset:37088
	v_pk_fma_f32 v[88:89], v[8:9], v[176:177], v[88:89]
	ds_read_b128 v[80:83], v199 offset:37104
	v_add_f32_e32 v86, v88, v89
	ds_read_b32 v84, v200 offset:36064
	v_pk_fma_f32 v[162:163], v[34:35], v[42:43], v[170:171] op_sel_hi:[1,0,1]
	v_add_f32_dpp v86, v86, v86 quad_perm:[1,0,3,2] row_mask:0xf bank_mask:0xf bound_ctrl:1
	v_add_f32_dpp v92, v92, v92 quad_perm:[1,0,3,2] row_mask:0xf bank_mask:0xf bound_ctrl:1
	ds_read_b128 v[68:71], v199 offset:36832
	v_add_f32_dpp v86, v86, v86 quad_perm:[2,3,0,1] row_mask:0xf bank_mask:0xf bound_ctrl:1
	v_add_f32_dpp v92, v92, v92 quad_perm:[2,3,0,1] row_mask:0xf bank_mask:0xf bound_ctrl:1
	ds_read_b128 v[72:75], v199 offset:36848
	v_add_f32_dpp v86, v86, v86 row_half_mirror row_mask:0xf bank_mask:0xf bound_ctrl:1
	v_add_f32_dpp v92, v92, v92 row_half_mirror row_mask:0xf bank_mask:0xf bound_ctrl:1
	v_pk_fma_f32 v[164:165], v[36:37], v[42:43], v[172:173] op_sel_hi:[1,0,1]
	v_pk_fma_f32 v[166:167], v[38:39], v[42:43], v[174:175] op_sel_hi:[1,0,1]
	v_pk_fma_f32 v[168:169], v[40:41], v[42:43], v[176:177] op_sel_hi:[1,0,1]
	s_waitcnt lgkmcnt(10)
	v_pk_fma_f32 v[94:95], v[26:27], v[86:87], v[162:163] op_sel_hi:[1,0,1]
	v_pk_fma_f32 v[96:97], v[28:29], v[86:87], v[164:165] op_sel_hi:[1,0,1]
	v_pk_fma_f32 v[98:99], v[30:31], v[86:87], v[166:167] op_sel_hi:[1,0,1]
	v_pk_fma_f32 v[100:101], v[32:33], v[86:87], v[168:169] op_sel_hi:[1,0,1]
	ds_write_b32 v201, v92 offset:5120
	v_pk_mul_f32 v[90:91], v[52:53], v[170:171]
	v_pk_fma_f32 v[90:91], v[54:55], v[172:173], v[90:91]
	v_pk_fma_f32 v[90:91], v[56:57], v[174:175], v[90:91]
	v_pk_fma_f32 v[90:91], v[58:59], v[176:177], v[90:91]
	ds_read_b128 v[52:55], v199 offset:36320
	v_add_f32_e32 v93, v90, v91
	ds_read_b128 v[56:59], v199 offset:36336
	s_waitcnt lgkmcnt(5)
	v_pk_mul_f32 v[88:89], v[44:45], v[94:95]
	ds_read_b128 v[2:5], v199 offset:37632
	v_pk_fma_f32 v[88:89], v[46:47], v[96:97], v[88:89]
	ds_read_b128 v[6:9], v199 offset:37648
	v_pk_fma_f32 v[88:89], v[48:49], v[98:99], v[88:89]
	ds_read_b128 v[34:37], v199 offset:38656
	v_pk_fma_f32 v[88:89], v[50:51], v[100:101], v[88:89]
	ds_read_b128 v[38:41], v199 offset:38672
	v_add_f32_e32 v86, v88, v89
	ds_read_b32 v42, v200 offset:37632
	ds_read_b128 v[18:21], v199 offset:36576
	ds_read_b128 v[22:25], v199 offset:36592
	v_add_f32_dpp v86, v86, v86 quad_perm:[1,0,3,2] row_mask:0xf bank_mask:0xf bound_ctrl:1
	v_add_f32_dpp v93, v93, v93 quad_perm:[1,0,3,2] row_mask:0xf bank_mask:0xf bound_ctrl:1
	ds_read_b128 v[26:29], v199 offset:38400
	v_add_f32_dpp v86, v86, v86 quad_perm:[2,3,0,1] row_mask:0xf bank_mask:0xf bound_ctrl:1
	v_add_f32_dpp v93, v93, v93 quad_perm:[2,3,0,1] row_mask:0xf bank_mask:0xf bound_ctrl:1
	ds_read_b128 v[30:33], v199 offset:38416
	v_add_f32_dpp v86, v86, v86 row_half_mirror row_mask:0xf bank_mask:0xf bound_ctrl:1
	v_add_f32_dpp v93, v93, v93 row_half_mirror row_mask:0xf bank_mask:0xf bound_ctrl:1
	v_pk_fma_f32 v[162:163], v[76:77], v[84:85], v[94:95] op_sel_hi:[1,0,1]
	v_pk_fma_f32 v[164:165], v[78:79], v[84:85], v[96:97] op_sel_hi:[1,0,1]
	v_pk_fma_f32 v[166:167], v[80:81], v[84:85], v[98:99] op_sel_hi:[1,0,1]
	v_pk_fma_f32 v[168:169], v[82:83], v[84:85], v[100:101] op_sel_hi:[1,0,1]
	s_waitcnt lgkmcnt(12)
; template <int CPL>
; DI void scan_block2(CP p, int layer, int s, int d, int hd, int rowhalf, char* smem) {
;     ...
; #pragma unroll 8
;       for (int jj = 0; jj < nst; ++jj) {
;         float4 na[CPL / 4], ny[CPL / 4], nw[CPL / 4], nb[CPL / 4], nk[CPL / 4];
;         float nvv;
;         {
;           const int jn = jj + 1;
;           const float* o = ob + jn * 392 + cg * CPL;
; #pragma unroll
;           for (int i = 0; i < CPL / 4; ++i) {
;             na[i] = *(const float4*)(o + 4 * i); ny[i] = *(const float4*)(o + 64 + 4 * i); nw[i] = *(const float4*)(o + 128 + 4 * i);
;             nb[i] = *(const float4*)(o + 192 + 4 * i); nk[i] = *(const float4*)(o + 256 + 4 * i);
;           }
;           nvv = ob[jn * 392 + 320 + row];
;         }
;         f2 A[NV], Y[NV], W[NV], B[NV], K[NV];
; #pragma unroll
;         for (int i = 0; i < CPL / 4; ++i) {
;           A[2 * i] = mk2(ca[i].x, ca[i].y); A[2 * i + 1] = mk2(ca[i].z, ca[i].w);
;           Y[2 * i] = mk2(cy[i].x, cy[i].y); Y[2 * i + 1] = mk2(cy[i].z, cy[i].w);
;           W[2 * i] = mk2(cw[i].x, cw[i].y); W[2 * i + 1] = mk2(cw[i].z, cw[i].w);
;           B[2 * i] = mk2(cb[i].x, cb[i].y); B[2 * i + 1] = mk2(cb[i].z, cb[i].w);
;           K[2 * i] = mk2(ck[i].x, ck[i].y); K[2 * i + 1] = mk2(ck[i].z, ck[i].w);
;         }
;         const float vv = cvv;
;         f2 pa0 = S[0] * A[0], pa1 = S[1] * A[1];
; #pragma unroll
;         for (int i = 2; i < NV; i += 2) { pa0 = S[i] * A[i] + pa0; pa1 = S[i + 1] * A[i + 1] + pa1; }
;         pa0 = pa0 + pa1;
;         float da = pa0.x + pa0.y;
;         const f2 vvv = mk2(vv, vv);
;         f2 SW[NV];
; #pragma unroll
;         for (int i = 0; i < NV; ++i) SW[i] = S[i] * W[i] + vvv * K[i];
;         da += __int_as_float(__builtin_amdgcn_update_dpp(0, __float_as_int(da), 0xB1, 0xf, 0xf, false));
;         da += __int_as_float(__builtin_amdgcn_update_dpp(0, __float_as_int(da), 0x4E, 0xf, 0xf, false));
;         if (CPL == 8) da += __int_as_float(__builtin_amdgcn_update_dpp(0, __float_as_int(da), 0x141, 0xf, 0xf, false));
;         const f2 dav = mk2(da, da);
; #pragma unroll
;         for (int i = 0; i < NV; ++i) S[i] = dav * B[i] + SW[i];
;         f2 py0 = S[0] * Y[0], py1 = S[1] * Y[1];
; #pragma unroll
;         for (int i = 2; i < NV; i += 2) { py0 = S[i] * Y[i] + py0; py1 = S[i + 1] * Y[i + 1] + py1; }
;         py0 = py0 + py1;
;         float yv = py0.x + py0.y;
	v_pk_fma_f32 v[170:171], v[68:69], v[86:87], v[162:163] op_sel_hi:[1,0,1]
	v_pk_fma_f32 v[172:173], v[70:71], v[86:87], v[164:165] op_sel_hi:[1,0,1]
	v_pk_fma_f32 v[174:175], v[72:73], v[86:87], v[166:167] op_sel_hi:[1,0,1]
	v_pk_fma_f32 v[176:177], v[74:75], v[86:87], v[168:169] op_sel_hi:[1,0,1]
	s_waitcnt lgkmcnt(2)
	v_pk_mul_f32 v[170:171], v[170:171], v[18:19]
	v_pk_mul_f32 v[172:173], v[172:173], v[20:21]
	v_pk_mul_f32 v[174:175], v[174:175], v[22:23]
	v_pk_mul_f32 v[176:177], v[176:177], v[24:25]
	ds_write_b32 v201, v93 offset:5376
	v_pk_mul_f32 v[90:91], v[10:11], v[94:95]
	v_pk_fma_f32 v[90:91], v[12:13], v[96:97], v[90:91]
	v_pk_fma_f32 v[90:91], v[14:15], v[98:99], v[90:91]
	v_pk_fma_f32 v[90:91], v[16:17], v[100:101], v[90:91]
	ds_read_b128 v[10:13], v199 offset:37888
	v_add_f32_e32 v92, v90, v91
	ds_read_b128 v[14:17], v199 offset:37904
	s_waitcnt lgkmcnt(7)
	v_pk_mul_f32 v[88:89], v[2:3], v[170:171]
	ds_read_b128 v[44:47], v199 offset:39200
	v_pk_fma_f32 v[88:89], v[4:5], v[172:173], v[88:89]
	ds_read_b128 v[48:51], v199 offset:39216
	v_pk_fma_f32 v[88:89], v[6:7], v[174:175], v[88:89]
	ds_read_b128 v[76:79], v199 offset:40224
	v_pk_fma_f32 v[88:89], v[8:9], v[176:177], v[88:89]
	ds_read_b128 v[80:83], v199 offset:40240
	v_add_f32_e32 v86, v88, v89
	ds_read_b32 v84, v200 offset:39200
	v_pk_fma_f32 v[162:163], v[34:35], v[42:43], v[170:171] op_sel_hi:[1,0,1]
	v_add_f32_dpp v86, v86, v86 quad_perm:[1,0,3,2] row_mask:0xf bank_mask:0xf bound_ctrl:1
	v_add_f32_dpp v92, v92, v92 quad_perm:[1,0,3,2] row_mask:0xf bank_mask:0xf bound_ctrl:1
	ds_read_b128 v[68:71], v199 offset:39968
	v_add_f32_dpp v86, v86, v86 quad_perm:[2,3,0,1] row_mask:0xf bank_mask:0xf bound_ctrl:1
	v_add_f32_dpp v92, v92, v92 quad_perm:[2,3,0,1] row_mask:0xf bank_mask:0xf bound_ctrl:1
	ds_read_b128 v[72:75], v199 offset:39984
	v_add_f32_dpp v86, v86, v86 row_half_mirror row_mask:0xf bank_mask:0xf bound_ctrl:1
	v_add_f32_dpp v92, v92, v92 row_half_mirror row_mask:0xf bank_mask:0xf bound_ctrl:1
	v_pk_fma_f32 v[164:165], v[36:37], v[42:43], v[172:173] op_sel_hi:[1,0,1]
	v_pk_fma_f32 v[166:167], v[38:39], v[42:43], v[174:175] op_sel_hi:[1,0,1]
	v_pk_fma_f32 v[168:169], v[40:41], v[42:43], v[176:177] op_sel_hi:[1,0,1]
	s_waitcnt lgkmcnt(10)
	v_pk_fma_f32 v[94:95], v[26:27], v[86:87], v[162:163] op_sel_hi:[1,0,1]
	v_pk_fma_f32 v[96:97], v[28:29], v[86:87], v[164:165] op_sel_hi:[1,0,1]
	v_pk_fma_f32 v[98:99], v[30:31], v[86:87], v[166:167] op_sel_hi:[1,0,1]
	v_pk_fma_f32 v[100:101], v[32:33], v[86:87], v[168:169] op_sel_hi:[1,0,1]
	ds_write_b32 v201, v92 offset:5632
	v_pk_mul_f32 v[90:91], v[52:53], v[170:171]
	v_pk_fma_f32 v[90:91], v[54:55], v[172:173], v[90:91]
	v_pk_fma_f32 v[90:91], v[56:57], v[174:175], v[90:91]
	v_pk_fma_f32 v[90:91], v[58:59], v[176:177], v[90:91]
	ds_read_b128 v[52:55], v199 offset:39456
	v_add_f32_e32 v93, v90, v91
	ds_read_b128 v[56:59], v199 offset:39472
	s_waitcnt lgkmcnt(5)
	v_pk_mul_f32 v[88:89], v[44:45], v[94:95]
	ds_read_b128 v[2:5], v199 offset:40768
	v_pk_fma_f32 v[88:89], v[46:47], v[96:97], v[88:89]
	ds_read_b128 v[6:9], v199 offset:40784
	v_pk_fma_f32 v[88:89], v[48:49], v[98:99], v[88:89]
	ds_read_b128 v[34:37], v199 offset:41792
	v_pk_fma_f32 v[88:89], v[50:51], v[100:101], v[88:89]
	ds_read_b128 v[38:41], v199 offset:41808
	v_add_f32_e32 v86, v88, v89
	ds_read_b32 v42, v200 offset:40768
	v_pk_fma_f32 v[162:163], v[76:77], v[84:85], v[94:95] op_sel_hi:[1,0,1]
	v_add_f32_dpp v86, v86, v86 quad_perm:[1,0,3,2] row_mask:0xf bank_mask:0xf bound_ctrl:1
	v_add_f32_dpp v93, v93, v93 quad_perm:[1,0,3,2] row_mask:0xf bank_mask:0xf bound_ctrl:1
	ds_read_b128 v[26:29], v199 offset:41536
	v_add_f32_dpp v86, v86, v86 quad_perm:[2,3,0,1] row_mask:0xf bank_mask:0xf bound_ctrl:1
	v_add_f32_dpp v93, v93, v93 quad_perm:[2,3,0,1] row_mask:0xf bank_mask:0xf bound_ctrl:1
	ds_read_b128 v[30:33], v199 offset:41552
	v_add_f32_dpp v86, v86, v86 row_half_mirror row_mask:0xf bank_mask:0xf bound_ctrl:1
	v_add_f32_dpp v93, v93, v93 row_half_mirror row_mask:0xf bank_mask:0xf bound_ctrl:1
	v_pk_fma_f32 v[164:165], v[78:79], v[84:85], v[96:97] op_sel_hi:[1,0,1]
	v_pk_fma_f32 v[166:167], v[80:81], v[84:85], v[98:99] op_sel_hi:[1,0,1]
	v_pk_fma_f32 v[168:169], v[82:83], v[84:85], v[100:101] op_sel_hi:[1,0,1]
	s_waitcnt lgkmcnt(10)
	v_pk_fma_f32 v[170:171], v[68:69], v[86:87], v[162:163] op_sel_hi:[1,0,1]
	v_pk_fma_f32 v[172:173], v[70:71], v[86:87], v[164:165] op_sel_hi:[1,0,1]
	v_pk_fma_f32 v[174:175], v[72:73], v[86:87], v[166:167] op_sel_hi:[1,0,1]
	v_pk_fma_f32 v[176:177], v[74:75], v[86:87], v[168:169] op_sel_hi:[1,0,1]
	ds_write_b32 v201, v93 offset:5888
	v_pk_mul_f32 v[90:91], v[10:11], v[94:95]
	v_pk_fma_f32 v[90:91], v[12:13], v[96:97], v[90:91]
	v_pk_fma_f32 v[90:91], v[14:15], v[98:99], v[90:91]
	v_pk_fma_f32 v[90:91], v[16:17], v[100:101], v[90:91]
	ds_read_b128 v[10:13], v199 offset:41024
	v_add_f32_e32 v92, v90, v91
	ds_read_b128 v[14:17], v199 offset:41040
	s_waitcnt lgkmcnt(5)
; template <int CPL>
; DI void scan_block2(CP p, int layer, int s, int d, int hd, int rowhalf, char* smem) {
;     ...
; #pragma unroll 8
;       for (int jj = 0; jj < nst; ++jj) {
;         float4 na[CPL / 4], ny[CPL / 4], nw[CPL / 4], nb[CPL / 4], nk[CPL / 4];
;         float nvv;
;         {
;           const int jn = jj + 1;
;           const float* o = ob + jn * 392 + cg * CPL;
; #pragma unroll
;           for (int i = 0; i < CPL / 4; ++i) {
;             na[i] = *(const float4*)(o + 4 * i); ny[i] = *(const float4*)(o + 64 + 4 * i); nw[i] = *(const float4*)(o + 128 + 4 * i);
;             nb[i] = *(const float4*)(o + 192 + 4 * i); nk[i] = *(const float4*)(o + 256 + 4 * i);
;           }
;           nvv = ob[jn * 392 + 320 + row];
;         }
;         f2 A[NV], Y[NV], W[NV], B[NV], K[NV];
; #pragma unroll
;         for (int i = 0; i < CPL / 4; ++i) {
;           A[2 * i] = mk2(ca[i].x, ca[i].y); A[2 * i + 1] = mk2(ca[i].z, ca[i].w);
;           Y[2 * i] = mk2(cy[i].x, cy[i].y); Y[2 * i + 1] = mk2(cy[i].z, cy[i].w);
;           W[2 * i] = mk2(cw[i].x, cw[i].y); W[2 * i + 1] = mk2(cw[i].z, cw[i].w);
;           B[2 * i] = mk2(cb[i].x, cb[i].y); B[2 * i + 1] = mk2(cb[i].z, cb[i].w);
;           K[2 * i] = mk2(ck[i].x, ck[i].y); K[2 * i + 1] = mk2(ck[i].z, ck[i].w);
;         }
;         const float vv = cvv;
;         f2 pa0 = S[0] * A[0], pa1 = S[1] * A[1];
; #pragma unroll
;         for (int i = 2; i < NV; i += 2) { pa0 = S[i] * A[i] + pa0; pa1 = S[i + 1] * A[i + 1] + pa1; }
;         pa0 = pa0 + pa1;
;         float da = pa0.x + pa0.y;
;         const f2 vvv = mk2(vv, vv);
;         f2 SW[NV];
; #pragma unroll
;         for (int i = 0; i < NV; ++i) SW[i] = S[i] * W[i] + vvv * K[i];
;         da += __int_as_float(__builtin_amdgcn_update_dpp(0, __float_as_int(da), 0xB1, 0xf, 0xf, false));
;         da += __int_as_float(__builtin_amdgcn_update_dpp(0, __float_as_int(da), 0x4E, 0xf, 0xf, false));
;         if (CPL == 8) da += __int_as_float(__builtin_amdgcn_update_dpp(0, __float_as_int(da), 0x141, 0xf, 0xf, false));
;         const f2 dav = mk2(da, da);
; #pragma unroll
;         for (int i = 0; i < NV; ++i) S[i] = dav * B[i] + SW[i];
;         f2 py0 = S[0] * Y[0], py1 = S[1] * Y[1];
; #pragma unroll
;         for (int i = 2; i < NV; i += 2) { py0 = S[i] * Y[i] + py0; py1 = S[i + 1] * Y[i + 1] + py1; }
;         py0 = py0 + py1;
;         float yv = py0.x + py0.y;
	v_pk_mul_f32 v[88:89], v[2:3], v[170:171]
	ds_read_b128 v[44:47], v199 offset:42336
	v_pk_fma_f32 v[88:89], v[4:5], v[172:173], v[88:89]
	ds_read_b128 v[48:51], v199 offset:42352
	v_pk_fma_f32 v[88:89], v[6:7], v[174:175], v[88:89]
	ds_read_b128 v[76:79], v199 offset:43360
	v_pk_fma_f32 v[88:89], v[8:9], v[176:177], v[88:89]
	ds_read_b128 v[80:83], v199 offset:43376
	v_add_f32_e32 v86, v88, v89
	ds_read_b32 v84, v200 offset:42336
	v_pk_fma_f32 v[162:163], v[34:35], v[42:43], v[170:171] op_sel_hi:[1,0,1]
	v_add_f32_dpp v86, v86, v86 quad_perm:[1,0,3,2] row_mask:0xf bank_mask:0xf bound_ctrl:1
	v_add_f32_dpp v92, v92, v92 quad_perm:[1,0,3,2] row_mask:0xf bank_mask:0xf bound_ctrl:1
	ds_read_b128 v[68:71], v199 offset:43104
	v_add_f32_dpp v86, v86, v86 quad_perm:[2,3,0,1] row_mask:0xf bank_mask:0xf bound_ctrl:1
	v_add_f32_dpp v92, v92, v92 quad_perm:[2,3,0,1] row_mask:0xf bank_mask:0xf bound_ctrl:1
	ds_read_b128 v[72:75], v199 offset:43120
	v_add_f32_dpp v86, v86, v86 row_half_mirror row_mask:0xf bank_mask:0xf bound_ctrl:1
	v_add_f32_dpp v92, v92, v92 row_half_mirror row_mask:0xf bank_mask:0xf bound_ctrl:1
	v_pk_fma_f32 v[164:165], v[36:37], v[42:43], v[172:173] op_sel_hi:[1,0,1]
	v_pk_fma_f32 v[166:167], v[38:39], v[42:43], v[174:175] op_sel_hi:[1,0,1]
	v_pk_fma_f32 v[168:169], v[40:41], v[42:43], v[176:177] op_sel_hi:[1,0,1]
	s_waitcnt lgkmcnt(10)
	v_pk_fma_f32 v[94:95], v[26:27], v[86:87], v[162:163] op_sel_hi:[1,0,1]
	v_pk_fma_f32 v[96:97], v[28:29], v[86:87], v[164:165] op_sel_hi:[1,0,1]
	v_pk_fma_f32 v[98:99], v[30:31], v[86:87], v[166:167] op_sel_hi:[1,0,1]
	v_pk_fma_f32 v[100:101], v[32:33], v[86:87], v[168:169] op_sel_hi:[1,0,1]
	ds_write_b32 v201, v92 offset:6144
	v_pk_mul_f32 v[90:91], v[52:53], v[170:171]
	v_pk_fma_f32 v[90:91], v[54:55], v[172:173], v[90:91]
	v_pk_fma_f32 v[90:91], v[56:57], v[174:175], v[90:91]
	v_pk_fma_f32 v[90:91], v[58:59], v[176:177], v[90:91]
	ds_read_b128 v[52:55], v199 offset:42592
	v_add_f32_e32 v93, v90, v91
	ds_read_b128 v[56:59], v199 offset:42608
	s_waitcnt lgkmcnt(5)
	v_pk_mul_f32 v[88:89], v[44:45], v[94:95]
	ds_read_b128 v[2:5], v199 offset:43904
	v_pk_fma_f32 v[88:89], v[46:47], v[96:97], v[88:89]
	ds_read_b128 v[6:9], v199 offset:43920
	v_pk_fma_f32 v[88:89], v[48:49], v[98:99], v[88:89]
	ds_read_b128 v[34:37], v199 offset:44928
	v_pk_fma_f32 v[88:89], v[50:51], v[100:101], v[88:89]
	ds_read_b128 v[38:41], v199 offset:44944
	v_add_f32_e32 v86, v88, v89
	ds_read_b32 v42, v200 offset:43904
	ds_read_b128 v[18:21], v199 offset:42848
	ds_read_b128 v[22:25], v199 offset:42864
	v_add_f32_dpp v86, v86, v86 quad_perm:[1,0,3,2] row_mask:0xf bank_mask:0xf bound_ctrl:1
	v_add_f32_dpp v93, v93, v93 quad_perm:[1,0,3,2] row_mask:0xf bank_mask:0xf bound_ctrl:1
	ds_read_b128 v[26:29], v199 offset:44672
	v_add_f32_dpp v86, v86, v86 quad_perm:[2,3,0,1] row_mask:0xf bank_mask:0xf bound_ctrl:1
	v_add_f32_dpp v93, v93, v93 quad_perm:[2,3,0,1] row_mask:0xf bank_mask:0xf bound_ctrl:1
	ds_read_b128 v[30:33], v199 offset:44688
	v_add_f32_dpp v86, v86, v86 row_half_mirror row_mask:0xf bank_mask:0xf bound_ctrl:1
	v_add_f32_dpp v93, v93, v93 row_half_mirror row_mask:0xf bank_mask:0xf bound_ctrl:1
	v_pk_fma_f32 v[162:163], v[76:77], v[84:85], v[94:95] op_sel_hi:[1,0,1]
	v_pk_fma_f32 v[164:165], v[78:79], v[84:85], v[96:97] op_sel_hi:[1,0,1]
	v_pk_fma_f32 v[166:167], v[80:81], v[84:85], v[98:99] op_sel_hi:[1,0,1]
	v_pk_fma_f32 v[168:169], v[82:83], v[84:85], v[100:101] op_sel_hi:[1,0,1]
	s_waitcnt lgkmcnt(12)
	v_pk_fma_f32 v[170:171], v[68:69], v[86:87], v[162:163] op_sel_hi:[1,0,1]
	v_pk_fma_f32 v[172:173], v[70:71], v[86:87], v[164:165] op_sel_hi:[1,0,1]
	v_pk_fma_f32 v[174:175], v[72:73], v[86:87], v[166:167] op_sel_hi:[1,0,1]
	v_pk_fma_f32 v[176:177], v[74:75], v[86:87], v[168:169] op_sel_hi:[1,0,1]
	s_waitcnt lgkmcnt(2)
	v_pk_mul_f32 v[170:171], v[170:171], v[18:19]
	v_pk_mul_f32 v[172:173], v[172:173], v[20:21]
	v_pk_mul_f32 v[174:175], v[174:175], v[22:23]
	v_pk_mul_f32 v[176:177], v[176:177], v[24:25]
	ds_write_b32 v201, v93 offset:6400
	v_pk_mul_f32 v[90:91], v[10:11], v[94:95]
	v_pk_fma_f32 v[90:91], v[12:13], v[96:97], v[90:91]
	v_pk_fma_f32 v[90:91], v[14:15], v[98:99], v[90:91]
	v_pk_fma_f32 v[90:91], v[16:17], v[100:101], v[90:91]
	ds_read_b128 v[10:13], v199 offset:44160
	v_add_f32_e32 v92, v90, v91
	ds_read_b128 v[14:17], v199 offset:44176
	s_waitcnt lgkmcnt(7)
	v_pk_mul_f32 v[88:89], v[2:3], v[170:171]
	ds_read_b128 v[44:47], v199 offset:45472
	v_pk_fma_f32 v[88:89], v[4:5], v[172:173], v[88:89]
	ds_read_b128 v[48:51], v199 offset:45488
	v_pk_fma_f32 v[88:89], v[6:7], v[174:175], v[88:89]
	ds_read_b128 v[76:79], v199 offset:46496
	v_pk_fma_f32 v[88:89], v[8:9], v[176:177], v[88:89]
	ds_read_b128 v[80:83], v199 offset:46512
	v_add_f32_e32 v86, v88, v89
	ds_read_b32 v84, v200 offset:45472
	v_pk_fma_f32 v[162:163], v[34:35], v[42:43], v[170:171] op_sel_hi:[1,0,1]
	v_add_f32_dpp v86, v86, v86 quad_perm:[1,0,3,2] row_mask:0xf bank_mask:0xf bound_ctrl:1
	v_add_f32_dpp v92, v92, v92 quad_perm:[1,0,3,2] row_mask:0xf bank_mask:0xf bound_ctrl:1
	ds_read_b128 v[68:71], v199 offset:46240
	v_add_f32_dpp v86, v86, v86 quad_perm:[2,3,0,1] row_mask:0xf bank_mask:0xf bound_ctrl:1
	v_add_f32_dpp v92, v92, v92 quad_perm:[2,3,0,1] row_mask:0xf bank_mask:0xf bound_ctrl:1
	ds_read_b128 v[72:75], v199 offset:46256
	v_add_f32_dpp v86, v86, v86 row_half_mirror row_mask:0xf bank_mask:0xf bound_ctrl:1
	v_add_f32_dpp v92, v92, v92 row_half_mirror row_mask:0xf bank_mask:0xf bound_ctrl:1
	v_pk_fma_f32 v[164:165], v[36:37], v[42:43], v[172:173] op_sel_hi:[1,0,1]
	v_pk_fma_f32 v[166:167], v[38:39], v[42:43], v[174:175] op_sel_hi:[1,0,1]
	v_pk_fma_f32 v[168:169], v[40:41], v[42:43], v[176:177] op_sel_hi:[1,0,1]
	s_waitcnt lgkmcnt(10)
; template <int CPL>
; DI void scan_block2(CP p, int layer, int s, int d, int hd, int rowhalf, char* smem) {
;     ...
; #pragma unroll 8
;       for (int jj = 0; jj < nst; ++jj) {
;         float4 na[CPL / 4], ny[CPL / 4], nw[CPL / 4], nb[CPL / 4], nk[CPL / 4];
;         float nvv;
;         {
;           const int jn = jj + 1;
;           const float* o = ob + jn * 392 + cg * CPL;
; #pragma unroll
;           for (int i = 0; i < CPL / 4; ++i) {
;             na[i] = *(const float4*)(o + 4 * i); ny[i] = *(const float4*)(o + 64 + 4 * i); nw[i] = *(const float4*)(o + 128 + 4 * i);
;             nb[i] = *(const float4*)(o + 192 + 4 * i); nk[i] = *(const float4*)(o + 256 + 4 * i);
;           }
;           nvv = ob[jn * 392 + 320 + row];
;         }
;         f2 A[NV], Y[NV], W[NV], B[NV], K[NV];
; #pragma unroll
;         for (int i = 0; i < CPL / 4; ++i) {
;           A[2 * i] = mk2(ca[i].x, ca[i].y); A[2 * i + 1] = mk2(ca[i].z, ca[i].w);
;           Y[2 * i] = mk2(cy[i].x, cy[i].y); Y[2 * i + 1] = mk2(cy[i].z, cy[i].w);
;           W[2 * i] = mk2(cw[i].x, cw[i].y); W[2 * i + 1] = mk2(cw[i].z, cw[i].w);
;           B[2 * i] = mk2(cb[i].x, cb[i].y); B[2 * i + 1] = mk2(cb[i].z, cb[i].w);
;           K[2 * i] = mk2(ck[i].x, ck[i].y); K[2 * i + 1] = mk2(ck[i].z, ck[i].w);
;         }
;         const float vv = cvv;
;         f2 pa0 = S[0] * A[0], pa1 = S[1] * A[1];
; #pragma unroll
;         for (int i = 2; i < NV; i += 2) { pa0 = S[i] * A[i] + pa0; pa1 = S[i + 1] * A[i + 1] + pa1; }
;         pa0 = pa0 + pa1;
;         float da = pa0.x + pa0.y;
;         const f2 vvv = mk2(vv, vv);
;         f2 SW[NV];
; #pragma unroll
;         for (int i = 0; i < NV; ++i) SW[i] = S[i] * W[i] + vvv * K[i];
;         da += __int_as_float(__builtin_amdgcn_update_dpp(0, __float_as_int(da), 0xB1, 0xf, 0xf, false));
;         da += __int_as_float(__builtin_amdgcn_update_dpp(0, __float_as_int(da), 0x4E, 0xf, 0xf, false));
;         if (CPL == 8) da += __int_as_float(__builtin_amdgcn_update_dpp(0, __float_as_int(da), 0x141, 0xf, 0xf, false));
;         const f2 dav = mk2(da, da);
; #pragma unroll
;         for (int i = 0; i < NV; ++i) S[i] = dav * B[i] + SW[i];
;         f2 py0 = S[0] * Y[0], py1 = S[1] * Y[1];
; #pragma unroll
;         for (int i = 2; i < NV; i += 2) { py0 = S[i] * Y[i] + py0; py1 = S[i + 1] * Y[i + 1] + py1; }
;         py0 = py0 + py1;
;         float yv = py0.x + py0.y;
	v_pk_fma_f32 v[94:95], v[26:27], v[86:87], v[162:163] op_sel_hi:[1,0,1]
	v_pk_fma_f32 v[96:97], v[28:29], v[86:87], v[164:165] op_sel_hi:[1,0,1]
	v_pk_fma_f32 v[98:99], v[30:31], v[86:87], v[166:167] op_sel_hi:[1,0,1]
	v_pk_fma_f32 v[100:101], v[32:33], v[86:87], v[168:169] op_sel_hi:[1,0,1]
	ds_write_b32 v201, v92 offset:6656
	v_pk_mul_f32 v[90:91], v[52:53], v[170:171]
	v_pk_fma_f32 v[90:91], v[54:55], v[172:173], v[90:91]
	v_pk_fma_f32 v[90:91], v[56:57], v[174:175], v[90:91]
	v_pk_fma_f32 v[90:91], v[58:59], v[176:177], v[90:91]
	ds_read_b128 v[52:55], v199 offset:45728
	v_add_f32_e32 v93, v90, v91
	ds_read_b128 v[56:59], v199 offset:45744
	s_waitcnt lgkmcnt(5)
	v_pk_mul_f32 v[88:89], v[44:45], v[94:95]
	ds_read_b128 v[2:5], v199 offset:47040
	v_pk_fma_f32 v[88:89], v[46:47], v[96:97], v[88:89]
	ds_read_b128 v[6:9], v199 offset:47056
	v_pk_fma_f32 v[88:89], v[48:49], v[98:99], v[88:89]
	ds_read_b128 v[34:37], v199 offset:48064
	v_pk_fma_f32 v[88:89], v[50:51], v[100:101], v[88:89]
	ds_read_b128 v[38:41], v199 offset:48080
	v_add_f32_e32 v86, v88, v89
	ds_read_b32 v42, v200 offset:47040
	v_pk_fma_f32 v[162:163], v[76:77], v[84:85], v[94:95] op_sel_hi:[1,0,1]
	v_add_f32_dpp v86, v86, v86 quad_perm:[1,0,3,2] row_mask:0xf bank_mask:0xf bound_ctrl:1
	v_add_f32_dpp v93, v93, v93 quad_perm:[1,0,3,2] row_mask:0xf bank_mask:0xf bound_ctrl:1
	ds_read_b128 v[26:29], v199 offset:47808
	v_add_f32_dpp v86, v86, v86 quad_perm:[2,3,0,1] row_mask:0xf bank_mask:0xf bound_ctrl:1
	v_add_f32_dpp v93, v93, v93 quad_perm:[2,3,0,1] row_mask:0xf bank_mask:0xf bound_ctrl:1
	ds_read_b128 v[30:33], v199 offset:47824
	v_add_f32_dpp v86, v86, v86 row_half_mirror row_mask:0xf bank_mask:0xf bound_ctrl:1
	v_add_f32_dpp v93, v93, v93 row_half_mirror row_mask:0xf bank_mask:0xf bound_ctrl:1
	v_pk_fma_f32 v[164:165], v[78:79], v[84:85], v[96:97] op_sel_hi:[1,0,1]
	v_pk_fma_f32 v[166:167], v[80:81], v[84:85], v[98:99] op_sel_hi:[1,0,1]
	v_pk_fma_f32 v[168:169], v[82:83], v[84:85], v[100:101] op_sel_hi:[1,0,1]
	s_waitcnt lgkmcnt(10)
	v_pk_fma_f32 v[170:171], v[68:69], v[86:87], v[162:163] op_sel_hi:[1,0,1]
	v_pk_fma_f32 v[172:173], v[70:71], v[86:87], v[164:165] op_sel_hi:[1,0,1]
	v_pk_fma_f32 v[174:175], v[72:73], v[86:87], v[166:167] op_sel_hi:[1,0,1]
	v_pk_fma_f32 v[176:177], v[74:75], v[86:87], v[168:169] op_sel_hi:[1,0,1]
	ds_write_b32 v201, v93 offset:6912
	v_pk_mul_f32 v[90:91], v[10:11], v[94:95]
	v_pk_fma_f32 v[90:91], v[12:13], v[96:97], v[90:91]
	v_pk_fma_f32 v[90:91], v[14:15], v[98:99], v[90:91]
	v_pk_fma_f32 v[90:91], v[16:17], v[100:101], v[90:91]
	ds_read_b128 v[10:13], v199 offset:47296
	v_add_f32_e32 v92, v90, v91
	ds_read_b128 v[14:17], v199 offset:47312
	s_waitcnt lgkmcnt(5)
	v_pk_mul_f32 v[88:89], v[2:3], v[170:171]
	ds_read_b128 v[44:47], v199 offset:48608
	v_pk_fma_f32 v[88:89], v[4:5], v[172:173], v[88:89]
	ds_read_b128 v[48:51], v199 offset:48624
	v_pk_fma_f32 v[88:89], v[6:7], v[174:175], v[88:89]
	ds_read_b128 v[76:79], v199 offset:49632
	v_pk_fma_f32 v[88:89], v[8:9], v[176:177], v[88:89]
	ds_read_b128 v[80:83], v199 offset:49648
	v_add_f32_e32 v86, v88, v89
	ds_read_b32 v84, v200 offset:48608
	v_pk_fma_f32 v[162:163], v[34:35], v[42:43], v[170:171] op_sel_hi:[1,0,1]
	v_add_f32_dpp v86, v86, v86 quad_perm:[1,0,3,2] row_mask:0xf bank_mask:0xf bound_ctrl:1
	v_add_f32_dpp v92, v92, v92 quad_perm:[1,0,3,2] row_mask:0xf bank_mask:0xf bound_ctrl:1
	ds_read_b128 v[68:71], v199 offset:49376
	v_add_f32_dpp v86, v86, v86 quad_perm:[2,3,0,1] row_mask:0xf bank_mask:0xf bound_ctrl:1
	v_add_f32_dpp v92, v92, v92 quad_perm:[2,3,0,1] row_mask:0xf bank_mask:0xf bound_ctrl:1
	ds_read_b128 v[72:75], v199 offset:49392
	v_add_f32_dpp v86, v86, v86 row_half_mirror row_mask:0xf bank_mask:0xf bound_ctrl:1
	v_add_f32_dpp v92, v92, v92 row_half_mirror row_mask:0xf bank_mask:0xf bound_ctrl:1
	v_pk_fma_f32 v[164:165], v[36:37], v[42:43], v[172:173] op_sel_hi:[1,0,1]
	v_pk_fma_f32 v[166:167], v[38:39], v[42:43], v[174:175] op_sel_hi:[1,0,1]
	v_pk_fma_f32 v[168:169], v[40:41], v[42:43], v[176:177] op_sel_hi:[1,0,1]
	s_waitcnt lgkmcnt(10)
	v_pk_fma_f32 v[94:95], v[26:27], v[86:87], v[162:163] op_sel_hi:[1,0,1]
	v_pk_fma_f32 v[96:97], v[28:29], v[86:87], v[164:165] op_sel_hi:[1,0,1]
	v_pk_fma_f32 v[98:99], v[30:31], v[86:87], v[166:167] op_sel_hi:[1,0,1]
	v_pk_fma_f32 v[100:101], v[32:33], v[86:87], v[168:169] op_sel_hi:[1,0,1]
	ds_write_b32 v201, v92 offset:7168
	v_pk_mul_f32 v[90:91], v[52:53], v[170:171]
	v_pk_fma_f32 v[90:91], v[54:55], v[172:173], v[90:91]
	v_pk_fma_f32 v[90:91], v[56:57], v[174:175], v[90:91]
	v_pk_fma_f32 v[90:91], v[58:59], v[176:177], v[90:91]
	ds_read_b128 v[52:55], v199 offset:48864
	v_add_f32_e32 v93, v90, v91
	ds_read_b128 v[56:59], v199 offset:48880
	s_waitcnt lgkmcnt(5)
	v_pk_mul_f32 v[88:89], v[44:45], v[94:95]
	ds_read_b128 v[2:5], v199 offset:50176
	v_pk_fma_f32 v[88:89], v[46:47], v[96:97], v[88:89]
	ds_read_b128 v[6:9], v199 offset:50192
	v_pk_fma_f32 v[88:89], v[48:49], v[98:99], v[88:89]
	ds_read_b128 v[34:37], v199 offset:51200
	v_pk_fma_f32 v[88:89], v[50:51], v[100:101], v[88:89]
	ds_read_b128 v[38:41], v199 offset:51216
	v_add_f32_e32 v86, v88, v89
	ds_read_b32 v42, v200 offset:50176
	ds_read_b128 v[18:21], v199 offset:49120
	ds_read_b128 v[22:25], v199 offset:49136
	v_add_f32_dpp v86, v86, v86 quad_perm:[1,0,3,2] row_mask:0xf bank_mask:0xf bound_ctrl:1
	v_add_f32_dpp v93, v93, v93 quad_perm:[1,0,3,2] row_mask:0xf bank_mask:0xf bound_ctrl:1
	ds_read_b128 v[26:29], v199 offset:50944
	v_add_f32_dpp v86, v86, v86 quad_perm:[2,3,0,1] row_mask:0xf bank_mask:0xf bound_ctrl:1
	v_add_f32_dpp v93, v93, v93 quad_perm:[2,3,0,1] row_mask:0xf bank_mask:0xf bound_ctrl:1
	ds_read_b128 v[30:33], v199 offset:50960
	v_add_f32_dpp v86, v86, v86 row_half_mirror row_mask:0xf bank_mask:0xf bound_ctrl:1
	v_add_f32_dpp v93, v93, v93 row_half_mirror row_mask:0xf bank_mask:0xf bound_ctrl:1
	v_pk_fma_f32 v[162:163], v[76:77], v[84:85], v[94:95] op_sel_hi:[1,0,1]
	v_pk_fma_f32 v[164:165], v[78:79], v[84:85], v[96:97] op_sel_hi:[1,0,1]
	v_pk_fma_f32 v[166:167], v[80:81], v[84:85], v[98:99] op_sel_hi:[1,0,1]
	v_pk_fma_f32 v[168:169], v[82:83], v[84:85], v[100:101] op_sel_hi:[1,0,1]
	s_waitcnt lgkmcnt(12)
; template <int CPL>
; DI void scan_block2(CP p, int layer, int s, int d, int hd, int rowhalf, char* smem) {
;     ...
;     const int q = lane & 15;
;     float bias[2][2];
; #pragma unroll
;     for (int mat = 0; mat < 2; ++mat)
; #pragma unroll
;       for (int nt2 = 0; nt2 < 2; ++nt2)
;         bias[mat][nt2] = mat ? p.iclr_a0[(size_t)(layer * 2 + d) * 512 + hd * 64 + nt2 * 32 + l32]
;                              : p.decay_w0[(size_t)(layer * 2 + d) * 512 + hd * 64 + nt2 * 32 + l32];
;     uint2 raw[2][5];
;     auto load_raw = [&](int c) {
; #pragma unroll
;       for (int u = 0; u < 2; ++u) {
;         const int sj = 8 * sw + 4 * u + (lane >> 4);
;         const int sidc = min(c * 32 + sj, L - 1);
;     ...
;         f2 pa0 = S[0] * A[0], pa1 = S[1] * A[1];
; #pragma unroll
;         for (int i = 2; i < NV; i += 2) { pa0 = S[i] * A[i] + pa0; pa1 = S[i + 1] * A[i + 1] + pa1; }
;         pa0 = pa0 + pa1;
;         float da = pa0.x + pa0.y;
;         const f2 vvv = mk2(vv, vv);
;         f2 SW[NV];
; #pragma unroll
;         for (int i = 0; i < NV; ++i) SW[i] = S[i] * W[i] + vvv * K[i];
;         da += __int_as_float(__builtin_amdgcn_update_dpp(0, __float_as_int(da), 0xB1, 0xf, 0xf, false));
;         da += __int_as_float(__builtin_amdgcn_update_dpp(0, __float_as_int(da), 0x4E, 0xf, 0xf, false));
;         if (CPL == 8) da += __int_as_float(__builtin_amdgcn_update_dpp(0, __float_as_int(da), 0x141, 0xf, 0xf, false));
;         const f2 dav = mk2(da, da);
; #pragma unroll
;         for (int i = 0; i < NV; ++i) S[i] = dav * B[i] + SW[i];
;         f2 py0 = S[0] * Y[0], py1 = S[1] * Y[1];
; #pragma unroll
;         for (int i = 2; i < NV; i += 2) { py0 = S[i] * Y[i] + py0; py1 = S[i + 1] * Y[i + 1] + py1; }
;         py0 = py0 + py1;
;         float yv = py0.x + py0.y;
;         yv += __int_as_float(__builtin_amdgcn_update_dpp(0, __float_as_int(yv), 0xB1, 0xf, 0xf, false));
;         yv += __int_as_float(__builtin_amdgcn_update_dpp(0, __float_as_int(yv), 0x4E, 0xf, 0xf, false));
;         if (CPL == 8) yv += __int_as_float(__builtin_amdgcn_update_dpp(0, __float_as_int(yv), 0x141, 0xf, 0xf, false));
;         ydst[jj * ystride] = yv;
; #pragma unroll
;         for (int i = 0; i < CPL / 4; ++i) { ca[i] = na[i]; cy[i] = ny[i]; cw[i] = nw[i]; cb[i] = nb[i]; ck[i] = nk[i]; }
;         cvv = nvv;
;       }
;       __syncthreads();
	v_pk_fma_f32 v[170:171], v[68:69], v[86:87], v[162:163] op_sel_hi:[1,0,1]
	v_pk_fma_f32 v[172:173], v[70:71], v[86:87], v[164:165] op_sel_hi:[1,0,1]
	v_pk_fma_f32 v[174:175], v[72:73], v[86:87], v[166:167] op_sel_hi:[1,0,1]
	v_pk_fma_f32 v[176:177], v[74:75], v[86:87], v[168:169] op_sel_hi:[1,0,1]
	s_waitcnt lgkmcnt(2)
	v_pk_mul_f32 v[170:171], v[170:171], v[18:19]
	v_pk_mul_f32 v[172:173], v[172:173], v[20:21]
	v_pk_mul_f32 v[174:175], v[174:175], v[22:23]
	v_pk_mul_f32 v[176:177], v[176:177], v[24:25]
	ds_write_b32 v201, v93 offset:7424
	v_pk_mul_f32 v[90:91], v[10:11], v[94:95]
	v_pk_fma_f32 v[90:91], v[12:13], v[96:97], v[90:91]
	v_pk_fma_f32 v[90:91], v[14:15], v[98:99], v[90:91]
	v_pk_fma_f32 v[90:91], v[16:17], v[100:101], v[90:91]
	ds_read_b128 v[10:13], v199 offset:50432
	v_add_f32_e32 v92, v90, v91
	ds_read_b128 v[14:17], v199 offset:50448
	v_pk_mul_f32 v[90:91], v[52:53], v[170:171]
	v_add_f32_dpp v92, v92, v92 quad_perm:[1,0,3,2] row_mask:0xf bank_mask:0xf bound_ctrl:1
	v_pk_fma_f32 v[90:91], v[54:55], v[172:173], v[90:91]
	v_pk_fma_f32 v[90:91], v[56:57], v[174:175], v[90:91]
	v_add_f32_dpp v92, v92, v92 quad_perm:[2,3,0,1] row_mask:0xf bank_mask:0xf bound_ctrl:1
	v_pk_fma_f32 v[90:91], v[58:59], v[176:177], v[90:91]
	v_add_f32_e32 v93, v90, v91
	v_add_f32_dpp v92, v92, v92 row_half_mirror row_mask:0xf bank_mask:0xf bound_ctrl:1
	s_nop 0
	v_add_f32_dpp v93, v93, v93 quad_perm:[1,0,3,2] row_mask:0xf bank_mask:0xf bound_ctrl:1
	ds_write_b32 v201, v92 offset:7680
	s_nop 0
	v_add_f32_dpp v93, v93, v93 quad_perm:[2,3,0,1] row_mask:0xf bank_mask:0xf bound_ctrl:1
	s_nop 1
	v_add_f32_dpp v93, v93, v93 row_half_mirror row_mask:0xf bank_mask:0xf bound_ctrl:1
	s_nop 0
	ds_write_b32 v201, v93 offset:7936
.Lsc8_next:
	s_waitcnt lgkmcnt(0)
	s_barrier
	s_add_i32 s10, s10, 1
	s_cmp_eq_u32 s10, 0x101
	s_cbranch_scc0 .Lsc8_chunk
	s_branch .Lsc8_done
.Lsc8_drain16:
	v_pk_mul_f32 v[90:91], v[52:53], v[170:171]
	v_add_f32_dpp v92, v92, v92 quad_perm:[1,0,3,2] row_mask:0xf bank_mask:0xf bound_ctrl:1
	v_pk_fma_f32 v[90:91], v[54:55], v[172:173], v[90:91]
	v_pk_fma_f32 v[90:91], v[56:57], v[174:175], v[90:91]
	v_add_f32_dpp v92, v92, v92 quad_perm:[2,3,0,1] row_mask:0xf bank_mask:0xf bound_ctrl:1
	v_pk_fma_f32 v[90:91], v[58:59], v[176:177], v[90:91]
	v_add_f32_e32 v93, v90, v91
	v_add_f32_dpp v92, v92, v92 row_half_mirror row_mask:0xf bank_mask:0xf bound_ctrl:1
	s_nop 0
	v_add_f32_dpp v93, v93, v93 quad_perm:[1,0,3,2] row_mask:0xf bank_mask:0xf bound_ctrl:1
	ds_write_b32 v201, v92 offset:3584
	s_nop 0
	v_add_f32_dpp v93, v93, v93 quad_perm:[2,3,0,1] row_mask:0xf bank_mask:0xf bound_ctrl:1
	s_nop 1
	v_add_f32_dpp v93, v93, v93 row_half_mirror row_mask:0xf bank_mask:0xf bound_ctrl:1
	s_nop 0
	ds_write_b32 v201, v93 offset:3840
	s_branch .Lsc8_next
.Lsc8_done:
	s_setprio 0
.LBB0_187:
	s_andn2_saveexec_b64 s[8:9], s[2:3]
	s_cbranch_execz .LBB0_85
	s_setprio 0
	s_lshl_b32 s2, s75, 11
	s_ashr_i32 s15, s82, 5
	s_or_b32 s10, s2, s80
	s_add_u32 s2, s58, s10
	s_addc_u32 s3, s59, 0
	s_lshl_b32 s11, s73, 2
	s_add_u32 s2, s2, s11
	s_addc_u32 s3, s3, 0
	s_add_u32 s10, s54, s10
	s_addc_u32 s17, s55, 0
	v_and_b32_e32 v46, 31, v2
	s_add_u32 s10, s10, s11
	v_subrev_u32_e32 v50, 32, v52
	v_lshrrev_b32_e32 v53, 4, v6
	v_lshlrev_b32_e32 v0, 2, v46
	s_addc_u32 s11, s17, 0
	v_or_b32_e32 v54, v50, v53
	global_load_dword v64, v0, s[10:11]
	global_load_dword v63, v0, s[10:11] offset:128
	global_load_dword v56, v0, s[2:3]
	global_load_dword v55, v0, s[2:3] offset:128
	v_min_u32_e32 v0, 0x200f, v54
	s_cmp_eq_u32 s75, 0
	s_cselect_b64 vcc, -1, 0
	v_sub_u32_e32 v4, 0x200f, v0
	s_mulk_i32 s15, 0x2010
	v_cndmask_b32_e32 v0, v4, v0, vcc
	v_and_b32_e32 v75, 15, v2
	v_add_u32_e32 v0, s15, v0
	v_mov_b64_e32 v[4:5], s[66:67]
	v_lshrrev_b32_e32 v3, 5, v6
	v_mad_i64_i32 v[6:7], s[2:3], v0, s88, v[4:5]
	v_lshlrev_b32_e32 v0, 3, v75
	v_lshl_add_u64 v[6:7], v[6:7], 0, v[0:1]
	s_lshl_b32 s76, s73, 1
	v_lshl_add_u64 v[8:9], v[6:7], 0, s[76:77]
	global_load_dwordx2 v[10:11], v[8:9], off
	global_load_dwordx2 v[12:13], v[8:9], off offset:1024
	s_nop 0
	global_load_dwordx2 v[8:9], v[8:9], off offset:2048
	s_lshl_b32 s72, s72, 1
	s_mov_b32 s73, s77
	v_lshl_add_u64 v[6:7], v[6:7], 0, s[72:73]
	global_load_dwordx2 v[14:15], v[6:7], off offset:3072
	global_load_dwordx2 v[16:17], v[6:7], off offset:3328
	v_or_b32_e32 v47, v52, v53
	v_subrev_u32_e32 v6, 28, v47
	v_min_u32_e32 v6, 0x200f, v6
	v_sub_u32_e32 v7, 0x200f, v6
	v_cndmask_b32_e32 v6, v7, v6, vcc
	v_add_u32_e32 v6, s15, v6
	v_mad_i64_i32 v[4:5], s[2:3], v6, s88, v[4:5]
	v_lshl_add_u64 v[4:5], v[4:5], 0, v[0:1]
	v_lshl_add_u64 v[6:7], v[4:5], 0, s[76:77]
	global_load_dwordx2 v[32:33], v[6:7], off
	global_load_dwordx2 v[26:27], v[6:7], off offset:1024
	global_load_dwordx2 v[30:31], v[6:7], off offset:2048
	v_lshl_add_u64 v[6:7], v[4:5], 0, s[72:73]
	global_load_dwordx2 v[4:5], v[6:7], off offset:3072
	s_nop 0
	global_load_dwordx2 v[6:7], v[6:7], off offset:3328
	s_movk_i32 s3, 0x90
	v_readlane_b32 s2, v252, 29
	v_readlane_b32 s10, v252, 30
	v_mov_b32_e32 v77, v1
	v_cmp_gt_u32_e64 s[40:41], s31, v50
	s_mul_i32 s17, s75, 0x8100
	s_waitcnt vmcnt(9)
	v_lshlrev_b32_e32 v22, 16, v10
	v_and_b32_e32 v23, 0xffff0000, v10
	s_waitcnt vmcnt(7)
	v_lshlrev_b32_e32 v18, 16, v8
	v_and_b32_e32 v19, 0xffff0000, v8
	v_mul_lo_u32 v8, v54, s3
	v_add3_u32 v67, s2, v8, v0
	v_add3_u32 v68, s10, v8, v0
	v_and_or_b32 v0, v2, 7, v50
	v_mul_lo_u32 v0, v0, s3
	v_lshlrev_b32_e32 v2, 4, v3
	v_add3_u32 v62, s2, v0, v2
	v_readlane_b32 s2, v252, 26
	v_lshlrev_b32_e32 v8, 4, v75
	v_lshlrev_b32_e32 v20, 16, v9
	v_add_u32_e32 v51, s2, v2
	s_movk_i32 s2, 0x188
	v_and_b32_e32 v21, 0xffff0000, v9
	v_add_u32_e32 v9, 0, v8
	v_mul_lo_u32 v74, v54, s2
	s_waitcnt vmcnt(6)
; #define MFMA(a, b, c) __builtin_amdgcn_mfma_f32_32x32x16_bf16((a), (b), (c), 0, 0, 0)
; DI float bflo(unsigned u) { return __uint_as_float(u << 16); }
; DI float bfhi(unsigned u) { return __uint_as_float(u & 0xffff0000u); }
; template <int CPL>
; DI void scan_block2(CP p, int layer, int s, int d, int hd, int rowhalf, char* smem) {
;     ...
;     auto stage = [&](int c) {
;       float r4[2][4], k4[2][4], kk4[2][4], v4[2][4];
; #pragma unroll
;       for (int u = 0; u < 2; ++u) {
;         const int sj = 8 * sw + 4 * u + (lane >> 4);
;         r4[u][0] = bflo(raw[u][0].x); r4[u][1] = bfhi(raw[u][0].x); r4[u][2] = bflo(raw[u][0].y); r4[u][3] = bfhi(raw[u][0].y);
;         k4[u][0] = bflo(raw[u][1].x); k4[u][1] = bfhi(raw[u][1].x); k4[u][2] = bflo(raw[u][1].y); k4[u][3] = bfhi(raw[u][1].y);
;         v4[u][0] = bflo(raw[u][2].x); v4[u][1] = bfhi(raw[u][2].x); v4[u][2] = bflo(raw[u][2].y); v4[u][3] = bfhi(raw[u][2].y);
;         *(uint2*)(XL + sj * 72 + 4 * q) = raw[u][3];
;         *(uint2*)(XL + 32 * 72 + sj * 72 + 4 * q) = raw[u][4];
;         const float4 kkw = *(const float4*)(CS + 4 * q);
;         float x0 = k4[u][0] * kkw.x, x1 = k4[u][1] * kkw.y, x2 = k4[u][2] * kkw.z, x3 = k4[u][3] * kkw.w;
;         float ss = sum16(x0 * x0 + x1 * x1 + x2 * x2 + x3 * x3);
;         float inv = __builtin_amdgcn_rsqf(fmaxf(ss, 1e-24f));
;         kk4[u][0] = x0 * inv; kk4[u][1] = x1 * inv; kk4[u][2] = x2 * inv; kk4[u][3] = x3 * inv;
;       }
;       LDS_FENCE();
;       float* OPn = OP + (c & 1) * 32 * 392;
; #pragma unroll
;       for (int mat = 0; mat < 2; ++mat)
; #pragma unroll
;         for (int nt2 = 0; nt2 < 2; ++nt2) {
;           f32x16 acc;
; #pragma unroll
;           for (int r = 0; r < 16; ++r) acc[r] = 0.f;
;           const u16* xb = XL + mat * 32 * 72 + (8 * sw + (l32 & 7)) * 72 + hh * 8;
; #pragma unroll
;           for (int ks = 0; ks < 4; ++ks) acc = MFMA(*(const bf16x8*)(xb + ks * 16), *(const bf16x8*)(WL + (mat * 64 + nt2 * 32 + l32) * 72 + ks * 16 + hh * 8), acc);
; #pragma unroll
;           for (int r = 0; r < 4; ++r) {
;             float x = acc[r] + bias[mat][nt2];
;             float sg = sigmoidf_(x);
;             float val = mat ? sg : __expf(-0.6065306597126334f * sg);
;             OPn[(8 * sw + 4 * hh + r) * 392 + (mat ? 0 : 128) + nt2 * 32 + l32] = val;
;           }
;         }
;       LDS_FENCE();
	ds_write_b64 v67, v[14:15]
	s_waitcnt vmcnt(5)
	ds_write_b64 v68, v[16:17]
	v_add_u32_e32 v69, 0x1f600, v9
	v_lshl_add_u32 v48, v74, 2, 0
	v_lshlrev_b32_e32 v24, 16, v11
	v_and_b32_e32 v25, 0xffff0000, v11
	v_add_u32_e32 v57, v48, v8
	v_add_u32_e32 v58, 0x1f700, v9
	v_add_u32_e32 v61, 0x1f800, v9
	ds_read_b128 v[8:11], v69
	v_lshl_or_b32 v2, v3, 2, v50
	v_lshlrev_b32_e32 v44, 16, v12
	v_and_b32_e32 v45, 0xffff0000, v12
	v_mul_lo_u32 v2, v2, s2
	v_lshlrev_b32_e32 v42, 16, v13
	v_and_b32_e32 v43, 0xffff0000, v13
	v_or_b32_e32 v70, v2, v46
	s_waitcnt lgkmcnt(0)
	v_pk_mul_f32 v[2:3], v[8:9], v[44:45]
	v_pk_mul_f32 v[10:11], v[10:11], v[42:43]
	v_pk_mul_f32 v[8:9], v[2:3], v[2:3]
	v_pk_mul_f32 v[12:13], v[10:11], v[10:11]
	v_add_f32_e32 v8, v8, v9
	v_add_f32_e32 v8, v8, v12
	v_add_f32_e32 v8, v8, v13
	s_waitcnt vmcnt(1)
	ds_write_b64 v67, v[4:5] offset:576
	s_waitcnt vmcnt(0)
	ds_write_b64 v68, v[6:7] offset:576
	v_add_f32_dpp v8, v8, v8 row_ror:8 row_mask:0xf bank_mask:0xf bound_ctrl:1
	v_lshlrev_b32_e32 v36, 16, v26
	v_and_b32_e32 v37, 0xffff0000, v26
	v_add_f32_dpp v8, v8, v8 row_ror:4 row_mask:0xf bank_mask:0xf bound_ctrl:1
	v_lshlrev_b32_e32 v34, 16, v27
	v_and_b32_e32 v35, 0xffff0000, v27
	v_add_f32_dpp v8, v8, v8 row_ror:2 row_mask:0xf bank_mask:0xf bound_ctrl:1
	v_mad_u32_u24 v0, v46, s3, v51
	v_lshl_add_u32 v59, v70, 2, 0
	v_add_f32_dpp v8, v8, v8 row_ror:1 row_mask:0xf bank_mask:0xf bound_ctrl:1
	v_max_f32_e32 v8, 0x179abe15, v8
	v_rsq_f32_e32 v8, v8
	v_add_u32_e32 v71, 0x80, v70
	v_lshl_add_u32 v66, v71, 2, 0
	v_add_u32_e32 v72, 0xa0, v70
	v_pk_mul_f32 v[26:27], v[2:3], v[8:9] op_sel_hi:[1,0]
	ds_read_b128 v[2:5], v69
	s_waitcnt lgkmcnt(0)
	v_pk_mul_f32 v[28:29], v[10:11], v[8:9] op_sel_hi:[1,0]
	v_lshl_add_u32 v65, v72, 2, 0
	v_add_u32_e32 v73, 32, v70
	s_waitcnt lgkmcnt(0)
	v_pk_mul_f32 v[38:39], v[2:3], v[36:37]
	v_pk_mul_f32 v[40:41], v[4:5], v[34:35]
	v_pk_mul_f32 v[2:3], v[38:39], v[38:39]
	v_pk_mul_f32 v[4:5], v[40:41], v[40:41]
	v_add_f32_e32 v2, v2, v3
	v_add_f32_e32 v2, v2, v4
	v_add_f32_e32 v2, v2, v5
	v_lshl_add_u32 v60, v73, 2, 0
	s_nop 0
	v_add_f32_dpp v2, v2, v2 row_ror:8 row_mask:0xf bank_mask:0xf bound_ctrl:1
	s_nop 1
	v_add_f32_dpp v2, v2, v2 row_ror:4 row_mask:0xf bank_mask:0xf bound_ctrl:1
	s_nop 1
	v_add_f32_dpp v49, v2, v2 row_ror:2 row_mask:0xf bank_mask:0xf bound_ctrl:1
	ds_read_b128 v[2:5], v62
	ds_read_b128 v[78:81], v62 offset:32
	ds_read_b128 v[6:9], v0
	ds_read_b128 v[82:85], v0 offset:32
	s_waitcnt lgkmcnt(1)
	v_mfma_f32_32x32x16_bf16 v[2:17], v[2:5], v[6:9], 0
	v_mov_b32_dpp v77, v49 row_ror:1 row_mask:0xf bank_mask:0xf
	s_waitcnt lgkmcnt(0)
	v_mfma_f32_32x32x16_bf16 v[2:17], v[78:81], v[82:85], v[2:17]
	ds_read_b128 v[78:81], v62 offset:64
	ds_read_b128 v[82:85], v0 offset:64
	s_waitcnt lgkmcnt(0)
	v_mfma_f32_32x32x16_bf16 v[2:17], v[78:81], v[82:85], v[2:17]
	ds_read_b128 v[78:81], v62 offset:96
	ds_read_b128 v[82:85], v0 offset:96
	s_waitcnt lgkmcnt(0)
	v_mfma_f32_32x32x16_bf16 v[2:17], v[78:81], v[82:85], v[2:17]
	s_nop 11
	v_add_f32_e32 v2, v64, v2
	v_mul_f32_e32 v2, 0xbfb8aa3b, v2
	v_exp_f32_e32 v2, v2
	s_nop 0
	v_add_f32_e32 v2, 1.0, v2
	v_rcp_f32_e32 v2, v2
	s_nop 0
	v_mul_f32_e32 v2, 0xbf1b4598, v2
	v_mul_f32_e32 v2, 0x3fb8aa3b, v2
	v_exp_f32_e32 v2, v2
	ds_write_b32 v59, v2 offset:512
	v_add_f32_e32 v2, v64, v3
	v_mul_f32_e32 v2, 0xbfb8aa3b, v2
	v_exp_f32_e32 v2, v2
	s_nop 0
	v_add_f32_e32 v2, 1.0, v2
	v_rcp_f32_e32 v2, v2
	s_nop 0
	v_mul_f32_e32 v2, 0xbf1b4598, v2
	v_mul_f32_e32 v2, 0x3fb8aa3b, v2
	v_exp_f32_e32 v2, v2
	ds_write_b32 v66, v2 offset:1568
	v_add_f32_e32 v2, v64, v4
	v_mul_f32_e32 v2, 0xbfb8aa3b, v2
	v_exp_f32_e32 v2, v2
	s_nop 0
	v_add_f32_e32 v2, 1.0, v2
	v_rcp_f32_e32 v2, v2
	s_nop 0
	v_mul_f32_e32 v2, 0xbf1b4598, v2
	v_mul_f32_e32 v2, 0x3fb8aa3b, v2
	v_exp_f32_e32 v2, v2
	ds_write_b32 v66, v2 offset:3136
	v_add_f32_e32 v2, v64, v5
	v_mul_f32_e32 v2, 0xbfb8aa3b, v2
	v_exp_f32_e32 v2, v2
	s_nop 0
	v_add_f32_e32 v2, 1.0, v2
	v_rcp_f32_e32 v2, v2
	s_nop 0
	v_mul_f32_e32 v2, 0xbf1b4598, v2
	v_mul_f32_e32 v2, 0x3fb8aa3b, v2
	v_exp_f32_e32 v2, v2
	ds_write_b32 v66, v2 offset:4704
	ds_read_b128 v[2:5], v62
	ds_read_b128 v[78:81], v62 offset:32
	ds_read_b128 v[6:9], v0 offset:4608
	ds_read_b128 v[82:85], v0 offset:4640
	s_waitcnt lgkmcnt(1)
	v_mfma_f32_32x32x16_bf16 v[2:17], v[2:5], v[6:9], 0
	s_waitcnt lgkmcnt(0)
	v_mfma_f32_32x32x16_bf16 v[2:17], v[78:81], v[82:85], v[2:17]
	ds_read_b128 v[78:81], v62 offset:64
	ds_read_b128 v[82:85], v0 offset:4672
	s_waitcnt lgkmcnt(0)
	v_mfma_f32_32x32x16_bf16 v[2:17], v[78:81], v[82:85], v[2:17]
	ds_read_b128 v[78:81], v62 offset:96
	ds_read_b128 v[82:85], v0 offset:4704
	s_waitcnt lgkmcnt(0)
; template <int CPL>
; DI void scan_block2(CP p, int layer, int s, int d, int hd, int rowhalf, char* smem) {
;     ...
; #pragma unroll
;       for (int mat = 0; mat < 2; ++mat)
; #pragma unroll
;         for (int nt2 = 0; nt2 < 2; ++nt2) {
;           f32x16 acc;
; #pragma unroll
;           for (int r = 0; r < 16; ++r) acc[r] = 0.f;
;           const u16* xb = XL + mat * 32 * 72 + (8 * sw + (l32 & 7)) * 72 + hh * 8;
; #pragma unroll
;           for (int ks = 0; ks < 4; ++ks) acc = MFMA(*(const bf16x8*)(xb + ks * 16), *(const bf16x8*)(WL + (mat * 64 + nt2 * 32 + l32) * 72 + ks * 16 + hh * 8), acc);
; #pragma unroll
;           for (int r = 0; r < 4; ++r) {
;             float x = acc[r] + bias[mat][nt2];
;             float sg = sigmoidf_(x);
;             float val = mat ? sg : __expf(-0.6065306597126334f * sg);
;             OPn[(8 * sw + 4 * hh + r) * 392 + (mat ? 0 : 128) + nt2 * 32 + l32] = val;
;           }
;         }
;       LDS_FENCE();
; #pragma unroll
;       for (int u = 0; u < 2; ++u) {
;         const int sj = 8 * sw + 4 * u + (lane >> 4);
;         const float4 w4 = *(const float4*)(OPn + sj * 392 + 128 + 4 * q);
;         const float4 a4 = *(const float4*)(OPn + sj * 392 + 4 * q);
;         const float4 ka = *(const float4*)(CS + 64 + 4 * q);
;         const float4 brk = *(const float4*)(CS + 128 + 4 * q);
;         const float wv4[4] = {w4.x, w4.y, w4.z, w4.w}, av4[4] = {a4.x, a4.y, a4.z, a4.w};
;         const float kav[4] = {ka.x, ka.y, ka.z, ka.w}, bkv[4] = {brk.x, brk.y, brk.z, brk.w};
;         float bb[4], kd[4];
;         float bs = 0.f;
; #pragma unroll
;         for (int e = 0; e < 4; ++e) {
;           bb[e] = -kk4[u][e] * av4[e];
;           kd[e] = k4[u][e] * (1.f + (av4[e] - 1.f) * kav[e]);
;           bs += r4[u][e] * kd[e] * bkv[e];
;         }
;         bs = sum16(bs);
;         float* o = OPn + sj * 392 + 4 * q;
;         *(float4*)(o) = make_float4(kk4[u][0], kk4[u][1], kk4[u][2], kk4[u][3]);
;         *(float4*)(o + 64) = make_float4(r4[u][0], r4[u][1], r4[u][2], r4[u][3]);
;         *(float4*)(o + 128) = w4;
;         *(float4*)(o + 192) = make_float4(bb[0], bb[1], bb[2], bb[3]);
;         *(float4*)(o + 256) = make_float4(kd[0], kd[1], kd[2], kd[3]);
;         *(float4*)(o + 320) = make_float4(v4[u][0], v4[u][1], v4[u][2], v4[u][3]);
;         if (q == 0) {
;           const int sidx = c * 32 + sj;
	v_mfma_f32_32x32x16_bf16 v[2:17], v[78:81], v[82:85], v[2:17]
	s_nop 11
	v_add_f32_e32 v2, v63, v2
	v_mul_f32_e32 v2, 0xbfb8aa3b, v2
	v_exp_f32_e32 v2, v2
	s_nop 0
	v_add_f32_e32 v2, 1.0, v2
	v_rcp_f32_e32 v2, v2
	s_nop 0
	v_mul_f32_e32 v2, 0xbf1b4598, v2
	v_mul_f32_e32 v2, 0x3fb8aa3b, v2
	v_exp_f32_e32 v2, v2
	ds_write_b32 v59, v2 offset:640
	v_add_f32_e32 v2, v63, v3
	v_mul_f32_e32 v2, 0xbfb8aa3b, v2
	v_exp_f32_e32 v2, v2
	s_nop 0
	v_add_f32_e32 v2, 1.0, v2
	v_rcp_f32_e32 v2, v2
	s_nop 0
	v_mul_f32_e32 v2, 0xbf1b4598, v2
	v_mul_f32_e32 v2, 0x3fb8aa3b, v2
	v_exp_f32_e32 v2, v2
	ds_write_b32 v65, v2 offset:1568
	v_add_f32_e32 v2, v63, v4
	v_mul_f32_e32 v2, 0xbfb8aa3b, v2
	v_exp_f32_e32 v2, v2
	s_nop 0
	v_add_f32_e32 v2, 1.0, v2
	v_rcp_f32_e32 v2, v2
	s_nop 0
	v_mul_f32_e32 v2, 0xbf1b4598, v2
	v_mul_f32_e32 v2, 0x3fb8aa3b, v2
	v_exp_f32_e32 v2, v2
	ds_write_b32 v65, v2 offset:3136
	v_add_f32_e32 v2, v63, v5
	v_mul_f32_e32 v2, 0xbfb8aa3b, v2
	v_exp_f32_e32 v2, v2
	s_nop 0
	v_add_f32_e32 v2, 1.0, v2
	v_rcp_f32_e32 v2, v2
	s_nop 0
	v_mul_f32_e32 v2, 0xbf1b4598, v2
	v_mul_f32_e32 v2, 0x3fb8aa3b, v2
	v_exp_f32_e32 v2, v2
	ds_write_b32 v65, v2 offset:4704
	ds_read_b128 v[2:5], v62 offset:4608
	ds_read_b128 v[78:81], v62 offset:4640
	ds_read_b128 v[6:9], v0 offset:9216
	ds_read_b128 v[82:85], v0 offset:9248
	s_waitcnt lgkmcnt(1)
	v_mfma_f32_32x32x16_bf16 v[2:17], v[2:5], v[6:9], 0
	s_waitcnt lgkmcnt(0)
	v_mfma_f32_32x32x16_bf16 v[2:17], v[78:81], v[82:85], v[2:17]
	ds_read_b128 v[78:81], v62 offset:4672
	ds_read_b128 v[82:85], v0 offset:9280
	s_waitcnt lgkmcnt(0)
	v_mfma_f32_32x32x16_bf16 v[2:17], v[78:81], v[82:85], v[2:17]
	ds_read_b128 v[78:81], v62 offset:4704
	ds_read_b128 v[82:85], v0 offset:9312
	s_waitcnt lgkmcnt(0)
	v_mfma_f32_32x32x16_bf16 v[2:17], v[78:81], v[82:85], v[2:17]
	s_nop 11
	v_add_f32_e32 v2, v56, v2
	v_mul_f32_e32 v2, 0xbfb8aa3b, v2
	v_exp_f32_e32 v2, v2
	s_nop 0
	v_add_f32_e32 v2, 1.0, v2
	v_rcp_f32_e32 v2, v2
	ds_write_b32 v59, v2
	v_add_f32_e32 v2, v56, v3
	v_mul_f32_e32 v2, 0xbfb8aa3b, v2
	v_exp_f32_e32 v2, v2
	s_nop 0
	v_add_f32_e32 v2, 1.0, v2
	v_rcp_f32_e32 v2, v2
	ds_write_b32 v59, v2 offset:1568
	v_add_f32_e32 v2, v56, v4
	v_mul_f32_e32 v2, 0xbfb8aa3b, v2
	v_exp_f32_e32 v2, v2
	s_nop 0
	v_add_f32_e32 v2, 1.0, v2
	v_rcp_f32_e32 v2, v2
	ds_write_b32 v59, v2 offset:3136
	v_add_f32_e32 v2, v56, v5
	v_mul_f32_e32 v2, 0xbfb8aa3b, v2
	v_exp_f32_e32 v2, v2
	s_nop 0
	v_add_f32_e32 v2, 1.0, v2
	v_rcp_f32_e32 v2, v2
	ds_write_b32 v59, v2 offset:4704
	ds_read_b128 v[2:5], v62 offset:4608
	ds_read_b128 v[78:81], v62 offset:4640
	ds_read_b128 v[6:9], v0 offset:13824
	ds_read_b128 v[82:85], v0 offset:13856
	s_waitcnt lgkmcnt(1)
	v_mfma_f32_32x32x16_bf16 v[2:17], v[2:5], v[6:9], 0
	s_waitcnt lgkmcnt(0)
	v_mfma_f32_32x32x16_bf16 v[2:17], v[78:81], v[82:85], v[2:17]
	ds_read_b128 v[78:81], v62 offset:4672
	ds_read_b128 v[82:85], v0 offset:13888
	s_waitcnt lgkmcnt(0)
	v_mfma_f32_32x32x16_bf16 v[2:17], v[78:81], v[82:85], v[2:17]
	ds_read_b128 v[78:81], v62 offset:4704
	ds_read_b128 v[82:85], v0 offset:13920
	s_waitcnt lgkmcnt(0)
	v_mfma_f32_32x32x16_bf16 v[2:17], v[78:81], v[82:85], v[2:17]
	s_nop 11
	v_add_f32_e32 v0, v55, v2
	v_mul_f32_e32 v0, 0xbfb8aa3b, v0
	v_exp_f32_e32 v0, v0
	s_nop 0
	v_add_f32_e32 v0, 1.0, v0
	v_rcp_f32_e32 v0, v0
	ds_write_b32 v59, v0 offset:128
	v_add_f32_e32 v0, v55, v3
	v_mul_f32_e32 v0, 0xbfb8aa3b, v0
	v_exp_f32_e32 v0, v0
	s_nop 0
	v_add_f32_e32 v0, 1.0, v0
	v_rcp_f32_e32 v0, v0
	ds_write_b32 v60, v0 offset:1568
	v_add_f32_e32 v0, v55, v4
	v_mul_f32_e32 v0, 0xbfb8aa3b, v0
	v_exp_f32_e32 v0, v0
	s_nop 0
	v_add_f32_e32 v0, 1.0, v0
	v_rcp_f32_e32 v0, v0
	ds_write_b32 v60, v0 offset:3136
	v_add_f32_e32 v0, v55, v5
	v_mul_f32_e32 v0, 0xbfb8aa3b, v0
	v_exp_f32_e32 v0, v0
	s_nop 0
	v_add_f32_e32 v0, 1.0, v0
	v_rcp_f32_e32 v0, v0
	ds_write_b32 v60, v0 offset:4704
	s_waitcnt lgkmcnt(0)
	ds_read_b128 v[2:5], v61
	ds_read_b128 v[10:13], v57
	ds_write_b128 v57, v[22:25] offset:256
	s_waitcnt lgkmcnt(1)
	v_pk_mul_f32 v[6:7], v[10:11], v[26:27] neg_lo:[0,1] neg_hi:[0,1]
	v_pk_mul_f32 v[8:9], v[12:13], v[28:29] neg_lo:[0,1] neg_hi:[0,1]
	ds_write_b128 v57, v[26:29]
	ds_write_b128 v57, v[6:9] offset:768
	ds_read_b128 v[6:9], v58
	v_pk_add_f32 v[10:11], v[10:11], -1.0 op_sel_hi:[1,0]
	v_pk_add_f32 v[12:13], v[12:13], -1.0 op_sel_hi:[1,0]
	s_waitcnt lgkmcnt(0)
	v_pk_fma_f32 v[10:11], v[10:11], v[6:7], 1.0 op_sel_hi:[1,1,0]
	s_nop 0
	v_pk_mul_f32 v[10:11], v[10:11], v[44:45]
	v_pk_fma_f32 v[12:13], v[12:13], v[8:9], 1.0 op_sel_hi:[1,1,0]
	v_mul_f32_e32 v0, v10, v22
	v_fma_f32 v0, v2, v0, 0
	v_mul_f32_e32 v14, v11, v23
	v_pk_mul_f32 v[12:13], v[12:13], v[42:43]
	v_fmac_f32_e32 v0, v3, v14
	v_mul_f32_e32 v14, v12, v24
	v_mul_f32_e32 v15, v13, v25
	v_fmac_f32_e32 v0, v4, v14
	v_fmac_f32_e32 v0, v5, v15
	ds_write_b128 v57, v[10:13] offset:1024
	ds_write_b128 v57, v[18:21] offset:1280
	v_add_f32_dpp v0, v0, v0 row_ror:8 row_mask:0xf bank_mask:0xf bound_ctrl:1
	v_or_b32_e32 v10, s16, v75
	v_mov_b32_e32 v14, v1
	v_add_f32_dpp v0, v0, v0 row_ror:4 row_mask:0xf bank_mask:0xf bound_ctrl:1
	v_cmp_eq_u32_e64 s[42:43], 0, v10
	s_and_b64 s[2:3], s[42:43], s[40:41]
	v_add_f32_dpp v0, v0, v0 row_ror:2 row_mask:0xf bank_mask:0xf bound_ctrl:1
	s_nop 1
	v_mov_b32_dpp v14, v0 row_ror:1 row_mask:0xf bank_mask:0xf
	s_and_saveexec_b64 s[10:11], s[2:3]
	s_cbranch_execz .LBB0_190
	s_ashr_i32 s41, s15, 31
	v_add_f32_e32 v12, v0, v14
	v_sub_u32_e32 v0, 0x200f, v54
	s_add_u32 s40, s17, s15
	v_cndmask_b32_e32 v0, v0, v54, vcc
	s_addc_u32 s41, 0, s41
	v_lshl_add_u64 v[10:11], s[40:41], 0, v[0:1]
	v_lshlrev_b64 v[10:11], 5, v[10:11]
	v_lshl_add_u64 v[10:11], s[64:65], 0, v[10:11]
	s_lshl_b32 s40, s74, 2
	s_mov_b32 s41, s77
	v_lshl_add_u64 v[10:11], v[10:11], 0, s[40:41]
	global_store_dword v[10:11], v12, off

; template <int CPL>
; DI void scan_block2(CP p, int layer, int s, int d, int hd, int rowhalf, char* smem) {
;     ...
;     auto load_raw = [&](int c) {
; #pragma unroll
;       for (int u = 0; u < 2; ++u) {
;         const int sj = 8 * sw + 4 * u + (lane >> 4);
;         const int sidc = min(c * 32 + sj, L - 1);
;         const int tok = d == 0 ? sidc : L - 1 - sidc;
;         const u16* base = p.regB + (size_t)(r0 + tok) * 1952 + 4 * q;
;         raw[u][0] = *(const uint2*)(base + aoff0); raw[u][1] = *(const uint2*)(base + aoff1); raw[u][2] = *(const uint2*)(base + aoff2);
;         raw[u][3] = *(const uint2*)(base + aoff3); raw[u][4] = *(const uint2*)(base + aoff4);
;       }
;     ...
;     load_raw(0);
;     stage(0);
;     if (nch > 1) load_raw(1);
;     __syncthreads();
.LBB0_194:
	s_or_b64 exec, exec, s[2:3]
	v_min_u32_e32 v0, 0x200f, v47
	v_sub_u32_e32 v3, 0x200f, v0
	v_cndmask_b32_e32 v0, v3, v0, vcc
	v_add_u32_e32 v0, s15, v0
	v_mov_b64_e32 v[4:5], s[66:67]
	v_mad_i64_i32 v[6:7], s[2:3], v0, s88, v[4:5]
	v_lshlrev_b32_e32 v0, 1, v76
	v_lshl_add_u64 v[6:7], v[6:7], 0, v[0:1]
	s_mov_b32 s73, s77
	v_lshl_add_u64 v[8:9], v[6:7], 0, s[76:77]
	v_lshl_add_u64 v[6:7], v[6:7], 0, s[72:73]
	global_load_dwordx2 v[10:11], v[8:9], off
	global_load_dwordx2 v[12:13], v[8:9], off offset:1024
	s_nop 0
	global_load_dwordx2 v[8:9], v[8:9], off offset:2048
	s_nop 0
	global_load_dwordx2 v[14:15], v[6:7], off offset:3072
	s_nop 0
	global_load_dwordx2 v[6:7], v[6:7], off offset:3328
	v_or_b32_e32 v3, 4, v47
	v_min_u32_e32 v3, 0x200f, v3
	v_sub_u32_e32 v16, 0x200f, v3
	v_cndmask_b32_e32 v3, v16, v3, vcc
	v_add_u32_e32 v3, s15, v3
	v_mad_i64_i32 v[4:5], s[2:3], v3, s88, v[4:5]
	v_lshl_add_u64 v[4:5], v[4:5], 0, v[0:1]
	v_lshl_add_u64 v[16:17], v[4:5], 0, s[76:77]
	v_lshl_add_u64 v[4:5], v[4:5], 0, s[72:73]
	global_load_dwordx2 v[32:33], v[16:17], off
	global_load_dwordx2 v[26:27], v[16:17], off offset:1024
	global_load_dwordx2 v[30:31], v[16:17], off offset:2048
	s_nop 0
	global_load_dwordx2 v[16:17], v[4:5], off offset:3072
	global_load_dwordx2 v[42:43], v[4:5], off offset:3328
	s_mov_b64 s[98:99], exec
	s_mov_b64 exec, -1
	v_and_b32_e32 v105, 63, v179
	v_lshlrev_b32_e32 v105, 2, v105
	v_lshrrev_b32_e32 v106, 6, v179
	v_add_u32_e32 v106, -4, v106
	v_mul_u32_u24_e32 v106, 0x3100, v106
	v_mov_b32_e32 v107, 0x0
	v_add3_u32 v105, v105, v106, v107
	s_waitcnt lgkmcnt(0)
	ds_read_b32 v109, v105 offset:256
	ds_read_b32 v110, v105 offset:512
	ds_read_b32 v111, v105 offset:768
	ds_read_b32 v112, v105 offset:1024
	s_waitcnt lgkmcnt(0)
	v_mov_b32_e32 v113, v110
	v_rcp_f32_e32 v114, v113
	v_mul_f32_e32 v109, v109, v113
	v_mul_f32_e32 v111, v111, v114
	v_mul_f32_e32 v112, v112, v114
	ds_write_b32 v105, v109 offset:256
	ds_write_b32 v105, v111 offset:768
	ds_write_b32 v105, v112 offset:1024
	ds_read_b32 v108, v105 offset:1568
	ds_read_b32 v109, v105 offset:1824
	ds_read_b32 v110, v105 offset:2080
	ds_read_b32 v111, v105 offset:2336
	ds_read_b32 v112, v105 offset:2592
	s_waitcnt lgkmcnt(0)
	v_mul_f32_e32 v108, v108, v113
	v_mul_f32_e32 v113, v113, v110
	v_rcp_f32_e32 v114, v113
	v_mul_f32_e32 v109, v109, v113
	v_mul_f32_e32 v111, v111, v114
	v_mul_f32_e32 v112, v112, v114
	ds_write_b32 v105, v108 offset:1568
	ds_write_b32 v105, v109 offset:1824
	ds_write_b32 v105, v113 offset:2080
	ds_write_b32 v105, v111 offset:2336
	ds_write_b32 v105, v112 offset:2592
	ds_read_b32 v108, v105 offset:3136
	ds_read_b32 v109, v105 offset:3392
	ds_read_b32 v110, v105 offset:3648
	ds_read_b32 v111, v105 offset:3904
	ds_read_b32 v112, v105 offset:4160
	s_waitcnt lgkmcnt(0)
	v_mul_f32_e32 v108, v108, v113
	v_mul_f32_e32 v113, v113, v110
	v_rcp_f32_e32 v114, v113
	v_mul_f32_e32 v109, v109, v113
	v_mul_f32_e32 v111, v111, v114
	v_mul_f32_e32 v112, v112, v114
	ds_write_b32 v105, v108 offset:3136
	ds_write_b32 v105, v109 offset:3392
	ds_write_b32 v105, v113 offset:3648
	ds_write_b32 v105, v111 offset:3904
	ds_write_b32 v105, v112 offset:4160
	ds_read_b32 v108, v105 offset:4704
	ds_read_b32 v110, v105 offset:5216
	ds_read_b32 v111, v105 offset:5472
	ds_read_b32 v112, v105 offset:5728
	s_waitcnt lgkmcnt(0)
	v_mul_f32_e32 v108, v108, v113
	v_mul_f32_e32 v113, v113, v110
	v_rcp_f32_e32 v114, v113
	s_nop 0
	v_mul_f32_e32 v111, v111, v114
	v_mul_f32_e32 v112, v112, v114
	ds_write_b32 v105, v108 offset:4704
	ds_write_b32 v105, v113 offset:5216
	ds_write_b32 v105, v111 offset:5472
	ds_write_b32 v105, v112 offset:5728
	ds_read_b32 v109, v105 offset:6528
	ds_read_b32 v110, v105 offset:6784
	ds_read_b32 v111, v105 offset:7040
	ds_read_b32 v112, v105 offset:7296
	s_waitcnt lgkmcnt(0)
	v_mov_b32_e32 v113, v110
	v_rcp_f32_e32 v114, v113
	v_mul_f32_e32 v109, v109, v113
	v_mul_f32_e32 v111, v111, v114
	v_mul_f32_e32 v112, v112, v114
	ds_write_b32 v105, v109 offset:6528
	ds_write_b32 v105, v111 offset:7040
	ds_write_b32 v105, v112 offset:7296
	ds_read_b32 v108, v105 offset:7840
	ds_read_b32 v109, v105 offset:8096
	ds_read_b32 v110, v105 offset:8352
	ds_read_b32 v111, v105 offset:8608
	ds_read_b32 v112, v105 offset:8864
	s_waitcnt lgkmcnt(0)
	v_mul_f32_e32 v108, v108, v113
	v_mul_f32_e32 v113, v113, v110
	v_rcp_f32_e32 v114, v113
	v_mul_f32_e32 v109, v109, v113
	v_mul_f32_e32 v111, v111, v114
	v_mul_f32_e32 v112, v112, v114
	ds_write_b32 v105, v108 offset:7840
	ds_write_b32 v105, v109 offset:8096
	ds_write_b32 v105, v113 offset:8352
	ds_write_b32 v105, v111 offset:8608
	ds_write_b32 v105, v112 offset:8864
	ds_read_b32 v108, v105 offset:9408
	ds_read_b32 v109, v105 offset:9664
	ds_read_b32 v110, v105 offset:9920
	ds_read_b32 v111, v105 offset:10176
	ds_read_b32 v112, v105 offset:10432
	s_waitcnt lgkmcnt(0)
	v_mul_f32_e32 v108, v108, v113
	v_mul_f32_e32 v113, v113, v110
	v_rcp_f32_e32 v114, v113
	v_mul_f32_e32 v109, v109, v113
	v_mul_f32_e32 v111, v111, v114
	v_mul_f32_e32 v112, v112, v114
	ds_write_b32 v105, v108 offset:9408
	ds_write_b32 v105, v109 offset:9664
	ds_write_b32 v105, v113 offset:9920
	ds_write_b32 v105, v111 offset:10176
	ds_write_b32 v105, v112 offset:10432
	ds_read_b32 v108, v105 offset:10976
	ds_read_b32 v110, v105 offset:11488
	ds_read_b32 v111, v105 offset:11744
	ds_read_b32 v112, v105 offset:12000
	s_waitcnt lgkmcnt(0)
	v_mul_f32_e32 v108, v108, v113
	v_mul_f32_e32 v113, v113, v110
	v_rcp_f32_e32 v114, v113
	s_nop 0
	v_mul_f32_e32 v111, v111, v114
	v_mul_f32_e32 v112, v112, v114
	ds_write_b32 v105, v108 offset:10976
	ds_write_b32 v105, v113 offset:11488
	ds_write_b32 v105, v111 offset:11744
	ds_write_b32 v105, v112 offset:12000
	s_mov_b64 exec, s[98:99]
	s_waitcnt lgkmcnt(0)
	s_barrier
; #define MFMA(a, b, c) __builtin_amdgcn_mfma_f32_32x32x16_bf16((a), (b), (c), 0, 0, 0)
; DI float bflo(unsigned u) { return __uint_as_float(u << 16); }
; DI float bfhi(unsigned u) { return __uint_as_float(u & 0xffff0000u); }
; template <int CPL>
; DI void scan_block2(CP p, int layer, int s, int d, int hd, int rowhalf, char* smem) {
;     ...
;     auto stage = [&](int c) {
;       float r4[2][4], k4[2][4], kk4[2][4], v4[2][4];
; #pragma unroll
;       for (int u = 0; u < 2; ++u) {
;         const int sj = 8 * sw + 4 * u + (lane >> 4);
;         r4[u][0] = bflo(raw[u][0].x); r4[u][1] = bfhi(raw[u][0].x); r4[u][2] = bflo(raw[u][0].y); r4[u][3] = bfhi(raw[u][0].y);
;         k4[u][0] = bflo(raw[u][1].x); k4[u][1] = bfhi(raw[u][1].x); k4[u][2] = bflo(raw[u][1].y); k4[u][3] = bfhi(raw[u][1].y);
;         v4[u][0] = bflo(raw[u][2].x); v4[u][1] = bfhi(raw[u][2].x); v4[u][2] = bflo(raw[u][2].y); v4[u][3] = bfhi(raw[u][2].y);
;         *(uint2*)(XL + sj * 72 + 4 * q) = raw[u][3];
;         *(uint2*)(XL + 32 * 72 + sj * 72 + 4 * q) = raw[u][4];
;         const float4 kkw = *(const float4*)(CS + 4 * q);
;         float x0 = k4[u][0] * kkw.x, x1 = k4[u][1] * kkw.y, x2 = k4[u][2] * kkw.z, x3 = k4[u][3] * kkw.w;
;         float ss = sum16(x0 * x0 + x1 * x1 + x2 * x2 + x3 * x3);
;         float inv = __builtin_amdgcn_rsqf(fmaxf(ss, 1e-24f));
;         kk4[u][0] = x0 * inv; kk4[u][1] = x1 * inv; kk4[u][2] = x2 * inv; kk4[u][3] = x3 * inv;
;       }
;       LDS_FENCE();
;       float* OPn = OP + (c & 1) * 32 * 392;
; #pragma unroll
;       for (int mat = 0; mat < 2; ++mat)
; #pragma unroll
;         for (int nt2 = 0; nt2 < 2; ++nt2) {
;           f32x16 acc;
; #pragma unroll
;           for (int r = 0; r < 16; ++r) acc[r] = 0.f;
;           const u16* xb = XL + mat * 32 * 72 + (8 * sw + (l32 & 7)) * 72 + hh * 8;
; #pragma unroll
;           for (int ks = 0; ks < 4; ++ks) acc = MFMA(*(const bf16x8*)(xb + ks * 16), *(const bf16x8*)(WL + (mat * 64 + nt2 * 32 + l32) * 72 + ks * 16 + hh * 8), acc);
; #pragma unroll
;           for (int r = 0; r < 4; ++r) {
;             float x = acc[r] + bias[mat][nt2];
;             float sg = sigmoidf_(x);
;             float val = mat ? sg : __expf(-0.6065306597126334f * sg);
;             OPn[(8 * sw + 4 * hh + r) * 392 + (mat ? 0 : 128) + nt2 * 32 + l32] = val;
;           }
;         }
;       LDS_FENCE();
	v_lshlrev_b32_e32 v2, 2, v2
	v_mov_b32_e32 v3, v1
	v_lshl_add_u64 v[36:37], s[64:65], 0, v[2:3]
	v_mul_u32_u24_e32 v78, 0x90, v46
	v_add_u32_e32 v79, 0x240, v67
	v_add_u32_e32 v80, 0x240, v68
	v_add_u32_e32 v78, v51, v78
	s_cmp_eq_u32 s16, 0
	s_movk_i32 s2, 0x1ff0
	s_cselect_b64 s[74:75], -1, 0
	v_cmp_gt_u32_e64 s[44:45], s2, v50
	v_cmp_eq_u32_e64 s[40:41], 0, v75
	v_mov_b32_e32 v83, v1
	s_and_b64 s[2:3], s[74:75], s[44:45]
	v_cmp_ne_u32_e64 s[42:43], 0, v75
	s_and_b64 s[10:11], s[40:41], s[2:3]
	s_waitcnt vmcnt(6)
	ds_write_b64 v67, v[14:15]
	s_waitcnt vmcnt(5)
	ds_write_b64 v68, v[6:7]
	ds_read_b128 v[2:5], v69
	v_lshlrev_b32_e32 v48, 16, v12
	v_and_b32_e32 v49, 0xffff0000, v12
	v_lshlrev_b32_e32 v46, 16, v13
	v_and_b32_e32 v47, 0xffff0000, v13
	s_waitcnt lgkmcnt(0)
	v_pk_mul_f32 v[2:3], v[2:3], v[48:49]
	v_pk_mul_f32 v[4:5], v[4:5], v[46:47]
	v_pk_mul_f32 v[6:7], v[2:3], v[2:3]
	v_lshlrev_b32_e32 v18, 16, v8
	v_and_b32_e32 v19, 0xffff0000, v8
	v_lshlrev_b32_e32 v20, 16, v9
	v_and_b32_e32 v21, 0xffff0000, v9
	v_pk_mul_f32 v[8:9], v[4:5], v[4:5]
	v_add_f32_e32 v6, v6, v7
	v_add_f32_e32 v6, v6, v8
	v_add_f32_e32 v6, v6, v9
	s_waitcnt vmcnt(1)
	ds_write_b64 v79, v[16:17]
	s_waitcnt vmcnt(0)
	ds_write_b64 v80, v[42:43]
	v_add_f32_dpp v6, v6, v6 row_ror:8 row_mask:0xf bank_mask:0xf bound_ctrl:1
	v_lshlrev_b32_e32 v40, 16, v26
	v_and_b32_e32 v41, 0xffff0000, v26
	v_add_f32_dpp v6, v6, v6 row_ror:4 row_mask:0xf bank_mask:0xf bound_ctrl:1
	v_lshlrev_b32_e32 v38, 16, v27
	v_and_b32_e32 v39, 0xffff0000, v27
	v_add_f32_dpp v6, v6, v6 row_ror:2 row_mask:0xf bank_mask:0xf bound_ctrl:1
	v_lshlrev_b32_e32 v22, 16, v10
	v_and_b32_e32 v23, 0xffff0000, v10
	v_add_f32_dpp v6, v6, v6 row_ror:1 row_mask:0xf bank_mask:0xf bound_ctrl:1
	v_max_f32_e32 v6, 0x179abe15, v6
	v_rsq_f32_e32 v6, v6
	v_lshlrev_b32_e32 v24, 16, v11
	v_and_b32_e32 v25, 0xffff0000, v11
	v_pk_mul_f32 v[26:27], v[2:3], v[6:7] op_sel_hi:[1,0]
	v_pk_mul_f32 v[28:29], v[4:5], v[6:7] op_sel_hi:[1,0]
	ds_read_b128 v[2:5], v69
	s_waitcnt lgkmcnt(0)
	s_waitcnt lgkmcnt(0)
	v_pk_mul_f32 v[42:43], v[2:3], v[40:41]
	v_pk_mul_f32 v[44:45], v[4:5], v[38:39]
	v_pk_mul_f32 v[2:3], v[42:43], v[42:43]
	v_pk_mul_f32 v[4:5], v[44:45], v[44:45]
	v_add_f32_e32 v2, v2, v3
	v_add_f32_e32 v2, v2, v4
	v_add_f32_e32 v2, v2, v5
	s_nop 1
	v_add_f32_dpp v2, v2, v2 row_ror:8 row_mask:0xf bank_mask:0xf bound_ctrl:1
	s_nop 1
	v_add_f32_dpp v2, v2, v2 row_ror:4 row_mask:0xf bank_mask:0xf bound_ctrl:1
	s_nop 1
	v_add_f32_dpp v82, v2, v2 row_ror:2 row_mask:0xf bank_mask:0xf bound_ctrl:1
	ds_read_b128 v[2:5], v62
	ds_read_b128 v[84:87], v62 offset:32
	ds_read_b128 v[6:9], v78
	ds_read_b128 v[88:91], v78 offset:32
	s_waitcnt lgkmcnt(1)
	v_mfma_f32_32x32x16_bf16 v[2:17], v[2:5], v[6:9], 0
	v_mov_b32_dpp v83, v82 row_ror:1 row_mask:0xf bank_mask:0xf
	s_waitcnt lgkmcnt(0)
	v_mfma_f32_32x32x16_bf16 v[2:17], v[84:87], v[88:91], v[2:17]
	ds_read_b128 v[84:87], v62 offset:64
	ds_read_b128 v[88:91], v78 offset:64
	s_waitcnt lgkmcnt(0)
	v_mfma_f32_32x32x16_bf16 v[2:17], v[84:87], v[88:91], v[2:17]
	ds_read_b128 v[84:87], v62 offset:96
	ds_read_b128 v[88:91], v78 offset:96
	s_waitcnt lgkmcnt(0)
	v_mfma_f32_32x32x16_bf16 v[2:17], v[84:87], v[88:91], v[2:17]
	s_nop 11
	v_add_f32_e32 v2, v64, v2
	v_mul_f32_e32 v2, 0xbfb8aa3b, v2
	v_exp_f32_e32 v2, v2
	s_nop 0
	v_add_f32_e32 v2, 1.0, v2
	v_rcp_f32_e32 v2, v2
	s_nop 0
	v_mul_f32_e32 v2, 0xbf1b4598, v2
	v_mul_f32_e32 v2, 0x3fb8aa3b, v2
	v_exp_f32_e32 v2, v2
	ds_write_b32 v59, v2 offset:50688
	v_add_f32_e32 v2, v64, v3
	v_mul_f32_e32 v2, 0xbfb8aa3b, v2
	v_exp_f32_e32 v2, v2
	s_nop 0
	v_add_f32_e32 v2, 1.0, v2
	v_rcp_f32_e32 v2, v2
	s_nop 0
	v_mul_f32_e32 v2, 0xbf1b4598, v2
	v_mul_f32_e32 v2, 0x3fb8aa3b, v2
	v_exp_f32_e32 v2, v2
	ds_write_b32 v66, v2 offset:51744
	v_add_f32_e32 v2, v64, v4
	v_mul_f32_e32 v2, 0xbfb8aa3b, v2
	v_exp_f32_e32 v2, v2
	s_nop 0
	v_add_f32_e32 v2, 1.0, v2
	v_rcp_f32_e32 v2, v2
	s_nop 0
	v_mul_f32_e32 v2, 0xbf1b4598, v2
	v_mul_f32_e32 v2, 0x3fb8aa3b, v2
	v_exp_f32_e32 v2, v2
	ds_write_b32 v66, v2 offset:53312
	v_add_f32_e32 v2, v64, v5
	v_mul_f32_e32 v2, 0xbfb8aa3b, v2
	v_exp_f32_e32 v2, v2
	s_nop 0
	v_add_f32_e32 v2, 1.0, v2
	v_rcp_f32_e32 v2, v2
	s_nop 0
	v_mul_f32_e32 v2, 0xbf1b4598, v2
	v_mul_f32_e32 v2, 0x3fb8aa3b, v2
	v_exp_f32_e32 v2, v2
	ds_write_b32 v66, v2 offset:54880
	ds_read_b128 v[2:5], v62
	ds_read_b128 v[84:87], v62 offset:32
	ds_read_b128 v[6:9], v78 offset:4608
	ds_read_b128 v[88:91], v78 offset:4640
	s_waitcnt lgkmcnt(1)
	v_mfma_f32_32x32x16_bf16 v[2:17], v[2:5], v[6:9], 0
	s_waitcnt lgkmcnt(0)
	v_mfma_f32_32x32x16_bf16 v[2:17], v[84:87], v[88:91], v[2:17]
	ds_read_b128 v[84:87], v62 offset:64
	ds_read_b128 v[88:91], v78 offset:4672
	s_waitcnt lgkmcnt(0)
	v_mfma_f32_32x32x16_bf16 v[2:17], v[84:87], v[88:91], v[2:17]
	ds_read_b128 v[84:87], v62 offset:96
	ds_read_b128 v[88:91], v78 offset:4704
	s_waitcnt lgkmcnt(0)
; template <int CPL>
; DI void scan_block2(CP p, int layer, int s, int d, int hd, int rowhalf, char* smem) {
;     ...
; #pragma unroll
;       for (int mat = 0; mat < 2; ++mat)
; #pragma unroll
;         for (int nt2 = 0; nt2 < 2; ++nt2) {
;           f32x16 acc;
; #pragma unroll
;           for (int r = 0; r < 16; ++r) acc[r] = 0.f;
;           const u16* xb = XL + mat * 32 * 72 + (8 * sw + (l32 & 7)) * 72 + hh * 8;
; #pragma unroll
;           for (int ks = 0; ks < 4; ++ks) acc = MFMA(*(const bf16x8*)(xb + ks * 16), *(const bf16x8*)(WL + (mat * 64 + nt2 * 32 + l32) * 72 + ks * 16 + hh * 8), acc);
; #pragma unroll
;           for (int r = 0; r < 4; ++r) {
;             float x = acc[r] + bias[mat][nt2];
;             float sg = sigmoidf_(x);
;             float val = mat ? sg : __expf(-0.6065306597126334f * sg);
;             OPn[(8 * sw + 4 * hh + r) * 392 + (mat ? 0 : 128) + nt2 * 32 + l32] = val;
;           }
;         }
;       LDS_FENCE();
; #pragma unroll
;       for (int u = 0; u < 2; ++u) {
;         const int sj = 8 * sw + 4 * u + (lane >> 4);
;         const float4 w4 = *(const float4*)(OPn + sj * 392 + 128 + 4 * q);
;         const float4 a4 = *(const float4*)(OPn + sj * 392 + 4 * q);
;         const float4 ka = *(const float4*)(CS + 64 + 4 * q);
;         const float4 brk = *(const float4*)(CS + 128 + 4 * q);
;         const float wv4[4] = {w4.x, w4.y, w4.z, w4.w}, av4[4] = {a4.x, a4.y, a4.z, a4.w};
;         const float kav[4] = {ka.x, ka.y, ka.z, ka.w}, bkv[4] = {brk.x, brk.y, brk.z, brk.w};
;         float bb[4], kd[4];
;         float bs = 0.f;
; #pragma unroll
;         for (int e = 0; e < 4; ++e) {
;           bb[e] = -kk4[u][e] * av4[e];
;           kd[e] = k4[u][e] * (1.f + (av4[e] - 1.f) * kav[e]);
;           bs += r4[u][e] * kd[e] * bkv[e];
;         }
;         bs = sum16(bs);
;         float* o = OPn + sj * 392 + 4 * q;
;         *(float4*)(o) = make_float4(kk4[u][0], kk4[u][1], kk4[u][2], kk4[u][3]);
;         *(float4*)(o + 64) = make_float4(r4[u][0], r4[u][1], r4[u][2], r4[u][3]);
;         *(float4*)(o + 128) = w4;
;         *(float4*)(o + 192) = make_float4(bb[0], bb[1], bb[2], bb[3]);
;         *(float4*)(o + 256) = make_float4(kd[0], kd[1], kd[2], kd[3]);
;         *(float4*)(o + 320) = make_float4(v4[u][0], v4[u][1], v4[u][2], v4[u][3]);
;         if (q == 0) {
;           const int sidx = c * 32 + sj;
	v_mfma_f32_32x32x16_bf16 v[2:17], v[84:87], v[88:91], v[2:17]
	s_nop 11
	v_add_f32_e32 v2, v63, v2
	v_mul_f32_e32 v2, 0xbfb8aa3b, v2
	v_exp_f32_e32 v2, v2
	s_nop 0
	v_add_f32_e32 v2, 1.0, v2
	v_rcp_f32_e32 v2, v2
	s_nop 0
	v_mul_f32_e32 v2, 0xbf1b4598, v2
	v_mul_f32_e32 v2, 0x3fb8aa3b, v2
	v_exp_f32_e32 v2, v2
	ds_write_b32 v59, v2 offset:50816
	v_add_f32_e32 v2, v63, v3
	v_mul_f32_e32 v2, 0xbfb8aa3b, v2
	v_exp_f32_e32 v2, v2
	s_nop 0
	v_add_f32_e32 v2, 1.0, v2
	v_rcp_f32_e32 v2, v2
	s_nop 0
	v_mul_f32_e32 v2, 0xbf1b4598, v2
	v_mul_f32_e32 v2, 0x3fb8aa3b, v2
	v_exp_f32_e32 v2, v2
	ds_write_b32 v65, v2 offset:51744
	v_add_f32_e32 v2, v63, v4
	v_mul_f32_e32 v2, 0xbfb8aa3b, v2
	v_exp_f32_e32 v2, v2
	s_nop 0
	v_add_f32_e32 v2, 1.0, v2
	v_rcp_f32_e32 v2, v2
	s_nop 0
	v_mul_f32_e32 v2, 0xbf1b4598, v2
	v_mul_f32_e32 v2, 0x3fb8aa3b, v2
	v_exp_f32_e32 v2, v2
	ds_write_b32 v65, v2 offset:53312
	v_add_f32_e32 v2, v63, v5
	v_mul_f32_e32 v2, 0xbfb8aa3b, v2
	v_exp_f32_e32 v2, v2
	s_nop 0
	v_add_f32_e32 v2, 1.0, v2
	v_rcp_f32_e32 v2, v2
	s_nop 0
	v_mul_f32_e32 v2, 0xbf1b4598, v2
	v_mul_f32_e32 v2, 0x3fb8aa3b, v2
	v_exp_f32_e32 v2, v2
	ds_write_b32 v65, v2 offset:54880
	ds_read_b128 v[2:5], v62 offset:4608
	ds_read_b128 v[84:87], v62 offset:4640
	ds_read_b128 v[6:9], v78 offset:9216
	ds_read_b128 v[88:91], v78 offset:9248
	s_waitcnt lgkmcnt(1)
	v_mfma_f32_32x32x16_bf16 v[2:17], v[2:5], v[6:9], 0
	s_waitcnt lgkmcnt(0)
	v_mfma_f32_32x32x16_bf16 v[2:17], v[84:87], v[88:91], v[2:17]
	ds_read_b128 v[84:87], v62 offset:4672
	ds_read_b128 v[88:91], v78 offset:9280
	s_waitcnt lgkmcnt(0)
	v_mfma_f32_32x32x16_bf16 v[2:17], v[84:87], v[88:91], v[2:17]
	ds_read_b128 v[84:87], v62 offset:4704
	ds_read_b128 v[88:91], v78 offset:9312
	s_waitcnt lgkmcnt(0)
	v_mfma_f32_32x32x16_bf16 v[2:17], v[84:87], v[88:91], v[2:17]
	s_nop 11
	v_add_f32_e32 v2, v56, v2
	v_mul_f32_e32 v2, 0xbfb8aa3b, v2
	v_exp_f32_e32 v2, v2
	s_nop 0
	v_add_f32_e32 v2, 1.0, v2
	v_rcp_f32_e32 v2, v2
	ds_write_b32 v59, v2 offset:50176
	v_add_f32_e32 v2, v56, v3
	v_mul_f32_e32 v2, 0xbfb8aa3b, v2
	v_exp_f32_e32 v2, v2
	s_nop 0
	v_add_f32_e32 v2, 1.0, v2
	v_rcp_f32_e32 v2, v2
	ds_write_b32 v59, v2 offset:51744
	v_add_f32_e32 v2, v56, v4
	v_mul_f32_e32 v2, 0xbfb8aa3b, v2
	v_exp_f32_e32 v2, v2
	s_nop 0
	v_add_f32_e32 v2, 1.0, v2
	v_rcp_f32_e32 v2, v2
	ds_write_b32 v59, v2 offset:53312
	v_add_f32_e32 v2, v56, v5
	v_mul_f32_e32 v2, 0xbfb8aa3b, v2
	v_exp_f32_e32 v2, v2
	s_nop 0
	v_add_f32_e32 v2, 1.0, v2
	v_rcp_f32_e32 v2, v2
	ds_write_b32 v59, v2 offset:54880
	ds_read_b128 v[2:5], v62 offset:4608
	ds_read_b128 v[84:87], v62 offset:4640
	ds_read_b128 v[6:9], v78 offset:13824
	ds_read_b128 v[88:91], v78 offset:13856
	s_waitcnt lgkmcnt(1)
	v_mfma_f32_32x32x16_bf16 v[2:17], v[2:5], v[6:9], 0
	s_waitcnt lgkmcnt(0)
	v_mfma_f32_32x32x16_bf16 v[2:17], v[84:87], v[88:91], v[2:17]
	ds_read_b128 v[84:87], v62 offset:4672
	ds_read_b128 v[88:91], v78 offset:13888
	s_waitcnt lgkmcnt(0)
	v_mfma_f32_32x32x16_bf16 v[2:17], v[84:87], v[88:91], v[2:17]
	ds_read_b128 v[84:87], v62 offset:4704
	ds_read_b128 v[88:91], v78 offset:13920
	s_waitcnt lgkmcnt(0)
	v_mfma_f32_32x32x16_bf16 v[2:17], v[84:87], v[88:91], v[2:17]
	s_nop 11
	v_add_f32_e32 v2, v55, v2
	v_mul_f32_e32 v2, 0xbfb8aa3b, v2
	v_exp_f32_e32 v2, v2
	s_nop 0
	v_add_f32_e32 v2, 1.0, v2
	v_rcp_f32_e32 v2, v2
	ds_write_b32 v59, v2 offset:50304
	v_add_f32_e32 v2, v55, v3
	v_mul_f32_e32 v2, 0xbfb8aa3b, v2
	v_exp_f32_e32 v2, v2
	s_nop 0
	v_add_f32_e32 v2, 1.0, v2
	v_rcp_f32_e32 v2, v2
	ds_write_b32 v60, v2 offset:51744
	v_add_f32_e32 v2, v55, v4
	v_mul_f32_e32 v2, 0xbfb8aa3b, v2
	v_exp_f32_e32 v2, v2
	s_nop 0
	v_add_f32_e32 v2, 1.0, v2
	v_rcp_f32_e32 v2, v2
	ds_write_b32 v60, v2 offset:53312
	v_add_f32_e32 v2, v55, v5
	v_mul_f32_e32 v2, 0xbfb8aa3b, v2
	v_exp_f32_e32 v2, v2
	s_nop 0
	v_add_f32_e32 v2, 1.0, v2
	v_rcp_f32_e32 v2, v2
	ds_write_b32 v60, v2 offset:54880
	s_waitcnt lgkmcnt(0)
	ds_read_b128 v[2:5], v61
	ds_read_b128 v[10:13], v57 offset:50176
	ds_write_b128 v57, v[22:25] offset:50432
	s_waitcnt lgkmcnt(1)
	v_pk_mul_f32 v[6:7], v[10:11], v[26:27] neg_lo:[0,1] neg_hi:[0,1]
	v_pk_mul_f32 v[8:9], v[12:13], v[28:29] neg_lo:[0,1] neg_hi:[0,1]
	ds_write_b128 v57, v[26:29] offset:50176
	ds_write_b128 v57, v[6:9] offset:50944
	ds_read_b128 v[6:9], v58
	v_pk_add_f32 v[10:11], v[10:11], -1.0 op_sel_hi:[1,0]
	v_pk_add_f32 v[12:13], v[12:13], -1.0 op_sel_hi:[1,0]
	s_waitcnt lgkmcnt(0)
	v_pk_fma_f32 v[10:11], v[10:11], v[6:7], 1.0 op_sel_hi:[1,1,0]
	s_nop 0
	v_pk_mul_f32 v[10:11], v[10:11], v[48:49]
	v_pk_fma_f32 v[12:13], v[12:13], v[8:9], 1.0 op_sel_hi:[1,1,0]
	v_mul_f32_e32 v14, v10, v22
	v_fma_f32 v14, v2, v14, 0
	v_mul_f32_e32 v15, v11, v23
	v_pk_mul_f32 v[12:13], v[12:13], v[46:47]
	v_fmac_f32_e32 v14, v3, v15
	v_mul_f32_e32 v15, v12, v24
	v_mul_f32_e32 v16, v13, v25
	v_fmac_f32_e32 v14, v4, v15
	v_fmac_f32_e32 v14, v5, v16
	v_mov_b32_e32 v15, v1
	ds_write_b128 v57, v[10:13] offset:51200
	ds_write_b128 v57, v[18:21] offset:51456
	v_add_f32_dpp v14, v14, v14 row_ror:8 row_mask:0xf bank_mask:0xf bound_ctrl:1
	s_nop 1
	v_add_f32_dpp v14, v14, v14 row_ror:4 row_mask:0xf bank_mask:0xf bound_ctrl:1
	s_nop 1
	v_add_f32_dpp v14, v14, v14 row_ror:2 row_mask:0xf bank_mask:0xf bound_ctrl:1
	s_nop 1
	v_mov_b32_dpp v15, v14 row_ror:1 row_mask:0xf bank_mask:0xf
	s_and_saveexec_b64 s[2:3], s[10:11]
	s_cbranch_execz .LBB0_196
	v_add_u32_e32 v10, 32, v54
	v_sub_u32_e32 v11, 0x1fef, v54
	v_cndmask_b32_e32 v10, v11, v10, vcc
	v_mov_b32_e32 v11, v1
	v_lshl_add_u64 v[10:11], v[34:35], 0, v[10:11]
	v_lshlrev_b64 v[10:11], 5, v[10:11]
	v_add_f32_e32 v12, v14, v15
	v_lshl_add_u64 v[10:11], v[36:37], 0, v[10:11]
	global_store_dword v[10:11], v12, off

; template <int CPL>
; DI void scan_block2(CP p, int layer, int s, int d, int hd, int rowhalf, char* smem) {
;     ...
;     auto load_raw = [&](int c) {
; #pragma unroll
;       for (int u = 0; u < 2; ++u) {
;         const int sj = 8 * sw + 4 * u + (lane >> 4);
;         const int sidc = min(c * 32 + sj, L - 1);
;         const int tok = d == 0 ? sidc : L - 1 - sidc;
;         const u16* base = p.regB + (size_t)(r0 + tok) * 1952 + 4 * q;
;         raw[u][0] = *(const uint2*)(base + aoff0); raw[u][1] = *(const uint2*)(base + aoff1); raw[u][2] = *(const uint2*)(base + aoff2);
;         raw[u][3] = *(const uint2*)(base + aoff3); raw[u][4] = *(const uint2*)(base + aoff4);
;       }
;     ...
;     for (int c = 0; c < nch; ++c) {
;       if (c + 1 < nch) { stage(c + 1); if (c + 2 < nch) load_raw(c + 2); }
;       if (c >= 1) writeout(c - 1);
;       __syncthreads();
.LBB0_198:
	s_or_b64 exec, exec, s[2:3]
	v_min_u32_e32 v2, 0x1fcf, v54
	v_add_u32_e32 v3, 64, v2
	v_sub_u32_e32 v2, 0x1fcf, v2
	v_cndmask_b32_e32 v2, v2, v3, vcc
	v_lshl_add_u64 v[44:45], s[66:67], 0, v[0:1]
	v_add_u32_e32 v2, s15, v2
	v_mad_i64_i32 v[2:3], s[2:3], v2, s88, v[44:45]
	v_lshl_add_u64 v[4:5], v[2:3], 0, s[76:77]
	s_mov_b32 s73, s77
	v_lshl_add_u64 v[2:3], v[2:3], 0, s[72:73]
	global_load_dwordx2 v[28:29], v[4:5], off
	global_load_dwordx2 v[50:51], v[4:5], off offset:1024
	global_load_dwordx2 v[48:49], v[4:5], off offset:2048
	global_load_dwordx2 v[6:7], v[2:3], off offset:3072
	v_min_u32_e32 v4, 0x1fcb, v54
	v_add_u32_e32 v5, 0x44, v4
	v_sub_u32_e32 v4, 0x1fcb, v4
	v_cndmask_b32_e32 v4, v4, v5, vcc
	v_add_u32_e32 v4, s15, v4
	v_mad_i64_i32 v[4:5], s[2:3], v4, s88, v[44:45]
	v_lshl_add_u64 v[10:11], v[4:5], 0, s[76:77]
	global_load_dwordx2 v[8:9], v[2:3], off offset:3328
	global_load_dwordx2 v[42:43], v[10:11], off
	global_load_dwordx2 v[46:47], v[10:11], off offset:1024
	global_load_dwordx2 v[40:41], v[10:11], off offset:2048
	v_lshl_add_u64 v[2:3], v[4:5], 0, s[72:73]
	global_load_dwordx2 v[4:5], v[2:3], off offset:3072
	s_nop 0
	global_load_dwordx2 v[2:3], v[2:3], off offset:3328
	s_lshl_b32 s2, s14, 1
	s_add_u32 s2, s78, s2
	s_addc_u32 s3, s79, 0
	s_add_u32 s2, s2, s76
	v_lshrrev_b32_e32 v10, 3, v75
	s_addc_u32 s3, s3, 0
	v_add_u32_e32 v83, v53, v52
	v_cmp_eq_u32_e64 s[44:45], s16, v10
	v_lshlrev_b32_e32 v82, 6, v54
	v_lshl_add_u64 v[38:39], s[2:3], 0, v[0:1]
	v_lshlrev_b32_e32 v75, 6, v77
	v_sub_u32_e32 v84, 0x1feb, v83
	s_mov_b32 s17, 0
	s_mov_b32 s16, 0
	s_mov_b64 s[98:99], exec
	s_mov_b64 exec, -1
	v_and_b32_e32 v105, 63, v179
	v_lshlrev_b32_e32 v105, 2, v105
	v_lshrrev_b32_e32 v106, 6, v179
	v_add_u32_e32 v106, -4, v106
	v_mul_u32_u24_e32 v106, 0x3100, v106
	v_mov_b32_e32 v107, 0xc400
	v_add3_u32 v105, v105, v106, v107
	s_waitcnt lgkmcnt(0)
	ds_read_b32 v109, v105 offset:256
	ds_read_b32 v110, v105 offset:512
	ds_read_b32 v111, v105 offset:768
	ds_read_b32 v112, v105 offset:1024
	s_waitcnt lgkmcnt(0)
	v_mov_b32_e32 v113, v110
	v_rcp_f32_e32 v114, v113
	v_mul_f32_e32 v109, v109, v113
	v_mul_f32_e32 v111, v111, v114
	v_mul_f32_e32 v112, v112, v114
	ds_write_b32 v105, v109 offset:256
	ds_write_b32 v105, v111 offset:768
	ds_write_b32 v105, v112 offset:1024
	ds_read_b32 v108, v105 offset:1568
	ds_read_b32 v109, v105 offset:1824
	ds_read_b32 v110, v105 offset:2080
	ds_read_b32 v111, v105 offset:2336
	ds_read_b32 v112, v105 offset:2592
	s_waitcnt lgkmcnt(0)
	v_mul_f32_e32 v108, v108, v113
	v_mul_f32_e32 v113, v113, v110
	v_rcp_f32_e32 v114, v113
	v_mul_f32_e32 v109, v109, v113
	v_mul_f32_e32 v111, v111, v114
	v_mul_f32_e32 v112, v112, v114
	ds_write_b32 v105, v108 offset:1568
	ds_write_b32 v105, v109 offset:1824
	ds_write_b32 v105, v113 offset:2080
	ds_write_b32 v105, v111 offset:2336
	ds_write_b32 v105, v112 offset:2592
	ds_read_b32 v108, v105 offset:3136
	ds_read_b32 v109, v105 offset:3392
	ds_read_b32 v110, v105 offset:3648
	ds_read_b32 v111, v105 offset:3904
	ds_read_b32 v112, v105 offset:4160
	s_waitcnt lgkmcnt(0)
	v_mul_f32_e32 v108, v108, v113
	v_mul_f32_e32 v113, v113, v110
	v_rcp_f32_e32 v114, v113
	v_mul_f32_e32 v109, v109, v113
	v_mul_f32_e32 v111, v111, v114
	v_mul_f32_e32 v112, v112, v114
	ds_write_b32 v105, v108 offset:3136
	ds_write_b32 v105, v109 offset:3392
	ds_write_b32 v105, v113 offset:3648
	ds_write_b32 v105, v111 offset:3904
	ds_write_b32 v105, v112 offset:4160
	ds_read_b32 v108, v105 offset:4704
	ds_read_b32 v110, v105 offset:5216
	ds_read_b32 v111, v105 offset:5472
	ds_read_b32 v112, v105 offset:5728
	s_waitcnt lgkmcnt(0)
	v_mul_f32_e32 v108, v108, v113
	v_mul_f32_e32 v113, v113, v110
	v_rcp_f32_e32 v114, v113
	s_nop 0
	v_mul_f32_e32 v111, v111, v114
	v_mul_f32_e32 v112, v112, v114
	ds_write_b32 v105, v108 offset:4704
	ds_write_b32 v105, v113 offset:5216
	ds_write_b32 v105, v111 offset:5472
	ds_write_b32 v105, v112 offset:5728
	ds_read_b32 v109, v105 offset:6528
	ds_read_b32 v110, v105 offset:6784
	ds_read_b32 v111, v105 offset:7040
	ds_read_b32 v112, v105 offset:7296
	s_waitcnt lgkmcnt(0)
	v_mov_b32_e32 v113, v110
	v_rcp_f32_e32 v114, v113
	v_mul_f32_e32 v109, v109, v113
	v_mul_f32_e32 v111, v111, v114
	v_mul_f32_e32 v112, v112, v114
	ds_write_b32 v105, v109 offset:6528
	ds_write_b32 v105, v111 offset:7040
	ds_write_b32 v105, v112 offset:7296
	ds_read_b32 v108, v105 offset:7840
	ds_read_b32 v109, v105 offset:8096
	ds_read_b32 v110, v105 offset:8352
	ds_read_b32 v111, v105 offset:8608
	ds_read_b32 v112, v105 offset:8864
	s_waitcnt lgkmcnt(0)
	v_mul_f32_e32 v108, v108, v113
	v_mul_f32_e32 v113, v113, v110
	v_rcp_f32_e32 v114, v113
	v_mul_f32_e32 v109, v109, v113
	v_mul_f32_e32 v111, v111, v114
	v_mul_f32_e32 v112, v112, v114
	ds_write_b32 v105, v108 offset:7840
	ds_write_b32 v105, v109 offset:8096
	ds_write_b32 v105, v113 offset:8352
	ds_write_b32 v105, v111 offset:8608
	ds_write_b32 v105, v112 offset:8864
	ds_read_b32 v108, v105 offset:9408
	ds_read_b32 v109, v105 offset:9664
	ds_read_b32 v110, v105 offset:9920
	ds_read_b32 v111, v105 offset:10176
	ds_read_b32 v112, v105 offset:10432
	s_waitcnt lgkmcnt(0)
	v_mul_f32_e32 v108, v108, v113
	v_mul_f32_e32 v113, v113, v110
	v_rcp_f32_e32 v114, v113
	v_mul_f32_e32 v109, v109, v113
	v_mul_f32_e32 v111, v111, v114
	v_mul_f32_e32 v112, v112, v114
	ds_write_b32 v105, v108 offset:9408
	ds_write_b32 v105, v109 offset:9664
	ds_write_b32 v105, v113 offset:9920
	ds_write_b32 v105, v111 offset:10176
	ds_write_b32 v105, v112 offset:10432
	ds_read_b32 v108, v105 offset:10976
	ds_read_b32 v110, v105 offset:11488
	ds_read_b32 v111, v105 offset:11744
	ds_read_b32 v112, v105 offset:12000
	s_waitcnt lgkmcnt(0)
	v_mul_f32_e32 v108, v108, v113
	v_mul_f32_e32 v113, v113, v110
	v_rcp_f32_e32 v114, v113
	s_nop 0
	v_mul_f32_e32 v111, v111, v114
	v_mul_f32_e32 v112, v112, v114
	ds_write_b32 v105, v108 offset:10976
	ds_write_b32 v105, v113 offset:11488
	ds_write_b32 v105, v111 offset:11744
	ds_write_b32 v105, v112 offset:12000
	s_mov_b64 exec, s[98:99]
	s_waitcnt lgkmcnt(0)
	s_barrier
	s_branch .LBB0_200
; template <int CPL>
; DI void scan_block2(CP p, int layer, int s, int d, int hd, int rowhalf, char* smem) {
;     ...
;     for (int c = 0; c < nch; ++c) {
;       if (c + 1 < nch) { stage(c + 1); if (c + 2 < nch) load_raw(c + 2); }
;       if (c >= 1) writeout(c - 1);
;       __syncthreads();
;     }
.LBB0_199:
	s_or_b64 exec, exec, s[2:3]
	s_mov_b64 s[98:99], exec
	s_mov_b64 exec, -1
	v_and_b32_e32 v105, 63, v179
	v_lshlrev_b32_e32 v105, 2, v105
	v_lshrrev_b32_e32 v106, 6, v179
	v_add_u32_e32 v106, -4, v106
	v_mul_u32_u24_e32 v106, 0x3100, v106
	v_mov_b32_e32 v107, 32
	v_and_b32_e32 v107, s16, v107
	v_mul_u32_u24_e32 v107, 0x620, v107
	v_add3_u32 v105, v105, v106, v107
	s_waitcnt lgkmcnt(0)
	ds_read_b32 v109, v105 offset:256
	ds_read_b32 v110, v105 offset:512
	ds_read_b32 v111, v105 offset:768
	ds_read_b32 v112, v105 offset:1024
	s_waitcnt lgkmcnt(0)
	v_mov_b32_e32 v113, v110
	v_rcp_f32_e32 v114, v113
	v_mul_f32_e32 v109, v109, v113
	v_mul_f32_e32 v111, v111, v114
	v_mul_f32_e32 v112, v112, v114
	ds_write_b32 v105, v109 offset:256
	ds_write_b32 v105, v111 offset:768
	ds_write_b32 v105, v112 offset:1024
	ds_read_b32 v108, v105 offset:1568
	ds_read_b32 v109, v105 offset:1824
	ds_read_b32 v110, v105 offset:2080
	ds_read_b32 v111, v105 offset:2336
	ds_read_b32 v112, v105 offset:2592
	s_waitcnt lgkmcnt(0)
	v_mul_f32_e32 v108, v108, v113
	v_mul_f32_e32 v113, v113, v110
	v_rcp_f32_e32 v114, v113
	v_mul_f32_e32 v109, v109, v113
	v_mul_f32_e32 v111, v111, v114
	v_mul_f32_e32 v112, v112, v114
	ds_write_b32 v105, v108 offset:1568
	ds_write_b32 v105, v109 offset:1824
	ds_write_b32 v105, v113 offset:2080
	ds_write_b32 v105, v111 offset:2336
	ds_write_b32 v105, v112 offset:2592
	ds_read_b32 v108, v105 offset:3136
	ds_read_b32 v109, v105 offset:3392
	ds_read_b32 v110, v105 offset:3648
	ds_read_b32 v111, v105 offset:3904
	ds_read_b32 v112, v105 offset:4160
	s_waitcnt lgkmcnt(0)
	v_mul_f32_e32 v108, v108, v113
	v_mul_f32_e32 v113, v113, v110
	v_rcp_f32_e32 v114, v113
	v_mul_f32_e32 v109, v109, v113
	v_mul_f32_e32 v111, v111, v114
	v_mul_f32_e32 v112, v112, v114
	ds_write_b32 v105, v108 offset:3136
	ds_write_b32 v105, v109 offset:3392
	ds_write_b32 v105, v113 offset:3648
	ds_write_b32 v105, v111 offset:3904
	ds_write_b32 v105, v112 offset:4160
	ds_read_b32 v108, v105 offset:4704
	ds_read_b32 v110, v105 offset:5216
	ds_read_b32 v111, v105 offset:5472
	ds_read_b32 v112, v105 offset:5728
	s_waitcnt lgkmcnt(0)
	v_mul_f32_e32 v108, v108, v113
	v_mul_f32_e32 v113, v113, v110
	v_rcp_f32_e32 v114, v113
	s_nop 0
	v_mul_f32_e32 v111, v111, v114
	v_mul_f32_e32 v112, v112, v114
	ds_write_b32 v105, v108 offset:4704
	ds_write_b32 v105, v113 offset:5216
	ds_write_b32 v105, v111 offset:5472
	ds_write_b32 v105, v112 offset:5728
	ds_read_b32 v109, v105 offset:6528
	ds_read_b32 v110, v105 offset:6784
	ds_read_b32 v111, v105 offset:7040
	ds_read_b32 v112, v105 offset:7296
	s_waitcnt lgkmcnt(0)
	v_mov_b32_e32 v113, v110
	v_rcp_f32_e32 v114, v113
	v_mul_f32_e32 v109, v109, v113
	v_mul_f32_e32 v111, v111, v114
	v_mul_f32_e32 v112, v112, v114
	ds_write_b32 v105, v109 offset:6528
	ds_write_b32 v105, v111 offset:7040
	ds_write_b32 v105, v112 offset:7296
	ds_read_b32 v108, v105 offset:7840
	ds_read_b32 v109, v105 offset:8096
	ds_read_b32 v110, v105 offset:8352
	ds_read_b32 v111, v105 offset:8608
	ds_read_b32 v112, v105 offset:8864
	s_waitcnt lgkmcnt(0)
	v_mul_f32_e32 v108, v108, v113
	v_mul_f32_e32 v113, v113, v110
	v_rcp_f32_e32 v114, v113
	v_mul_f32_e32 v109, v109, v113
	v_mul_f32_e32 v111, v111, v114
	v_mul_f32_e32 v112, v112, v114
	ds_write_b32 v105, v108 offset:7840
	ds_write_b32 v105, v109 offset:8096
	ds_write_b32 v105, v113 offset:8352
	ds_write_b32 v105, v111 offset:8608
	ds_write_b32 v105, v112 offset:8864
	ds_read_b32 v108, v105 offset:9408
	ds_read_b32 v109, v105 offset:9664
	ds_read_b32 v110, v105 offset:9920
	ds_read_b32 v111, v105 offset:10176
	ds_read_b32 v112, v105 offset:10432
	s_waitcnt lgkmcnt(0)
	v_mul_f32_e32 v108, v108, v113
	v_mul_f32_e32 v113, v113, v110
	v_rcp_f32_e32 v114, v113
	v_mul_f32_e32 v109, v109, v113
	v_mul_f32_e32 v111, v111, v114
	v_mul_f32_e32 v112, v112, v114
	ds_write_b32 v105, v108 offset:9408
	ds_write_b32 v105, v109 offset:9664
	ds_write_b32 v105, v113 offset:9920
	ds_write_b32 v105, v111 offset:10176
	ds_write_b32 v105, v112 offset:10432
	ds_read_b32 v108, v105 offset:10976
	ds_read_b32 v110, v105 offset:11488
	ds_read_b32 v111, v105 offset:11744
	ds_read_b32 v112, v105 offset:12000
	s_waitcnt lgkmcnt(0)
	v_mul_f32_e32 v108, v108, v113
	v_mul_f32_e32 v113, v113, v110
	v_rcp_f32_e32 v114, v113
	s_nop 0
	v_mul_f32_e32 v111, v111, v114
	v_mul_f32_e32 v112, v112, v114
	ds_write_b32 v105, v108 offset:10976
	ds_write_b32 v105, v113 offset:11488
	ds_write_b32 v105, v111 offset:11744
	ds_write_b32 v105, v112 offset:12000
	s_mov_b64 exec, s[98:99]
	s_add_i32 s16, s16, 32
	s_addk_i32 s17, 0x800
	s_cmpk_eq_i32 s16, 0x1fc0
	v_subrev_u32_e32 v84, 32, v84
	s_waitcnt lgkmcnt(0)
	s_barrier
	s_cbranch_scc1 .LBB0_213

; DI void store4(u16* dst, float a, float b, float c, float d) { *(uint2*)dst = make_uint2(pack2(a, b), pack2(c, d)); }
; template <int CPL>
; DI void scan_block2(CP p, int layer, int s, int d, int hd, int rowhalf, char* smem) {
;     ...
;     auto writeout = [&](int c) {
;       const float* yb = YB + (c & 1) * 2048;
; #pragma unroll
;       for (int u = 0; u < 2; ++u) {
;         const int sj = 8 * sw + 4 * u + (lane >> 4);
;         const int sidx = c * 32 + sj;
;         const bool mine = CPL == 16 ? true : ((q >> 3) == rowhalf);
;         if (sidx < L && mine) {
;           const int tok = d == 0 ? sidx : L - 1 - sidx;
;           const float4 yv = *(const float4*)(yb + sj * 64 + 4 * q);
;           store4((u16*)p.out + (size_t)(r0 + tok) * 1024 + d * 512 + hd * 64 + 4 * q, yv.x, yv.y, yv.z, yv.w);
;         }
;       }
;     };
;     load_raw(0);
;     stage(0);
;     if (nch > 1) load_raw(1);
;     __syncthreads();
;     for (int c = 0; c < nch; ++c) {
;       if (c + 1 < nch) { stage(c + 1); if (c + 2 < nch) load_raw(c + 2); }
;       if (c >= 1) writeout(c - 1);
;       __syncthreads();
;     }
;     writeout(nch - 1);
.LBB0_223:
	s_or_b64 exec, exec, s[2:3]
	v_cmp_gt_i32_e64 s[40:41], 48, v54
	s_and_b64 s[10:11], s[44:45], s[40:41]
	s_mov_b64 s[98:99], exec
	s_mov_b64 exec, -1
	v_and_b32_e32 v105, 63, v179
	v_lshlrev_b32_e32 v105, 2, v105
	v_lshrrev_b32_e32 v106, 6, v179
	v_add_u32_e32 v106, -4, v106
	v_mul_u32_u24_e32 v106, 0x3100, v106
	v_mov_b32_e32 v107, 0x0
	v_add3_u32 v105, v105, v106, v107
	s_waitcnt lgkmcnt(0)
	ds_read_b32 v109, v105 offset:256
	ds_read_b32 v110, v105 offset:512
	ds_read_b32 v111, v105 offset:768
	ds_read_b32 v112, v105 offset:1024
	s_waitcnt lgkmcnt(0)
	v_mov_b32_e32 v113, v110
	v_rcp_f32_e32 v114, v113
	v_mul_f32_e32 v109, v109, v113
	v_mul_f32_e32 v111, v111, v114
	v_mul_f32_e32 v112, v112, v114
	ds_write_b32 v105, v109 offset:256
	ds_write_b32 v105, v111 offset:768
	ds_write_b32 v105, v112 offset:1024
	ds_read_b32 v108, v105 offset:1568
	ds_read_b32 v109, v105 offset:1824
	ds_read_b32 v110, v105 offset:2080
	ds_read_b32 v111, v105 offset:2336
	ds_read_b32 v112, v105 offset:2592
	s_waitcnt lgkmcnt(0)
	v_mul_f32_e32 v108, v108, v113
	v_mul_f32_e32 v113, v113, v110
	v_rcp_f32_e32 v114, v113
	v_mul_f32_e32 v109, v109, v113
	v_mul_f32_e32 v111, v111, v114
	v_mul_f32_e32 v112, v112, v114
	ds_write_b32 v105, v108 offset:1568
	ds_write_b32 v105, v109 offset:1824
	ds_write_b32 v105, v113 offset:2080
	ds_write_b32 v105, v111 offset:2336
	ds_write_b32 v105, v112 offset:2592
	ds_read_b32 v108, v105 offset:3136
	ds_read_b32 v109, v105 offset:3392
	ds_read_b32 v110, v105 offset:3648
	ds_read_b32 v111, v105 offset:3904
	ds_read_b32 v112, v105 offset:4160
	s_waitcnt lgkmcnt(0)
	v_mul_f32_e32 v108, v108, v113
	v_mul_f32_e32 v113, v113, v110
	v_rcp_f32_e32 v114, v113
	v_mul_f32_e32 v109, v109, v113
	v_mul_f32_e32 v111, v111, v114
	v_mul_f32_e32 v112, v112, v114
	ds_write_b32 v105, v108 offset:3136
	ds_write_b32 v105, v109 offset:3392
	ds_write_b32 v105, v113 offset:3648
	ds_write_b32 v105, v111 offset:3904
	ds_write_b32 v105, v112 offset:4160
	ds_read_b32 v108, v105 offset:4704
	ds_read_b32 v110, v105 offset:5216
	ds_read_b32 v111, v105 offset:5472
	ds_read_b32 v112, v105 offset:5728
	s_waitcnt lgkmcnt(0)
	v_mul_f32_e32 v108, v108, v113
	v_mul_f32_e32 v113, v113, v110
	v_rcp_f32_e32 v114, v113
	s_nop 0
	v_mul_f32_e32 v111, v111, v114
	v_mul_f32_e32 v112, v112, v114
	ds_write_b32 v105, v108 offset:4704
	ds_write_b32 v105, v113 offset:5216
	ds_write_b32 v105, v111 offset:5472
	ds_write_b32 v105, v112 offset:5728
	ds_read_b32 v109, v105 offset:6528
	ds_read_b32 v110, v105 offset:6784
	ds_read_b32 v111, v105 offset:7040
	ds_read_b32 v112, v105 offset:7296
	s_waitcnt lgkmcnt(0)
	v_mov_b32_e32 v113, v110
	v_rcp_f32_e32 v114, v113
	v_mul_f32_e32 v109, v109, v113
	v_mul_f32_e32 v111, v111, v114
	v_mul_f32_e32 v112, v112, v114
	ds_write_b32 v105, v109 offset:6528
	ds_write_b32 v105, v111 offset:7040
	ds_write_b32 v105, v112 offset:7296
	ds_read_b32 v108, v105 offset:7840
	ds_read_b32 v109, v105 offset:8096
	ds_read_b32 v110, v105 offset:8352
	ds_read_b32 v111, v105 offset:8608
	ds_read_b32 v112, v105 offset:8864
	s_waitcnt lgkmcnt(0)
	v_mul_f32_e32 v108, v108, v113
	v_mul_f32_e32 v113, v113, v110
	v_rcp_f32_e32 v114, v113
	v_mul_f32_e32 v109, v109, v113
	v_mul_f32_e32 v111, v111, v114
	v_mul_f32_e32 v112, v112, v114
	ds_write_b32 v105, v108 offset:7840
	ds_write_b32 v105, v109 offset:8096
	ds_write_b32 v105, v113 offset:8352
	ds_write_b32 v105, v111 offset:8608
	ds_write_b32 v105, v112 offset:8864
	ds_read_b32 v108, v105 offset:9408
	ds_read_b32 v109, v105 offset:9664
	ds_read_b32 v110, v105 offset:9920
	ds_read_b32 v111, v105 offset:10176
	ds_read_b32 v112, v105 offset:10432
	s_waitcnt lgkmcnt(0)
	v_mul_f32_e32 v108, v108, v113
	v_mul_f32_e32 v113, v113, v110
	v_rcp_f32_e32 v114, v113
	v_mul_f32_e32 v109, v109, v113
	v_mul_f32_e32 v111, v111, v114
	v_mul_f32_e32 v112, v112, v114
	ds_write_b32 v105, v108 offset:9408
	ds_write_b32 v105, v109 offset:9664
	ds_write_b32 v105, v113 offset:9920
	ds_write_b32 v105, v111 offset:10176
	ds_write_b32 v105, v112 offset:10432
	ds_read_b32 v108, v105 offset:10976
	ds_read_b32 v110, v105 offset:11488
	ds_read_b32 v111, v105 offset:11744
	ds_read_b32 v112, v105 offset:12000
	s_waitcnt lgkmcnt(0)
	v_mul_f32_e32 v108, v108, v113
	v_mul_f32_e32 v113, v113, v110
	v_rcp_f32_e32 v114, v113
	s_nop 0
	v_mul_f32_e32 v111, v111, v114
	v_mul_f32_e32 v112, v112, v114
	ds_write_b32 v105, v108 offset:10976
	ds_write_b32 v105, v113 offset:11488
	ds_write_b32 v105, v111 offset:11744
	ds_write_b32 v105, v112 offset:12000
	s_mov_b64 exec, s[98:99]
	s_waitcnt lgkmcnt(0)
	s_barrier
	s_and_saveexec_b64 s[2:3], s[10:11]
	s_cbranch_execz .LBB0_225
	v_add_u32_e32 v5, 0x1fe0, v54
	v_sub_u32_e32 v6, 47, v54
	v_readlane_b32 s10, v252, 31
	v_cndmask_b32_e32 v5, v6, v5, vcc
	v_add_u32_e32 v10, s15, v5
	v_add3_u32 v6, s10, v4, v2
	ds_read_b128 v[6:9], v6
	v_ashrrev_i32_e32 v11, 31, v10
	v_lshlrev_b64 v[10:11], 11, v[10:11]
	v_lshl_add_u64 v[10:11], v[38:39], 0, v[10:11]
	s_waitcnt lgkmcnt(0)
	v_cvt_pk_bf16_f32 v6, v6, v7
	v_cvt_pk_bf16_f32 v7, v8, v9
	global_store_dwordx2 v[10:11], v[6:7], off

; DI void attn_item(CP p, int s, int hd, int qb, char* smem, bool dostore = true) {
;     ...
;   auto ldc = [&](int kt, int c) -> uint4 {
;     uint4 z = make_uint4(0, 0, 0, 0);
;     if (c < 768) {
;       int key = c / 12, cc = c - key * 12, kpos = kt * 64 + key;
;       if (kpos >= L) return z;
;       const u16* src = cc < 8 ? p.kn + (size_t)(r0 + kpos) * 512 + hd * 64 + cc * 8 : KR + (size_t)(r0 + kpos) * 32 + (cc - 8) * 8;
;       return *(const uint4*)src;
;     } else {
;       int c2 = c - 768, dv = c2 >> 3, kc = c2 & 7, kp0 = kt * 64 + kc * 8;
;       if (kp0 >= L) return z;
;       return *(const uint4*)(vtb + (size_t)dv * L + kp0);
;     }
;     ...
;   for (int kt = 0; kt < nt; ++kt) {
;     const int buf = kt & 1;
;     if (kt + 1 < nt) { rg[0] = ldc(kt + 1, tid); rg[1] = ldc(kt + 1, tid + 512); if (tid < 256) rg[2] = ldc(kt + 1, tid + 1024); }
.LBB0_292:
	s_cmp_lt_u32 s17, 0x80
	s_cbranch_scc1 .Lattn_slow
	s_cmp_eq_u32 s66, 2
	s_cbranch_scc0 .Lattn_h1
	s_add_i32 s17, s17, 64
	s_branch .Lattn_slow
.Lattn_h1:
	s_cmp_eq_u32 s66, 1
	s_cbranch_scc1 .Lattn_compute
	s_cmp_eq_u32 s17, 0x80
	s_cbranch_scc0 .Lattn_fast1
	v_lshl_add_u64 v[200:201], v[200:201], 0, v[206:207]
	v_lshl_add_u64 v[202:203], v[202:203], 0, v[208:209]
	v_lshl_add_u64 v[204:205], v[204:205], 0, v[210:211]
	global_load_dwordx4 v[164:167], v[200:201], off
	global_load_dwordx4 v[168:171], v[202:203], off
	s_and_saveexec_b64 s[54:55], s[42:43]
	s_nop 0
	global_load_dwordx4 v[172:175], v[204:205], off
	s_or_b64 exec, exec, s[54:55]
.Lattn_fast1:
	v_lshl_add_u64 v[200:201], v[200:201], 0, v[206:207]
	v_lshl_add_u64 v[202:203], v[202:203], 0, v[208:209]
	v_lshl_add_u64 v[204:205], v[204:205], 0, v[210:211]
	s_bitcmp1_b32 s17, 6
	s_cbranch_scc1 .Lattn_ldB
	global_load_dwordx4 v[2:5], v[200:201], off
	global_load_dwordx4 v[6:9], v[202:203], off
	s_and_saveexec_b64 s[54:55], s[42:43]
	s_nop 0
	global_load_dwordx4 v[104:107], v[204:205], off
	s_or_b64 exec, exec, s[54:55]
	s_branch .Lattn_compute
.Lattn_ldB:
	global_load_dwordx4 v[164:167], v[200:201], off
	global_load_dwordx4 v[168:171], v[202:203], off
	s_and_saveexec_b64 s[54:55], s[42:43]
	s_nop 0
	global_load_dwordx4 v[172:175], v[204:205], off
	s_or_b64 exec, exec, s[54:55]
	s_branch .Lattn_compute

; #define MFMA(a, b, c) __builtin_amdgcn_mfma_f32_32x32x16_bf16((a), (b), (c), 0, 0, 0)
; DI void attn_item(CP p, int s, int hd, int qb, char* smem, bool dostore = true) {
;     ...
;     if (wvalid) {
;       f32x16 st[2];
; #pragma unroll
;       for (int t = 0; t < 2; ++t) {
; #pragma unroll
;         for (int r = 0; r < 16; ++r) st[t][r] = 0.f;
;         const u16* kb = Ks + (buf * 64 + t * 32 + l32) * 104 + hh * 8;
; #pragma unroll
;         for (int ks = 0; ks < 6; ++ks) st[t] = MFMA(*(const bf16x8*)(kb + ks * 16), qf[ks], st[t]);
;       }
.Lattn_compute:
	s_cmp_eq_u32 s66, 2
	s_cbranch_scc0 .Lattn_c1
	s_add_i32 s17, s17, 0xffffffc0

; #define MFMA(a, b, c) __builtin_amdgcn_mfma_f32_32x32x16_bf16((a), (b), (c), 0, 0, 0)
; DI int crow(int reg, int h) { return (reg & 3) + 8 * (reg >> 2) + 4 * h; }
; DI void attn_item(CP p, int s, int hd, int qb, char* smem, bool dostore = true) {
;     ...
; #pragma unroll
;       for (int t = 0; t < 2; ++t) {
; #pragma unroll
;         for (int r = 0; r < 16; ++r) st[t][r] = 0.f;
;         const u16* kb = Ks + (buf * 64 + t * 32 + l32) * 104 + hh * 8;
; #pragma unroll
;         for (int ks = 0; ks < 6; ++ks) st[t] = MFMA(*(const bf16x8*)(kb + ks * 16), qf[ks], st[t]);
;       }
;       if (kt == nt - 1) {
; #pragma unroll
;         for (int t = 0; t < 2; ++t)
; #pragma unroll
;           for (int r = 0; r < 16; ++r) if (kt * 64 + t * 32 + crow(r, hh) >= L) st[t][r] = -1e30f;
;       }
;       float mx = -1e30f;
; #pragma unroll
;       for (int t = 0; t < 2; ++t)
; #pragma unroll
;         for (int r = 0; r < 16; ++r) mx = fmaxf(mx, st[t][r]);
;       mx = fmaxf(mx, __shfl_xor(mx, 32));
.LBB0_321:
	v_or_b32_e32 v11, s58, v133
	s_movk_i32 s54, 0xd0
	v_mad_u32_u24 v12, v11, s54, v136
	s_mov_b32 s54, 0xf149f2ca
	v_lshlrev_b32_e32 v162, 6, v11
	ds_read_b128 v[48:51], v12
	ds_read_b128 v[52:55], v12 offset:32
	ds_read_b128 v[212:215], v12 offset:64
	ds_read_b128 v[216:219], v12 offset:96
	ds_read_b128 v[220:223], v12 offset:128
	ds_read_b128 v[224:227], v12 offset:160
	ds_read_b128 v[228:231], v12 offset:6656
	ds_read_b128 v[232:235], v12 offset:6688
	ds_read_b128 v[240:243], v12 offset:6720
	ds_read_b128 v[244:247], v12 offset:6752
	ds_read_b128 v[248:251], v12 offset:6784
	ds_read_b128 v[152:155], v12 offset:6816
	v_and_b32_e32 v14, 64, v183
	v_xor_b32_e32 v10, 32, v183
	v_add_u32_e32 v14, 64, v14
	v_lshlrev_b32_e32 v11, 6, v11
	v_add_u32_e32 v13, 0x1a00, v12
	v_sub_u32_e32 v163, v12, v162
	v_or_b32_e32 v162, 0x800, v162
	v_sub_u32_e32 v162, v13, v162
	s_waitcnt lgkmcnt(11)
	v_mfma_f32_32x32x16_bf16 v[64:79], v[48:51], v[100:103], 0
	s_waitcnt lgkmcnt(10)
	v_mfma_f32_32x32x16_bf16 v[64:79], v[52:55], v[96:99], v[64:79]
	s_waitcnt lgkmcnt(9)
	v_mfma_f32_32x32x16_bf16 v[64:79], v[212:215], v[92:95], v[64:79]
	s_waitcnt lgkmcnt(8)
	v_mfma_f32_32x32x16_bf16 v[64:79], v[216:219], v[88:91], v[64:79]
	s_waitcnt lgkmcnt(7)
	v_mfma_f32_32x32x16_bf16 v[64:79], v[220:223], v[84:87], v[64:79]
	s_waitcnt lgkmcnt(6)
	v_mfma_f32_32x32x16_bf16 v[64:79], v[224:227], v[80:83], v[64:79]
	ds_read_b128 v[212:215], v163 offset:26624
	ds_read_b128 v[216:219], v163 offset:26656
	ds_read_b128 v[220:223], v163 offset:26688
	ds_read_b128 v[224:227], v163 offset:26720
	s_waitcnt lgkmcnt(9)
	v_mfma_f32_32x32x16_bf16 v[48:63], v[228:231], v[100:103], 0
	ds_read_b128 v[228:231], v162 offset:26624
	s_waitcnt lgkmcnt(9)
	v_mfma_f32_32x32x16_bf16 v[48:63], v[232:235], v[96:99], v[48:63]
	ds_read_b128 v[232:235], v162 offset:26656
	s_nop 1
	v_max3_f32 v0, v64, s54, v65
	v_max3_f32 v0, v0, v66, v67
	v_max3_f32 v0, v0, v68, v69
	v_max3_f32 v0, v0, v70, v71
	v_max3_f32 v0, v0, v72, v73
	v_max3_f32 v0, v0, v74, v75
	v_max3_f32 v0, v0, v76, v77
	v_max3_f32 v0, v0, v78, v79
	v_cmp_lt_i32_e64 s[54:55], v10, v14
	s_nop 1
	v_cndmask_b32_e64 v10, v183, v10, s[54:55]
	v_lshlrev_b32_e32 v10, 2, v10
	s_waitcnt lgkmcnt(9)
	v_mfma_f32_32x32x16_bf16 v[48:63], v[240:243], v[92:95], v[48:63]
	ds_read_b128 v[240:243], v162 offset:26688
	s_waitcnt lgkmcnt(9)
	v_mfma_f32_32x32x16_bf16 v[48:63], v[244:247], v[88:91], v[48:63]
	ds_read_b128 v[244:247], v162 offset:26720
	s_waitcnt lgkmcnt(9)
	v_mfma_f32_32x32x16_bf16 v[48:63], v[248:251], v[84:87], v[48:63]
	s_waitcnt lgkmcnt(8)
	v_mfma_f32_32x32x16_bf16 v[48:63], v[152:155], v[80:83], v[48:63]
	s_nop 11
	v_max3_f32 v0, v0, v48, v49
	v_max3_f32 v0, v0, v50, v51
	v_max3_f32 v0, v0, v52, v53
	v_max3_f32 v0, v0, v54, v55
	v_max3_f32 v0, v0, v56, v57
	v_max3_f32 v0, v0, v58, v59
	v_max3_f32 v0, v0, v60, v61
	v_max3_f32 v0, v0, v62, v63
	ds_bpermute_b32 v10, v10, v0
	s_waitcnt lgkmcnt(0)
; #define MFMA(a, b, c) __builtin_amdgcn_mfma_f32_32x32x16_bf16((a), (b), (c), 0, 0, 0)
; DI unsigned pack2(float a, float b) { fl2_t f; f.x = a; f.y = b; bf16x2_t r = __builtin_convertvector(f, bf16x2_t); return __builtin_bit_cast(unsigned, r); }
; DI void attn_item(CP p, int s, int hd, int qb, char* smem, bool dostore = true) {
;     ...
;       const float mnew = fmaxf(mrun, mx);
;       const float alpha = __builtin_amdgcn_exp2f(mrun - mnew);
;       float ls = 0.f;
; #pragma unroll
;       for (int t = 0; t < 2; ++t)
; #pragma unroll
;         for (int r = 0; r < 16; ++r) { float pv = __builtin_amdgcn_exp2f(st[t][r] - mnew); st[t][r] = pv; ls += pv; }
;       lrun = lrun * alpha + ls; mrun = mnew;
; #pragma unroll
;       for (int u = 0; u < 2; ++u)
; #pragma unroll
;         for (int r = 0; r < 16; ++r) o[u][r] *= alpha;
; #pragma unroll
;       for (int t = 0; t < 2; ++t)
; #pragma unroll
;         for (int s2 = 0; s2 < 2; ++s2) {
;           uint4 pk;
;           pk.x = pack2(st[t][8 * s2 + 0], st[t][8 * s2 + 1]); pk.y = pack2(st[t][8 * s2 + 2], st[t][8 * s2 + 3]);
;           pk.z = pack2(st[t][8 * s2 + 4], st[t][8 * s2 + 5]); pk.w = pack2(st[t][8 * s2 + 6], st[t][8 * s2 + 7]);
;           bf16x8 pf = __builtin_bit_cast(bf16x8, pk);
; #pragma unroll
;           for (int u = 0; u < 2; ++u) {
;             bf16x8 vf = *(const bf16x8*)(Vs + (buf * 64 + u * 32 + l32) * 72 + t * 32 + s2 * 16 + hh * 8);
;             o[u] = MFMA(vf, pf, o[u]);
;           }
;         }
;     ...
;     if (kt + 1 < nt) { stc(buf ^ 1, tid, rg[0]); stc(buf ^ 1, tid + 512, rg[1]); if (tid < 256) stc(buf ^ 1, tid + 1024, rg[2]); }
	v_max3_f32 v10, v150, v0, v10
	v_sub_f32_e32 v14, v64, v10
	v_exp_f32_e32 v14, v14
	v_sub_f32_e32 v64, v65, v10
	v_exp_f32_e32 v64, v64
	v_sub_f32_e32 v65, v66, v10
	v_exp_f32_e32 v65, v65
	v_sub_f32_e32 v66, v67, v10
	v_exp_f32_e32 v66, v66
	v_sub_f32_e32 v67, v68, v10
	v_add_f32_e32 v15, 0, v14
	v_exp_f32_e32 v67, v67
	v_sub_f32_e32 v68, v69, v10
	v_add_f32_e32 v15, v64, v15
	v_exp_f32_e32 v68, v68
	v_sub_f32_e32 v69, v70, v10
	v_add_f32_e32 v15, v65, v15
	v_exp_f32_e32 v69, v69
	v_sub_f32_e32 v70, v71, v10
	v_add_f32_e32 v15, v66, v15
	v_exp_f32_e32 v70, v70
	v_sub_f32_e32 v71, v72, v10
	v_add_f32_e32 v15, v67, v15
	v_exp_f32_e32 v71, v71
	v_sub_f32_e32 v72, v73, v10
	v_add_f32_e32 v15, v68, v15
	v_exp_f32_e32 v72, v72
	v_sub_f32_e32 v73, v74, v10
	v_add_f32_e32 v15, v69, v15
	v_exp_f32_e32 v73, v73
	v_sub_f32_e32 v74, v75, v10
	v_add_f32_e32 v15, v70, v15
	v_exp_f32_e32 v74, v74
	v_sub_f32_e32 v75, v76, v10
	v_sub_f32_e32 v48, v48, v10
	v_add_f32_e32 v15, v71, v15
	v_exp_f32_e32 v75, v75
	v_sub_f32_e32 v76, v77, v10
	v_sub_f32_e32 v77, v78, v10
	v_sub_f32_e32 v78, v79, v10
	v_exp_f32_e32 v79, v48
	v_sub_f32_e32 v48, v49, v10
	v_sub_f32_e32 v0, v150, v10
	v_add_f32_e32 v15, v72, v15
	v_exp_f32_e32 v76, v76
	v_exp_f32_e32 v150, v48
	v_sub_f32_e32 v48, v50, v10
	v_add_f32_e32 v15, v73, v15
	v_exp_f32_e32 v77, v77
	v_exp_f32_e32 v151, v48
	v_sub_f32_e32 v48, v51, v10
	v_add_f32_e32 v15, v74, v15
	v_exp_f32_e32 v78, v78
	v_exp_f32_e32 v152, v48
	v_sub_f32_e32 v48, v52, v10
	v_add_f32_e32 v15, v75, v15
	v_exp_f32_e32 v153, v48
	v_sub_f32_e32 v48, v53, v10
	v_add_f32_e32 v15, v76, v15
	v_exp_f32_e32 v154, v48
	v_sub_f32_e32 v48, v54, v10
	v_add_f32_e32 v15, v77, v15
	v_exp_f32_e32 v155, v48
	v_sub_f32_e32 v48, v55, v10
	v_add_f32_e32 v15, v78, v15
	v_exp_f32_e32 v156, v48
	v_sub_f32_e32 v48, v56, v10
	v_exp_f32_e32 v157, v48
	v_sub_f32_e32 v48, v57, v10
	v_add_f32_e32 v15, v79, v15
	v_exp_f32_e32 v158, v48
	v_sub_f32_e32 v48, v58, v10
	v_add_f32_e32 v15, v150, v15
	v_exp_f32_e32 v159, v48
	v_sub_f32_e32 v48, v59, v10
	v_add_f32_e32 v15, v151, v15
	v_exp_f32_e32 v160, v48
	v_sub_f32_e32 v48, v60, v10
	v_add_f32_e32 v15, v152, v15
	v_exp_f32_e32 v60, v48
	v_sub_f32_e32 v48, v61, v10
	v_add_f32_e32 v15, v153, v15
	v_exp_f32_e32 v61, v48
	v_sub_f32_e32 v48, v62, v10
	v_add_f32_e32 v15, v154, v15
	v_exp_f32_e32 v62, v48
	v_sub_f32_e32 v48, v63, v10
	v_add_f32_e32 v15, v155, v15
	v_exp_f32_e32 v63, v48
	v_exp_f32_e32 v0, v0
	v_add_f32_e32 v15, v156, v15
	v_cvt_pk_bf16_f32 v48, v14, v64
	v_sub_u32_e32 v64, v12, v11
	v_add_f32_e32 v15, v157, v15
	v_add_f32_e32 v15, v158, v15
	v_add_f32_e32 v15, v159, v15
	v_pk_mul_f32 v[46:47], v[46:47], v[0:1] op_sel_hi:[1,0]
	v_pk_mul_f32 v[44:45], v[44:45], v[0:1] op_sel_hi:[1,0]
	v_pk_mul_f32 v[42:43], v[42:43], v[0:1] op_sel_hi:[1,0]
	v_pk_mul_f32 v[40:41], v[40:41], v[0:1] op_sel_hi:[1,0]
	v_pk_mul_f32 v[38:39], v[38:39], v[0:1] op_sel_hi:[1,0]
	v_pk_mul_f32 v[36:37], v[36:37], v[0:1] op_sel_hi:[1,0]
	v_pk_mul_f32 v[34:35], v[34:35], v[0:1] op_sel_hi:[1,0]
	v_pk_mul_f32 v[32:33], v[32:33], v[0:1] op_sel_hi:[1,0]
	v_add_f32_e32 v15, v160, v15
	v_cvt_pk_bf16_f32 v49, v65, v66
	v_cvt_pk_bf16_f32 v50, v67, v68
	v_cvt_pk_bf16_f32 v51, v69, v70
	v_add_f32_e32 v15, v60, v15
	v_add_f32_e32 v15, v61, v15
	v_mfma_f32_32x32x16_bf16 v[32:47], v[212:215], v[48:51], v[32:47]
	v_or_b32_e32 v11, 0x800, v11
	v_add_f32_e32 v15, v62, v15
	v_sub_u32_e32 v11, v13, v11
	v_add_f32_e32 v161, v63, v15
	v_pk_mul_f32 v[30:31], v[30:31], v[0:1] op_sel_hi:[1,0]
	v_pk_mul_f32 v[28:29], v[28:29], v[0:1] op_sel_hi:[1,0]
	v_pk_mul_f32 v[26:27], v[26:27], v[0:1] op_sel_hi:[1,0]
	v_pk_mul_f32 v[24:25], v[24:25], v[0:1] op_sel_hi:[1,0]
	v_pk_mul_f32 v[22:23], v[22:23], v[0:1] op_sel_hi:[1,0]
	v_pk_mul_f32 v[20:21], v[20:21], v[0:1] op_sel_hi:[1,0]
	v_pk_mul_f32 v[18:19], v[18:19], v[0:1] op_sel_hi:[1,0]
	v_pk_mul_f32 v[16:17], v[16:17], v[0:1] op_sel_hi:[1,0]
	v_fmac_f32_e32 v161, v131, v0
	v_mov_b32_e32 v131, v161
	v_mfma_f32_32x32x16_bf16 v[16:31], v[228:231], v[48:51], v[16:31]
	v_cvt_pk_bf16_f32 v12, v71, v72
	v_cvt_pk_bf16_f32 v13, v73, v74
	v_cvt_pk_bf16_f32 v14, v75, v76
	v_cvt_pk_bf16_f32 v15, v77, v78
	s_nop 1
	v_mfma_f32_32x32x16_bf16 v[32:47], v[216:219], v[12:15], v[32:47]
	v_mfma_f32_32x32x16_bf16 v[16:31], v[232:235], v[12:15], v[16:31]
	v_cvt_pk_bf16_f32 v12, v79, v150
	v_cvt_pk_bf16_f32 v13, v151, v152
	v_cvt_pk_bf16_f32 v14, v153, v154
	v_cvt_pk_bf16_f32 v15, v155, v156
	v_mov_b32_e32 v150, v10
	s_nop 0
	v_mfma_f32_32x32x16_bf16 v[32:47], v[220:223], v[12:15], v[32:47]
	v_mfma_f32_32x32x16_bf16 v[16:31], v[240:243], v[12:15], v[16:31]
	v_cvt_pk_bf16_f32 v12, v157, v158
	v_cvt_pk_bf16_f32 v13, v159, v160
	v_cvt_pk_bf16_f32 v14, v60, v61
	v_cvt_pk_bf16_f32 v15, v62, v63
	s_nop 1
	v_mfma_f32_32x32x16_bf16 v[32:47], v[224:227], v[12:15], v[32:47]
	v_mfma_f32_32x32x16_bf16 v[16:31], v[244:247], v[12:15], v[16:31]
.LBB0_322:
	s_or_b64 exec, exec, s[56:57]
	s_xor_b32 s56, s58, 64
	v_add_u32_e32 v0, s56, v137
	v_mad_u64_u32 v[10:11], s[54:55], v0, v138, v[128:129]
	v_add_u32_e32 v0, s56, v139
	s_cmp_lt_u32 s17, 0x80
	s_cbranch_scc1 .Lattn_wA0
	s_cmp_lt_u32 s66, 3
	s_cbranch_scc1 .Lattn_wlast
	s_cmp_lg_u64 s[42:43], 0
	s_cbranch_scc1 .Lattn_w3
	s_waitcnt vmcnt(2)
	s_branch .Lattn_wsel

; DI void attn_item(CP p, int s, int hd, int qb, char* smem, bool dostore = true) {
;     ...
;   for (int kt = 0; kt < nt; ++kt) {
;     const int buf = kt & 1;
;     if (kt + 1 < nt) { rg[0] = ldc(kt + 1, tid); rg[1] = ldc(kt + 1, tid + 512); if (tid < 256) rg[2] = ldc(kt + 1, tid + 1024); }
;     ...
;     if (kt + 1 < nt) { stc(buf ^ 1, tid, rg[0]); stc(buf ^ 1, tid + 512, rg[1]); if (tid < 256) stc(buf ^ 1, tid + 1024, rg[2]); }
.Lattn_wsel:
	s_bitcmp1_b32 s17, 6
	s_cbranch_scc1 .Lattn_wA
	s_branch .Lattn_wB
.Lattn_wlast:
	s_waitcnt vmcnt(0)
	s_cmp_eq_u32 s66, 2
	s_cbranch_scc1 .Lattn_wB
	s_branch .Lattn_wA

; DI void attn_item(CP p, int s, int hd, int qb, char* smem, bool dostore = true) {
;     ...
;   auto stc = [&](int buf, int c, uint4 v) {
;     if (c < 768) { int key = c / 12, cc = c - key * 12; *(uint4*)(Ks + (buf * 64 + key) * 104 + cc * 8) = v; }
;     else { int c2 = c - 768, dv = c2 >> 3, kc = c2 & 7; *(uint4*)(Vs + (buf * 64 + dv) * 72 + kc * 8) = v; }
;   };
;     ...
;     if (kt + 1 < nt) { stc(buf ^ 1, tid, rg[0]); stc(buf ^ 1, tid + 512, rg[1]); if (tid < 256) stc(buf ^ 1, tid + 1024, rg[2]); }
.Lattn_wA:
	ds_write_b128 v10, v[2:5]
	v_mad_u64_u32 v[2:3], s[54:55], v0, v135, v[130:131]
	ds_write_b128 v2, v[6:9]
	s_and_saveexec_b64 s[54:55], s[42:43]
	s_cbranch_execz .LBB0_291
	v_add_u32_e32 v0, s56, v140
	v_mad_u64_u32 v[2:3], s[56:57], v0, v141, v[132:133]
	ds_write_b128 v2, v[104:107]
	s_branch .LBB0_291
.Lattn_wB:
	ds_write_b128 v10, v[164:167]
	v_mad_u64_u32 v[176:177], s[54:55], v0, v135, v[130:131]
	ds_write_b128 v176, v[168:171]
	s_and_saveexec_b64 s[54:55], s[42:43]
	s_cbranch_execz .LBB0_291
	v_add_u32_e32 v0, s56, v140
	v_mad_u64_u32 v[176:177], s[56:57], v0, v141, v[132:133]
	ds_write_b128 v176, v[172:175]
	s_branch .LBB0_291

; DI void attn_item(CP p, int s, int hd, int qb, char* smem, bool dostore = true) {
;     ...
;   for (int kt = 0; kt < nt; ++kt) {
;     const int buf = kt & 1;
;     if (kt + 1 < nt) { rg[0] = ldc(kt + 1, tid); rg[1] = ldc(kt + 1, tid + 512); if (tid < 256) rg[2] = ldc(kt + 1, tid + 1024); }
;     if (wvalid) {
;       f32x16 st[2];
.LBB0_339:
	s_or_b64 exec, exec, s[54:55]
	s_or_b64 exec, exec, s[56:57]
	s_branch .Lattn_compute

; #define LAS __attribute__((address_space(3)))
; template <bool COOP>
; __global__ void __launch_bounds__(NTHR) mega(Params pp, int lo, int hi) {
;   extern __shared__ __attribute__((aligned(16))) char smem[];
;   const __attribute__((address_space(4))) Params* kp = (const __attribute__((address_space(4))) Params*)__builtin_amdgcn_kernarg_segment_ptr();
;   volatile LAS unsigned* st = (volatile LAS unsigned*)(smem + SMEM_BYTES - 32);
	.amdhsa_kernel _Z4megaILb1EEv6Paramsii
		.amdhsa_group_segment_fixed_size 8192
		.amdhsa_private_segment_fixed_size 0
		.amdhsa_kernarg_size 616
		.amdhsa_user_sgpr_count 2
		.amdhsa_user_sgpr_dispatch_ptr 0
		.amdhsa_user_sgpr_queue_ptr 0
		.amdhsa_user_sgpr_kernarg_segment_ptr 1
		.amdhsa_user_sgpr_dispatch_id 0
		.amdhsa_user_sgpr_kernarg_preload_length 0
		.amdhsa_user_sgpr_kernarg_preload_offset 0
		.amdhsa_user_sgpr_private_segment_size 0
		.amdhsa_uses_dynamic_stack 0
		.amdhsa_enable_private_segment 0
		.amdhsa_system_sgpr_workgroup_id_x 1
		.amdhsa_system_sgpr_workgroup_id_y 0
		.amdhsa_system_sgpr_workgroup_id_z 0
		.amdhsa_system_sgpr_workgroup_info 0
		.amdhsa_system_vgpr_workitem_id 2
		.amdhsa_next_free_vgpr 254
		.amdhsa_next_free_sgpr 100
		.amdhsa_accum_offset 256
		.amdhsa_reserve_vcc 1
		.amdhsa_float_round_mode_32 0
		.amdhsa_float_round_mode_16_64 0
		.amdhsa_float_denorm_mode_32 3
		.amdhsa_float_denorm_mode_16_64 3
		.amdhsa_dx10_clamp 1
		.amdhsa_ieee_mode 1
		.amdhsa_fp16_overflow 0
		.amdhsa_tg_split 0
		.amdhsa_exception_fp_ieee_invalid_op 0
		.amdhsa_exception_fp_denorm_src 0
		.amdhsa_exception_fp_ieee_div_zero 0
		.amdhsa_exception_fp_ieee_overflow 0
		.amdhsa_exception_fp_ieee_underflow 0
		.amdhsa_exception_fp_ieee_inexact 0
		.amdhsa_exception_int_div_zero 0
	.end_amdhsa_kernel

; #define LAS __attribute__((address_space(3)))
; template <bool COOP>
; __global__ void __launch_bounds__(NTHR) mega(Params pp, int lo, int hi) {
;   extern __shared__ __attribute__((aligned(16))) char smem[];
;   const __attribute__((address_space(4))) Params* kp = (const __attribute__((address_space(4))) Params*)__builtin_amdgcn_kernarg_segment_ptr();
;   volatile LAS unsigned* st = (volatile LAS unsigned*)(smem + SMEM_BYTES - 32);
amdhsa.kernels:
  - .agpr_count:     0
    .args:
      - .offset:         0
        .size:           352
        .value_kind:     by_value
      - .offset:         352
        .size:           4
        .value_kind:     by_value
      - .offset:         356
        .size:           4
        .value_kind:     by_value
      - .offset:         360
        .size:           4
        .value_kind:     hidden_block_count_x
      - .offset:         364
        .size:           4
        .value_kind:     hidden_block_count_y
      - .offset:         368
        .size:           4
        .value_kind:     hidden_block_count_z
      - .offset:         372
        .size:           2
        .value_kind:     hidden_group_size_x
      - .offset:         374
        .size:           2
        .value_kind:     hidden_group_size_y
      - .offset:         376
        .size:           2
        .value_kind:     hidden_group_size_z
      - .offset:         378
        .size:           2
        .value_kind:     hidden_remainder_x
      - .offset:         380
        .size:           2
        .value_kind:     hidden_remainder_y
      - .offset:         382
        .size:           2
        .value_kind:     hidden_remainder_z
      - .offset:         400
        .size:           8
        .value_kind:     hidden_global_offset_x
      - .offset:         408
        .size:           8
        .value_kind:     hidden_global_offset_y
      - .offset:         416
        .size:           8
        .value_kind:     hidden_global_offset_z
      - .offset:         424
        .size:           2
        .value_kind:     hidden_grid_dims
      - .offset:         448
        .size:           8
        .value_kind:     hidden_multigrid_sync_arg
      - .offset:         480
        .size:           4
        .value_kind:     hidden_dynamic_lds_size
    .group_segment_fixed_size: 8192
    .kernarg_segment_align: 8
    .kernarg_segment_size: 616
    .language:       OpenCL C
    .language_version:
      - 2
      - 0
    .max_flat_workgroup_size: 512
    .name:           _Z4megaILb1EEv6Paramsii
    .private_segment_fixed_size: 0
    .sgpr_count:     106
    .sgpr_spill_count: 137
    .symbol:         _Z4megaILb1EEv6Paramsii.kd
    .uniform_work_group_size: 1
    .uses_dynamic_stack: false
    .vgpr_count:     254
    .vgpr_spill_count: 0
    .wavefront_size: 64
